# v23 + removed 52 no-op s_waitcnt lgkmcnt(0) between a K-loop barrier and the first MFMA (the same wave already waited lgkmcnt(0) right before the barrier)
# baseline (speedup 1.0000x reference)
.LBB0_123:
	s_ashr_i32 s19, s18, 31
	s_lshl_b64 s[20:21], s[18:19], 19
	v_readlane_b32 s70, v246, 34
	v_readlane_b32 s71, v246, 35
	s_add_u32 s20, s70, s20
	s_addc_u32 s21, s71, s21
	s_and_b64 s[22:23], s[0:1], exec
	s_cselect_b32 s5, s21, s3
	s_cselect_b32 s19, s20, s2
	s_ashr_i32 s17, s16, 31
	s_lshl_b64 s[22:23], s[16:17], 19
	s_add_u32 s22, s15, s22
	s_addc_u32 s23, s30, s23
	s_and_b64 s[28:29], s[0:1], exec
	s_cselect_b32 s17, s23, s27
	s_cselect_b32 s25, s22, s26
	s_add_u32 s2, s2, 0x40080
	s_addc_u32 s3, s3, 0
	s_add_u32 s33, s26, 0x100
	s_addc_u32 s46, s27, 0
	s_mov_b32 s47, -2
	v_readlane_b32 s68, v246, 32
	v_readlane_b32 s69, v246, 33
	ds_read_b128 v[128:131], v161
	ds_read_b128 v[132:135], v161 offset:1024
	ds_read_b128 v[152:155], v161 offset:2048
	ds_read_b128 v[164:167], v161 offset:3072
	ds_read_b128 v[172:175], v162
	ds_read_b128 v[176:179], v162 offset:1024
	ds_read_b128 v[180:183], v162 offset:2048
	ds_read_b128 v[184:187], v162 offset:3072
	s_add_u32 s26, s2, 0xfffc0080
	s_addc_u32 s27, s3, -1
	s_cmp_eq_u32 s47, 12
	s_cselect_b32 s29, s5, s27
	s_cselect_b32 s28, s19, s26
	s_cselect_b32 s27, s17, s46
	s_cselect_b32 s26, s25, s33
	v_lshl_add_u64 v[156:157], s[2:3], 0, v[144:145]
	s_add_i32 m0, s34, 0xc000
	ds_read_b128 v[188:191], v163
	ds_read_b128 v[192:195], v163 offset:1024
	ds_read_b128 v[196:199], v163 offset:2048
	ds_read_b128 v[200:203], v163 offset:3072
	ds_read_b128 v[204:207], v163 offset:4096
	ds_read_b128 v[208:211], v163 offset:5120
	ds_read_b128 v[212:215], v163 offset:6144
	ds_read_b128 v[216:219], v163 offset:7168
	global_load_lds_dwordx4 v[156:157], off
	v_lshl_add_u64 v[156:157], s[2:3], 0, v[146:147]
	s_add_i32 m0, s34, 0xe000
	s_nop 0
	global_load_lds_dwordx4 v[156:157], off
	s_waitcnt vmcnt(8)
	s_waitcnt lgkmcnt(0)
	s_barrier
	v_mfma_f32_16x16x32_bf16 v[124:127], v[128:131], v[188:191], 0
	v_mfma_f32_16x16x32_bf16 v[120:123], v[152:155], v[188:191], 0
	v_mfma_f32_16x16x32_bf16 v[108:111], v[128:131], v[196:199], 0
	v_mfma_f32_16x16x32_bf16 v[104:107], v[152:155], v[196:199], 0
	v_mfma_f32_16x16x32_bf16 v[92:95], v[128:131], v[204:207], 0
	v_mfma_f32_16x16x32_bf16 v[88:91], v[152:155], v[204:207], 0
	v_mfma_f32_16x16x32_bf16 v[76:79], v[128:131], v[212:215], 0
	v_mfma_f32_16x16x32_bf16 v[72:75], v[152:155], v[212:215], 0
	v_mfma_f32_16x16x32_bf16 v[124:127], v[132:135], v[192:195], v[124:127]
	v_mfma_f32_16x16x32_bf16 v[120:123], v[164:167], v[192:195], v[120:123]
	v_mfma_f32_16x16x32_bf16 v[108:111], v[132:135], v[200:203], v[108:111]
	v_mfma_f32_16x16x32_bf16 v[104:107], v[164:167], v[200:203], v[104:107]
	v_mfma_f32_16x16x32_bf16 v[92:95], v[132:135], v[208:211], v[92:95]
	v_mfma_f32_16x16x32_bf16 v[88:91], v[164:167], v[208:211], v[88:91]
	v_mfma_f32_16x16x32_bf16 v[76:79], v[132:135], v[216:219], v[76:79]
	v_mfma_f32_16x16x32_bf16 v[72:75], v[164:167], v[216:219], v[72:75]
	v_mfma_f32_16x16x32_bf16 v[116:119], v[172:175], v[188:191], 0
	v_mfma_f32_16x16x32_bf16 v[112:115], v[180:183], v[188:191], 0
	v_mfma_f32_16x16x32_bf16 v[100:103], v[172:175], v[196:199], 0
	v_mfma_f32_16x16x32_bf16 v[96:99], v[180:183], v[196:199], 0
	v_mfma_f32_16x16x32_bf16 v[84:87], v[172:175], v[204:207], 0
	v_mfma_f32_16x16x32_bf16 v[80:83], v[180:183], v[204:207], 0
	v_mfma_f32_16x16x32_bf16 v[68:71], v[172:175], v[212:215], 0
	v_mfma_f32_16x16x32_bf16 v[64:67], v[180:183], v[212:215], 0
	v_mfma_f32_16x16x32_bf16 v[116:119], v[176:179], v[192:195], v[116:119]
	v_mfma_f32_16x16x32_bf16 v[112:115], v[184:187], v[192:195], v[112:115]
	v_mfma_f32_16x16x32_bf16 v[100:103], v[176:179], v[200:203], v[100:103]
	v_mfma_f32_16x16x32_bf16 v[96:99], v[184:187], v[200:203], v[96:99]
	v_mfma_f32_16x16x32_bf16 v[84:87], v[176:179], v[208:211], v[84:87]
	v_mfma_f32_16x16x32_bf16 v[80:83], v[184:187], v[208:211], v[80:83]
	v_mfma_f32_16x16x32_bf16 v[68:71], v[176:179], v[216:219], v[68:71]
	v_mfma_f32_16x16x32_bf16 v[64:67], v[184:187], v[216:219], v[64:67]
	s_barrier
	s_add_i32 s49, s44, s31
	v_lshl_add_u64 v[156:157], s[26:27], 0, v[138:139]
	s_mov_b32 m0, s49
	ds_read_b128 v[188:191], v163 offset:16384
	ds_read_b128 v[192:195], v163 offset:17408
	ds_read_b128 v[196:199], v163 offset:18432
	ds_read_b128 v[200:203], v163 offset:19456
	ds_read_b128 v[204:207], v163 offset:20480
	ds_read_b128 v[208:211], v163 offset:21504
	ds_read_b128 v[212:215], v163 offset:22528
	ds_read_b128 v[216:219], v163 offset:23552
	global_load_lds_dwordx4 v[156:157], off
	s_add_i32 m0, s49, 0x2000
	s_add_u32 s50, s26, 0x40000
	v_lshl_add_u64 v[168:169], s[26:27], 0, v[142:143]
	s_addc_u32 s51, s27, 0
	s_add_i32 s49, s45, s31
	global_load_lds_dwordx4 v[168:169], off
	v_lshl_add_u64 v[220:221], s[50:51], 0, v[138:139]
	s_mov_b32 m0, s49
	v_lshl_add_u64 v[222:223], s[28:29], 0, v[140:141]
	global_load_lds_dwordx4 v[220:221], off
	v_lshl_add_u64 v[220:221], s[50:51], 0, v[142:143]
	s_add_i32 m0, s49, 0x2000
	s_nop 0
	global_load_lds_dwordx4 v[220:221], off
	v_lshl_add_u64 v[220:221], s[28:29], 0, v[136:137]
	s_mov_b32 m0, s34
	s_nop 0
	global_load_lds_dwordx4 v[220:221], off
	s_mov_b32 m0, s35
	s_nop 0
	global_load_lds_dwordx4 v[222:223], off
	s_waitcnt vmcnt(8)
	s_waitcnt lgkmcnt(0)
	s_barrier
	v_mfma_f32_16x16x32_bf16 v[60:63], v[128:131], v[188:191], 0
	v_mfma_f32_16x16x32_bf16 v[56:59], v[152:155], v[188:191], 0
	v_mfma_f32_16x16x32_bf16 v[44:47], v[128:131], v[196:199], 0
	v_mfma_f32_16x16x32_bf16 v[40:43], v[152:155], v[196:199], 0
	v_mfma_f32_16x16x32_bf16 v[28:31], v[128:131], v[204:207], 0
	v_mfma_f32_16x16x32_bf16 v[24:27], v[152:155], v[204:207], 0
	v_mfma_f32_16x16x32_bf16 v[12:15], v[128:131], v[212:215], 0
	v_mfma_f32_16x16x32_bf16 v[8:11], v[152:155], v[212:215], 0
	v_mfma_f32_16x16x32_bf16 v[60:63], v[132:135], v[192:195], v[60:63]
	v_mfma_f32_16x16x32_bf16 v[56:59], v[164:167], v[192:195], v[56:59]
	v_mfma_f32_16x16x32_bf16 v[44:47], v[132:135], v[200:203], v[44:47]
	v_mfma_f32_16x16x32_bf16 v[40:43], v[164:167], v[200:203], v[40:43]
	v_mfma_f32_16x16x32_bf16 v[28:31], v[132:135], v[208:211], v[28:31]
	v_mfma_f32_16x16x32_bf16 v[24:27], v[164:167], v[208:211], v[24:27]
	v_mfma_f32_16x16x32_bf16 v[12:15], v[132:135], v[216:219], v[12:15]
	v_mfma_f32_16x16x32_bf16 v[8:11], v[164:167], v[216:219], v[8:11]
	v_mfma_f32_16x16x32_bf16 v[52:55], v[172:175], v[188:191], 0
	v_mfma_f32_16x16x32_bf16 v[48:51], v[180:183], v[188:191], 0
	v_mfma_f32_16x16x32_bf16 v[36:39], v[172:175], v[196:199], 0
	v_mfma_f32_16x16x32_bf16 v[32:35], v[180:183], v[196:199], 0
	v_mfma_f32_16x16x32_bf16 v[20:23], v[172:175], v[204:207], 0
	v_mfma_f32_16x16x32_bf16 v[16:19], v[180:183], v[204:207], 0
	v_mfma_f32_16x16x32_bf16 v[4:7], v[172:175], v[212:215], 0
	v_mfma_f32_16x16x32_bf16 v[0:3], v[180:183], v[212:215], 0
	v_mfma_f32_16x16x32_bf16 v[52:55], v[176:179], v[192:195], v[52:55]
	v_mfma_f32_16x16x32_bf16 v[48:51], v[184:187], v[192:195], v[48:51]
	v_mfma_f32_16x16x32_bf16 v[36:39], v[176:179], v[200:203], v[36:39]
	v_mfma_f32_16x16x32_bf16 v[32:35], v[184:187], v[200:203], v[32:35]
	v_mfma_f32_16x16x32_bf16 v[20:23], v[176:179], v[208:211], v[20:23]
	v_mfma_f32_16x16x32_bf16 v[16:19], v[184:187], v[208:211], v[16:19]
	v_mfma_f32_16x16x32_bf16 v[4:7], v[176:179], v[216:219], v[4:7]
	v_mfma_f32_16x16x32_bf16 v[0:3], v[184:187], v[216:219], v[0:3]
	s_barrier
	s_branch .Lpeel124_mid
.LBB0_124:
	ds_read_b128 v[128:131], v161
	ds_read_b128 v[132:135], v161 offset:1024
	ds_read_b128 v[152:155], v161 offset:2048
	ds_read_b128 v[164:167], v161 offset:3072
	ds_read_b128 v[172:175], v162
	ds_read_b128 v[176:179], v162 offset:1024
	ds_read_b128 v[180:183], v162 offset:2048
	ds_read_b128 v[184:187], v162 offset:3072
	s_add_u32 s26, s2, 0xfffc0080
	s_addc_u32 s27, s3, -1
	s_cmp_eq_u32 s47, 12
	s_cselect_b32 s29, s5, s27
	s_cselect_b32 s28, s19, s26
	s_cselect_b32 s27, s17, s46
	s_cselect_b32 s26, s25, s33
	v_lshl_add_u64 v[156:157], s[2:3], 0, v[144:145]
	s_add_i32 m0, s34, 0xc000
	ds_read_b128 v[188:191], v163
	ds_read_b128 v[192:195], v163 offset:1024
	ds_read_b128 v[196:199], v163 offset:2048
	ds_read_b128 v[200:203], v163 offset:3072
	ds_read_b128 v[204:207], v163 offset:4096
	ds_read_b128 v[208:211], v163 offset:5120
	ds_read_b128 v[212:215], v163 offset:6144
	ds_read_b128 v[216:219], v163 offset:7168
	global_load_lds_dwordx4 v[156:157], off
	v_lshl_add_u64 v[156:157], s[2:3], 0, v[146:147]
	s_add_i32 m0, s34, 0xe000
	s_nop 0
	global_load_lds_dwordx4 v[156:157], off
	s_waitcnt vmcnt(8)
	s_waitcnt lgkmcnt(0)
	s_barrier
	v_mfma_f32_16x16x32_bf16 v[124:127], v[128:131], v[188:191], v[124:127]
	v_mfma_f32_16x16x32_bf16 v[120:123], v[152:155], v[188:191], v[120:123]
	v_mfma_f32_16x16x32_bf16 v[108:111], v[128:131], v[196:199], v[108:111]
	v_mfma_f32_16x16x32_bf16 v[104:107], v[152:155], v[196:199], v[104:107]
	v_mfma_f32_16x16x32_bf16 v[92:95], v[128:131], v[204:207], v[92:95]
	v_mfma_f32_16x16x32_bf16 v[88:91], v[152:155], v[204:207], v[88:91]
	v_mfma_f32_16x16x32_bf16 v[76:79], v[128:131], v[212:215], v[76:79]
	v_mfma_f32_16x16x32_bf16 v[72:75], v[152:155], v[212:215], v[72:75]
	v_mfma_f32_16x16x32_bf16 v[124:127], v[132:135], v[192:195], v[124:127]
	v_mfma_f32_16x16x32_bf16 v[120:123], v[164:167], v[192:195], v[120:123]
	v_mfma_f32_16x16x32_bf16 v[108:111], v[132:135], v[200:203], v[108:111]
	v_mfma_f32_16x16x32_bf16 v[104:107], v[164:167], v[200:203], v[104:107]
	v_mfma_f32_16x16x32_bf16 v[92:95], v[132:135], v[208:211], v[92:95]
	v_mfma_f32_16x16x32_bf16 v[88:91], v[164:167], v[208:211], v[88:91]
	v_mfma_f32_16x16x32_bf16 v[76:79], v[132:135], v[216:219], v[76:79]
	v_mfma_f32_16x16x32_bf16 v[72:75], v[164:167], v[216:219], v[72:75]
	v_mfma_f32_16x16x32_bf16 v[116:119], v[172:175], v[188:191], v[116:119]
	v_mfma_f32_16x16x32_bf16 v[112:115], v[180:183], v[188:191], v[112:115]
	v_mfma_f32_16x16x32_bf16 v[100:103], v[172:175], v[196:199], v[100:103]
	v_mfma_f32_16x16x32_bf16 v[96:99], v[180:183], v[196:199], v[96:99]
	v_mfma_f32_16x16x32_bf16 v[84:87], v[172:175], v[204:207], v[84:87]
	v_mfma_f32_16x16x32_bf16 v[80:83], v[180:183], v[204:207], v[80:83]
	v_mfma_f32_16x16x32_bf16 v[68:71], v[172:175], v[212:215], v[68:71]
	v_mfma_f32_16x16x32_bf16 v[64:67], v[180:183], v[212:215], v[64:67]
	v_mfma_f32_16x16x32_bf16 v[116:119], v[176:179], v[192:195], v[116:119]
	v_mfma_f32_16x16x32_bf16 v[112:115], v[184:187], v[192:195], v[112:115]
	v_mfma_f32_16x16x32_bf16 v[100:103], v[176:179], v[200:203], v[100:103]
	v_mfma_f32_16x16x32_bf16 v[96:99], v[184:187], v[200:203], v[96:99]
	v_mfma_f32_16x16x32_bf16 v[84:87], v[176:179], v[208:211], v[84:87]
	v_mfma_f32_16x16x32_bf16 v[80:83], v[184:187], v[208:211], v[80:83]
	v_mfma_f32_16x16x32_bf16 v[68:71], v[176:179], v[216:219], v[68:71]
	v_mfma_f32_16x16x32_bf16 v[64:67], v[184:187], v[216:219], v[64:67]
	s_barrier
	s_add_i32 s49, s44, s31
	v_lshl_add_u64 v[156:157], s[26:27], 0, v[138:139]
	s_mov_b32 m0, s49
	ds_read_b128 v[188:191], v163 offset:16384
	ds_read_b128 v[192:195], v163 offset:17408
	ds_read_b128 v[196:199], v163 offset:18432
	ds_read_b128 v[200:203], v163 offset:19456
	ds_read_b128 v[204:207], v163 offset:20480
	ds_read_b128 v[208:211], v163 offset:21504
	ds_read_b128 v[212:215], v163 offset:22528
	ds_read_b128 v[216:219], v163 offset:23552
	global_load_lds_dwordx4 v[156:157], off
	s_add_i32 m0, s49, 0x2000
	s_add_u32 s50, s26, 0x40000
	v_lshl_add_u64 v[168:169], s[26:27], 0, v[142:143]
	s_addc_u32 s51, s27, 0
	s_add_i32 s49, s45, s31
	global_load_lds_dwordx4 v[168:169], off
	v_lshl_add_u64 v[220:221], s[50:51], 0, v[138:139]
	s_mov_b32 m0, s49
	v_lshl_add_u64 v[222:223], s[28:29], 0, v[140:141]
	global_load_lds_dwordx4 v[220:221], off
	v_lshl_add_u64 v[220:221], s[50:51], 0, v[142:143]
	s_add_i32 m0, s49, 0x2000
	s_nop 0
	global_load_lds_dwordx4 v[220:221], off
	v_lshl_add_u64 v[220:221], s[28:29], 0, v[136:137]
	s_mov_b32 m0, s34
	s_nop 0
	global_load_lds_dwordx4 v[220:221], off
	s_mov_b32 m0, s35
	s_nop 0
	global_load_lds_dwordx4 v[222:223], off
	s_waitcnt vmcnt(8)
	s_waitcnt lgkmcnt(0)
	s_barrier
	v_mfma_f32_16x16x32_bf16 v[60:63], v[128:131], v[188:191], v[60:63]
	v_mfma_f32_16x16x32_bf16 v[56:59], v[152:155], v[188:191], v[56:59]
	v_mfma_f32_16x16x32_bf16 v[44:47], v[128:131], v[196:199], v[44:47]
	v_mfma_f32_16x16x32_bf16 v[40:43], v[152:155], v[196:199], v[40:43]
	v_mfma_f32_16x16x32_bf16 v[28:31], v[128:131], v[204:207], v[28:31]
	v_mfma_f32_16x16x32_bf16 v[24:27], v[152:155], v[204:207], v[24:27]
	v_mfma_f32_16x16x32_bf16 v[12:15], v[128:131], v[212:215], v[12:15]
	v_mfma_f32_16x16x32_bf16 v[8:11], v[152:155], v[212:215], v[8:11]
	v_mfma_f32_16x16x32_bf16 v[60:63], v[132:135], v[192:195], v[60:63]
	v_mfma_f32_16x16x32_bf16 v[56:59], v[164:167], v[192:195], v[56:59]
	v_mfma_f32_16x16x32_bf16 v[44:47], v[132:135], v[200:203], v[44:47]
	v_mfma_f32_16x16x32_bf16 v[40:43], v[164:167], v[200:203], v[40:43]
	v_mfma_f32_16x16x32_bf16 v[28:31], v[132:135], v[208:211], v[28:31]
	v_mfma_f32_16x16x32_bf16 v[24:27], v[164:167], v[208:211], v[24:27]
	v_mfma_f32_16x16x32_bf16 v[12:15], v[132:135], v[216:219], v[12:15]
	v_mfma_f32_16x16x32_bf16 v[8:11], v[164:167], v[216:219], v[8:11]
	v_mfma_f32_16x16x32_bf16 v[52:55], v[172:175], v[188:191], v[52:55]
	v_mfma_f32_16x16x32_bf16 v[48:51], v[180:183], v[188:191], v[48:51]
	v_mfma_f32_16x16x32_bf16 v[36:39], v[172:175], v[196:199], v[36:39]
	v_mfma_f32_16x16x32_bf16 v[32:35], v[180:183], v[196:199], v[32:35]
	v_mfma_f32_16x16x32_bf16 v[20:23], v[172:175], v[204:207], v[20:23]
	v_mfma_f32_16x16x32_bf16 v[16:19], v[180:183], v[204:207], v[16:19]
	v_mfma_f32_16x16x32_bf16 v[4:7], v[172:175], v[212:215], v[4:7]
	v_mfma_f32_16x16x32_bf16 v[0:3], v[180:183], v[212:215], v[0:3]
	v_mfma_f32_16x16x32_bf16 v[52:55], v[176:179], v[192:195], v[52:55]
	v_mfma_f32_16x16x32_bf16 v[48:51], v[184:187], v[192:195], v[48:51]
	v_mfma_f32_16x16x32_bf16 v[36:39], v[176:179], v[200:203], v[36:39]
	v_mfma_f32_16x16x32_bf16 v[32:35], v[184:187], v[200:203], v[32:35]
	v_mfma_f32_16x16x32_bf16 v[20:23], v[176:179], v[208:211], v[20:23]
	v_mfma_f32_16x16x32_bf16 v[16:19], v[184:187], v[208:211], v[16:19]
	v_mfma_f32_16x16x32_bf16 v[4:7], v[176:179], v[216:219], v[4:7]
	v_mfma_f32_16x16x32_bf16 v[0:3], v[184:187], v[216:219], v[0:3]
	s_barrier
.Lpeel124_mid:
	s_add_i32 s49, 0, 0x18000
	s_add_i32 s50, 0, 0x1c000
	v_add_u32_e32 v164, s49, v159
	v_add_u32_e32 v184, s50, v159
	ds_read_b128 v[128:131], v164
	ds_read_b128 v[132:135], v164 offset:1024
	ds_read_b128 v[152:155], v164 offset:2048
	ds_read_b128 v[164:167], v164 offset:3072
	ds_read_b128 v[172:175], v184
	ds_read_b128 v[176:179], v184 offset:1024
	ds_read_b128 v[180:183], v184 offset:2048
	ds_read_b128 v[184:187], v184 offset:3072
	s_add_u32 s28, s28, 0x40000
	s_addc_u32 s29, s29, 0
	s_mov_b32 m0, s36
	v_lshl_add_u64 v[224:225], s[28:29], 0, v[136:137]
	ds_read_b128 v[188:191], v163 offset:32768
	ds_read_b128 v[192:195], v163 offset:33792
	ds_read_b128 v[196:199], v163 offset:34816
	ds_read_b128 v[200:203], v163 offset:35840
	ds_read_b128 v[204:207], v163 offset:36864
	ds_read_b128 v[208:211], v163 offset:37888
	ds_read_b128 v[212:215], v163 offset:38912
	ds_read_b128 v[216:219], v163 offset:39936
	global_load_lds_dwordx4 v[224:225], off
	v_lshl_add_u64 v[224:225], s[28:29], 0, v[140:141]
	s_mov_b32 m0, s37
	s_nop 0
	global_load_lds_dwordx4 v[224:225], off
	s_waitcnt vmcnt(8)
	s_waitcnt lgkmcnt(0)
	s_barrier
	v_mfma_f32_16x16x32_bf16 v[124:127], v[128:131], v[188:191], v[124:127]
	v_mfma_f32_16x16x32_bf16 v[120:123], v[152:155], v[188:191], v[120:123]
	v_mfma_f32_16x16x32_bf16 v[108:111], v[128:131], v[196:199], v[108:111]
	v_mfma_f32_16x16x32_bf16 v[104:107], v[152:155], v[196:199], v[104:107]
	v_mfma_f32_16x16x32_bf16 v[92:95], v[128:131], v[204:207], v[92:95]
	v_mfma_f32_16x16x32_bf16 v[88:91], v[152:155], v[204:207], v[88:91]
	v_mfma_f32_16x16x32_bf16 v[76:79], v[128:131], v[212:215], v[76:79]
	v_mfma_f32_16x16x32_bf16 v[72:75], v[152:155], v[212:215], v[72:75]
	v_mfma_f32_16x16x32_bf16 v[124:127], v[132:135], v[192:195], v[124:127]
	v_mfma_f32_16x16x32_bf16 v[120:123], v[164:167], v[192:195], v[120:123]
	v_mfma_f32_16x16x32_bf16 v[108:111], v[132:135], v[200:203], v[108:111]
	v_mfma_f32_16x16x32_bf16 v[104:107], v[164:167], v[200:203], v[104:107]
	v_mfma_f32_16x16x32_bf16 v[92:95], v[132:135], v[208:211], v[92:95]
	v_mfma_f32_16x16x32_bf16 v[88:91], v[164:167], v[208:211], v[88:91]
	v_mfma_f32_16x16x32_bf16 v[76:79], v[132:135], v[216:219], v[76:79]
	v_mfma_f32_16x16x32_bf16 v[72:75], v[164:167], v[216:219], v[72:75]
	v_mfma_f32_16x16x32_bf16 v[116:119], v[172:175], v[188:191], v[116:119]
	v_mfma_f32_16x16x32_bf16 v[112:115], v[180:183], v[188:191], v[112:115]
	v_mfma_f32_16x16x32_bf16 v[100:103], v[172:175], v[196:199], v[100:103]
	v_mfma_f32_16x16x32_bf16 v[96:99], v[180:183], v[196:199], v[96:99]
	v_mfma_f32_16x16x32_bf16 v[84:87], v[172:175], v[204:207], v[84:87]
	v_mfma_f32_16x16x32_bf16 v[80:83], v[180:183], v[204:207], v[80:83]
	v_mfma_f32_16x16x32_bf16 v[68:71], v[172:175], v[212:215], v[68:71]
	v_mfma_f32_16x16x32_bf16 v[64:67], v[180:183], v[212:215], v[64:67]
	v_mfma_f32_16x16x32_bf16 v[116:119], v[176:179], v[192:195], v[116:119]
	v_mfma_f32_16x16x32_bf16 v[112:115], v[184:187], v[192:195], v[112:115]
	v_mfma_f32_16x16x32_bf16 v[100:103], v[176:179], v[200:203], v[100:103]
	v_mfma_f32_16x16x32_bf16 v[96:99], v[184:187], v[200:203], v[96:99]
	v_mfma_f32_16x16x32_bf16 v[84:87], v[176:179], v[208:211], v[84:87]
	v_mfma_f32_16x16x32_bf16 v[80:83], v[184:187], v[208:211], v[80:83]
	v_mfma_f32_16x16x32_bf16 v[68:71], v[176:179], v[216:219], v[68:71]
	v_mfma_f32_16x16x32_bf16 v[64:67], v[184:187], v[216:219], v[64:67]
	s_barrier
	s_add_i32 s28, s49, s31
	v_lshl_add_u64 v[156:157], v[156:157], 0, s[10:11]
	s_mov_b32 m0, s28
	ds_read_b128 v[188:191], v163 offset:49152
	ds_read_b128 v[192:195], v163 offset:50176
	ds_read_b128 v[196:199], v163 offset:51200
	ds_read_b128 v[200:203], v163 offset:52224
	ds_read_b128 v[204:207], v163 offset:53248
	ds_read_b128 v[208:211], v163 offset:54272
	ds_read_b128 v[212:215], v163 offset:55296
	ds_read_b128 v[216:219], v163 offset:56320
	global_load_lds_dwordx4 v[156:157], off
	s_add_i32 m0, s28, 0x2000
	s_add_u32 s26, s26, 0x40080
	v_lshl_add_u64 v[156:157], v[168:169], 0, s[10:11]
	s_addc_u32 s27, s27, 0
	s_add_i32 s28, s50, s31
	global_load_lds_dwordx4 v[156:157], off
	v_lshl_add_u64 v[156:157], s[26:27], 0, v[138:139]
	s_mov_b32 m0, s28
	s_nop 0
	global_load_lds_dwordx4 v[156:157], off
	v_lshl_add_u64 v[156:157], s[26:27], 0, v[142:143]
	s_add_i32 m0, s28, 0x2000
	s_nop 0
	global_load_lds_dwordx4 v[156:157], off
	v_lshl_add_u64 v[156:157], v[220:221], 0, s[10:11]
	s_mov_b32 m0, s41
	s_nop 0
	global_load_lds_dwordx4 v[156:157], off
	v_lshl_add_u64 v[156:157], v[222:223], 0, s[10:11]
	s_mov_b32 m0, s42
	s_nop 0
	global_load_lds_dwordx4 v[156:157], off
	s_waitcnt vmcnt(8)
	s_waitcnt lgkmcnt(0)
	s_barrier
	v_mfma_f32_16x16x32_bf16 v[60:63], v[128:131], v[188:191], v[60:63]
	v_mfma_f32_16x16x32_bf16 v[56:59], v[152:155], v[188:191], v[56:59]
	v_mfma_f32_16x16x32_bf16 v[44:47], v[128:131], v[196:199], v[44:47]
	v_mfma_f32_16x16x32_bf16 v[40:43], v[152:155], v[196:199], v[40:43]
	v_mfma_f32_16x16x32_bf16 v[28:31], v[128:131], v[204:207], v[28:31]
	v_mfma_f32_16x16x32_bf16 v[24:27], v[152:155], v[204:207], v[24:27]
	v_mfma_f32_16x16x32_bf16 v[12:15], v[128:131], v[212:215], v[12:15]
	v_mfma_f32_16x16x32_bf16 v[8:11], v[152:155], v[212:215], v[8:11]
	v_mfma_f32_16x16x32_bf16 v[60:63], v[132:135], v[192:195], v[60:63]
	v_mfma_f32_16x16x32_bf16 v[56:59], v[164:167], v[192:195], v[56:59]
	v_mfma_f32_16x16x32_bf16 v[44:47], v[132:135], v[200:203], v[44:47]
	v_mfma_f32_16x16x32_bf16 v[40:43], v[164:167], v[200:203], v[40:43]
	v_mfma_f32_16x16x32_bf16 v[28:31], v[132:135], v[208:211], v[28:31]
	v_mfma_f32_16x16x32_bf16 v[24:27], v[164:167], v[208:211], v[24:27]
	v_mfma_f32_16x16x32_bf16 v[12:15], v[132:135], v[216:219], v[12:15]
	v_mfma_f32_16x16x32_bf16 v[8:11], v[164:167], v[216:219], v[8:11]
	v_mfma_f32_16x16x32_bf16 v[52:55], v[172:175], v[188:191], v[52:55]
	v_mfma_f32_16x16x32_bf16 v[48:51], v[180:183], v[188:191], v[48:51]
	v_mfma_f32_16x16x32_bf16 v[36:39], v[172:175], v[196:199], v[36:39]
	v_mfma_f32_16x16x32_bf16 v[32:35], v[180:183], v[196:199], v[32:35]
	v_mfma_f32_16x16x32_bf16 v[20:23], v[172:175], v[204:207], v[20:23]
	v_mfma_f32_16x16x32_bf16 v[16:19], v[180:183], v[204:207], v[16:19]
	v_mfma_f32_16x16x32_bf16 v[4:7], v[172:175], v[212:215], v[4:7]
	v_mfma_f32_16x16x32_bf16 v[0:3], v[180:183], v[212:215], v[0:3]
	v_mfma_f32_16x16x32_bf16 v[52:55], v[176:179], v[192:195], v[52:55]
	v_mfma_f32_16x16x32_bf16 v[48:51], v[184:187], v[192:195], v[48:51]
	v_mfma_f32_16x16x32_bf16 v[36:39], v[176:179], v[200:203], v[36:39]
	v_mfma_f32_16x16x32_bf16 v[32:35], v[184:187], v[200:203], v[32:35]
	v_mfma_f32_16x16x32_bf16 v[20:23], v[176:179], v[208:211], v[20:23]
	v_mfma_f32_16x16x32_bf16 v[16:19], v[184:187], v[208:211], v[16:19]
	v_mfma_f32_16x16x32_bf16 v[4:7], v[176:179], v[216:219], v[4:7]
	v_mfma_f32_16x16x32_bf16 v[0:3], v[184:187], v[216:219], v[0:3]
	s_barrier
	s_add_i32 s47, s47, 2
	s_add_u32 s2, s2, 0x100
	s_addc_u32 s3, s3, 0
	s_add_u32 s33, s33, 0x100
	s_addc_u32 s46, s46, 0
	s_cmp_gt_u32 s47, 13
	s_cbranch_scc0 .LBB0_124
	s_and_b64 vcc, exec, s[12:13]
	s_cbranch_vccz .LBB0_127
	s_barrier

.LBB0_456:
	v_readlane_b32 s68, v246, 32
	v_readlane_b32 s69, v246, 33
	s_ashr_i32 s13, s12, 31
	v_readlane_b32 s70, v246, 34
	v_readlane_b32 s71, v246, 35
	s_mov_b64 s[60:61], s[68:69]
	s_lshl_b64 s[14:15], s[12:13], 19
	s_mov_b64 s[62:63], s[70:71]
	s_add_u32 s14, s62, s14
	s_addc_u32 s15, s63, s15
	s_and_b64 s[16:17], s[0:1], exec
	s_cselect_b32 s13, s15, s21
	s_cselect_b32 s42, s14, s20
	s_ashr_i32 s11, s10, 31
	s_lshl_b64 s[16:17], s[10:11], 19
	v_readlane_b32 s24, v246, 36
	v_readlane_b32 s25, v246, 37
	s_add_u32 s16, s24, s16
	s_addc_u32 s17, s25, s17
	s_and_b64 s[24:25], s[0:1], exec
	s_cselect_b32 s11, s17, s23
	s_cselect_b32 s43, s16, s22
	s_add_u32 s20, s20, 0x40080
	s_addc_u32 s21, s21, 0
	s_add_u32 s44, s22, 0x100
	s_addc_u32 s45, s23, 0
	s_mov_b32 s46, -2
	ds_read_b128 v[152:155], v148
	ds_read_b128 v[156:159], v148 offset:1024
	ds_read_b128 v[160:163], v148 offset:2048
	ds_read_b128 v[164:167], v148 offset:3072
	ds_read_b128 v[172:175], v149
	ds_read_b128 v[176:179], v149 offset:1024
	ds_read_b128 v[180:183], v149 offset:2048
	ds_read_b128 v[184:187], v149 offset:3072
	s_add_u32 s22, s20, 0xfffc0080
	s_addc_u32 s23, s21, -1
	s_cmp_eq_u32 s46, 12
	s_cselect_b32 s25, s13, s23
	s_cselect_b32 s24, s42, s22
	s_cselect_b32 s23, s11, s45
	s_cselect_b32 s22, s43, s44
	v_lshl_add_u64 v[168:169], s[20:21], 0, v[136:137]
	s_add_i32 m0, s19, 0xc000
	ds_read_b128 v[188:191], v150
	ds_read_b128 v[192:195], v150 offset:1024
	ds_read_b128 v[196:199], v150 offset:2048
	ds_read_b128 v[200:203], v150 offset:3072
	ds_read_b128 v[204:207], v150 offset:4096
	ds_read_b128 v[208:211], v150 offset:5120
	ds_read_b128 v[212:215], v150 offset:6144
	ds_read_b128 v[216:219], v150 offset:7168
	global_load_lds_dwordx4 v[168:169], off
	v_lshl_add_u64 v[168:169], s[20:21], 0, v[138:139]
	s_add_i32 m0, s19, 0xe000
	s_nop 0
	global_load_lds_dwordx4 v[168:169], off
	s_waitcnt vmcnt(8)
	s_waitcnt lgkmcnt(0)
	s_barrier
	v_mfma_f32_16x16x32_bf16 v[124:127], v[152:155], v[188:191], 0
	v_mfma_f32_16x16x32_bf16 v[120:123], v[160:163], v[188:191], 0
	v_mfma_f32_16x16x32_bf16 v[116:119], v[152:155], v[196:199], 0
	v_mfma_f32_16x16x32_bf16 v[108:111], v[160:163], v[196:199], 0
	v_mfma_f32_16x16x32_bf16 v[100:103], v[152:155], v[204:207], 0
	v_mfma_f32_16x16x32_bf16 v[92:95], v[160:163], v[204:207], 0
	v_mfma_f32_16x16x32_bf16 v[84:87], v[152:155], v[212:215], 0
	v_mfma_f32_16x16x32_bf16 v[76:79], v[160:163], v[212:215], 0
	v_mfma_f32_16x16x32_bf16 v[124:127], v[156:159], v[192:195], v[124:127]
	v_mfma_f32_16x16x32_bf16 v[120:123], v[164:167], v[192:195], v[120:123]
	v_mfma_f32_16x16x32_bf16 v[116:119], v[156:159], v[200:203], v[116:119]
	v_mfma_f32_16x16x32_bf16 v[108:111], v[164:167], v[200:203], v[108:111]
	v_mfma_f32_16x16x32_bf16 v[100:103], v[156:159], v[208:211], v[100:103]
	v_mfma_f32_16x16x32_bf16 v[92:95], v[164:167], v[208:211], v[92:95]
	v_mfma_f32_16x16x32_bf16 v[84:87], v[156:159], v[216:219], v[84:87]
	v_mfma_f32_16x16x32_bf16 v[76:79], v[164:167], v[216:219], v[76:79]
	v_mfma_f32_16x16x32_bf16 v[112:115], v[172:175], v[188:191], 0
	v_mfma_f32_16x16x32_bf16 v[104:107], v[180:183], v[188:191], 0
	v_mfma_f32_16x16x32_bf16 v[96:99], v[172:175], v[196:199], 0
	v_mfma_f32_16x16x32_bf16 v[88:91], v[180:183], v[196:199], 0
	v_mfma_f32_16x16x32_bf16 v[80:83], v[172:175], v[204:207], 0
	v_mfma_f32_16x16x32_bf16 v[72:75], v[180:183], v[204:207], 0
	v_mfma_f32_16x16x32_bf16 v[68:71], v[172:175], v[212:215], 0
	v_mfma_f32_16x16x32_bf16 v[64:67], v[180:183], v[212:215], 0
	v_mfma_f32_16x16x32_bf16 v[112:115], v[176:179], v[192:195], v[112:115]
	v_mfma_f32_16x16x32_bf16 v[104:107], v[184:187], v[192:195], v[104:107]
	v_mfma_f32_16x16x32_bf16 v[96:99], v[176:179], v[200:203], v[96:99]
	v_mfma_f32_16x16x32_bf16 v[88:91], v[184:187], v[200:203], v[88:91]
	v_mfma_f32_16x16x32_bf16 v[80:83], v[176:179], v[208:211], v[80:83]
	v_mfma_f32_16x16x32_bf16 v[72:75], v[184:187], v[208:211], v[72:75]
	v_mfma_f32_16x16x32_bf16 v[68:71], v[176:179], v[216:219], v[68:71]
	v_mfma_f32_16x16x32_bf16 v[64:67], v[184:187], v[216:219], v[64:67]
	s_barrier
	s_add_i32 s47, s38, s26
	v_lshl_add_u64 v[168:169], s[22:23], 0, v[130:131]
	s_mov_b32 m0, s47
	ds_read_b128 v[188:191], v150 offset:16384
	ds_read_b128 v[192:195], v150 offset:17408
	ds_read_b128 v[196:199], v150 offset:18432
	ds_read_b128 v[200:203], v150 offset:19456
	ds_read_b128 v[204:207], v150 offset:20480
	ds_read_b128 v[208:211], v150 offset:21504
	ds_read_b128 v[212:215], v150 offset:22528
	ds_read_b128 v[216:219], v150 offset:23552
	global_load_lds_dwordx4 v[168:169], off
	s_add_i32 m0, s47, 0x2000
	s_add_u32 s48, s22, 0x40000
	v_lshl_add_u64 v[220:221], s[22:23], 0, v[134:135]
	s_addc_u32 s49, s23, 0
	s_add_i32 s47, s39, s26
	global_load_lds_dwordx4 v[220:221], off
	v_lshl_add_u64 v[222:223], s[48:49], 0, v[130:131]
	s_mov_b32 m0, s47
	v_lshl_add_u64 v[224:225], s[24:25], 0, v[132:133]
	global_load_lds_dwordx4 v[222:223], off
	v_lshl_add_u64 v[222:223], s[48:49], 0, v[134:135]
	s_add_i32 m0, s47, 0x2000
	s_nop 0
	global_load_lds_dwordx4 v[222:223], off
	v_lshl_add_u64 v[222:223], s[24:25], 0, v[128:129]
	s_mov_b32 m0, s19
	s_nop 0
	global_load_lds_dwordx4 v[222:223], off
	s_mov_b32 m0, s29
	s_nop 0
	global_load_lds_dwordx4 v[224:225], off
	s_waitcnt vmcnt(8)
	s_waitcnt lgkmcnt(0)
	s_barrier
	v_mfma_f32_16x16x32_bf16 v[60:63], v[152:155], v[188:191], 0
	v_mfma_f32_16x16x32_bf16 v[56:59], v[160:163], v[188:191], 0
	v_mfma_f32_16x16x32_bf16 v[52:55], v[152:155], v[196:199], 0
	v_mfma_f32_16x16x32_bf16 v[44:47], v[160:163], v[196:199], 0
	v_mfma_f32_16x16x32_bf16 v[36:39], v[152:155], v[204:207], 0
	v_mfma_f32_16x16x32_bf16 v[28:31], v[160:163], v[204:207], 0
	v_mfma_f32_16x16x32_bf16 v[20:23], v[152:155], v[212:215], 0
	v_mfma_f32_16x16x32_bf16 v[12:15], v[160:163], v[212:215], 0
	v_mfma_f32_16x16x32_bf16 v[60:63], v[156:159], v[192:195], v[60:63]
	v_mfma_f32_16x16x32_bf16 v[56:59], v[164:167], v[192:195], v[56:59]
	v_mfma_f32_16x16x32_bf16 v[52:55], v[156:159], v[200:203], v[52:55]
	v_mfma_f32_16x16x32_bf16 v[44:47], v[164:167], v[200:203], v[44:47]
	v_mfma_f32_16x16x32_bf16 v[36:39], v[156:159], v[208:211], v[36:39]
	v_mfma_f32_16x16x32_bf16 v[28:31], v[164:167], v[208:211], v[28:31]
	v_mfma_f32_16x16x32_bf16 v[20:23], v[156:159], v[216:219], v[20:23]
	v_mfma_f32_16x16x32_bf16 v[12:15], v[164:167], v[216:219], v[12:15]
	v_mfma_f32_16x16x32_bf16 v[48:51], v[172:175], v[188:191], 0
	v_mfma_f32_16x16x32_bf16 v[40:43], v[180:183], v[188:191], 0
	v_mfma_f32_16x16x32_bf16 v[32:35], v[172:175], v[196:199], 0
	v_mfma_f32_16x16x32_bf16 v[24:27], v[180:183], v[196:199], 0
	v_mfma_f32_16x16x32_bf16 v[16:19], v[172:175], v[204:207], 0
	v_mfma_f32_16x16x32_bf16 v[8:11], v[180:183], v[204:207], 0
	v_mfma_f32_16x16x32_bf16 v[4:7], v[172:175], v[212:215], 0
	v_mfma_f32_16x16x32_bf16 v[0:3], v[180:183], v[212:215], 0
	v_mfma_f32_16x16x32_bf16 v[48:51], v[176:179], v[192:195], v[48:51]
	v_mfma_f32_16x16x32_bf16 v[40:43], v[184:187], v[192:195], v[40:43]
	v_mfma_f32_16x16x32_bf16 v[32:35], v[176:179], v[200:203], v[32:35]
	v_mfma_f32_16x16x32_bf16 v[24:27], v[184:187], v[200:203], v[24:27]
	v_mfma_f32_16x16x32_bf16 v[16:19], v[176:179], v[208:211], v[16:19]
	v_mfma_f32_16x16x32_bf16 v[8:11], v[184:187], v[208:211], v[8:11]
	v_mfma_f32_16x16x32_bf16 v[4:7], v[176:179], v[216:219], v[4:7]
	v_mfma_f32_16x16x32_bf16 v[0:3], v[184:187], v[216:219], v[0:3]
	s_barrier
	s_branch .Lpeel457_mid
.LBB0_457:
	ds_read_b128 v[152:155], v148
	ds_read_b128 v[156:159], v148 offset:1024
	ds_read_b128 v[160:163], v148 offset:2048
	ds_read_b128 v[164:167], v148 offset:3072
	ds_read_b128 v[172:175], v149
	ds_read_b128 v[176:179], v149 offset:1024
	ds_read_b128 v[180:183], v149 offset:2048
	ds_read_b128 v[184:187], v149 offset:3072
	s_add_u32 s22, s20, 0xfffc0080
	s_addc_u32 s23, s21, -1
	s_cmp_eq_u32 s46, 12
	s_cselect_b32 s25, s13, s23
	s_cselect_b32 s24, s42, s22
	s_cselect_b32 s23, s11, s45
	s_cselect_b32 s22, s43, s44
	v_lshl_add_u64 v[168:169], s[20:21], 0, v[136:137]
	s_add_i32 m0, s19, 0xc000
	ds_read_b128 v[188:191], v150
	ds_read_b128 v[192:195], v150 offset:1024
	ds_read_b128 v[196:199], v150 offset:2048
	ds_read_b128 v[200:203], v150 offset:3072
	ds_read_b128 v[204:207], v150 offset:4096
	ds_read_b128 v[208:211], v150 offset:5120
	ds_read_b128 v[212:215], v150 offset:6144
	ds_read_b128 v[216:219], v150 offset:7168
	global_load_lds_dwordx4 v[168:169], off
	v_lshl_add_u64 v[168:169], s[20:21], 0, v[138:139]
	s_add_i32 m0, s19, 0xe000
	s_nop 0
	global_load_lds_dwordx4 v[168:169], off
	s_waitcnt vmcnt(8)
	s_waitcnt lgkmcnt(0)
	s_barrier
	v_mfma_f32_16x16x32_bf16 v[124:127], v[152:155], v[188:191], v[124:127]
	v_mfma_f32_16x16x32_bf16 v[120:123], v[160:163], v[188:191], v[120:123]
	v_mfma_f32_16x16x32_bf16 v[116:119], v[152:155], v[196:199], v[116:119]
	v_mfma_f32_16x16x32_bf16 v[108:111], v[160:163], v[196:199], v[108:111]
	v_mfma_f32_16x16x32_bf16 v[100:103], v[152:155], v[204:207], v[100:103]
	v_mfma_f32_16x16x32_bf16 v[92:95], v[160:163], v[204:207], v[92:95]
	v_mfma_f32_16x16x32_bf16 v[84:87], v[152:155], v[212:215], v[84:87]
	v_mfma_f32_16x16x32_bf16 v[76:79], v[160:163], v[212:215], v[76:79]
	v_mfma_f32_16x16x32_bf16 v[124:127], v[156:159], v[192:195], v[124:127]
	v_mfma_f32_16x16x32_bf16 v[120:123], v[164:167], v[192:195], v[120:123]
	v_mfma_f32_16x16x32_bf16 v[116:119], v[156:159], v[200:203], v[116:119]
	v_mfma_f32_16x16x32_bf16 v[108:111], v[164:167], v[200:203], v[108:111]
	v_mfma_f32_16x16x32_bf16 v[100:103], v[156:159], v[208:211], v[100:103]
	v_mfma_f32_16x16x32_bf16 v[92:95], v[164:167], v[208:211], v[92:95]
	v_mfma_f32_16x16x32_bf16 v[84:87], v[156:159], v[216:219], v[84:87]
	v_mfma_f32_16x16x32_bf16 v[76:79], v[164:167], v[216:219], v[76:79]
	v_mfma_f32_16x16x32_bf16 v[112:115], v[172:175], v[188:191], v[112:115]
	v_mfma_f32_16x16x32_bf16 v[104:107], v[180:183], v[188:191], v[104:107]
	v_mfma_f32_16x16x32_bf16 v[96:99], v[172:175], v[196:199], v[96:99]
	v_mfma_f32_16x16x32_bf16 v[88:91], v[180:183], v[196:199], v[88:91]
	v_mfma_f32_16x16x32_bf16 v[80:83], v[172:175], v[204:207], v[80:83]
	v_mfma_f32_16x16x32_bf16 v[72:75], v[180:183], v[204:207], v[72:75]
	v_mfma_f32_16x16x32_bf16 v[68:71], v[172:175], v[212:215], v[68:71]
	v_mfma_f32_16x16x32_bf16 v[64:67], v[180:183], v[212:215], v[64:67]
	v_mfma_f32_16x16x32_bf16 v[112:115], v[176:179], v[192:195], v[112:115]
	v_mfma_f32_16x16x32_bf16 v[104:107], v[184:187], v[192:195], v[104:107]
	v_mfma_f32_16x16x32_bf16 v[96:99], v[176:179], v[200:203], v[96:99]
	v_mfma_f32_16x16x32_bf16 v[88:91], v[184:187], v[200:203], v[88:91]
	v_mfma_f32_16x16x32_bf16 v[80:83], v[176:179], v[208:211], v[80:83]
	v_mfma_f32_16x16x32_bf16 v[72:75], v[184:187], v[208:211], v[72:75]
	v_mfma_f32_16x16x32_bf16 v[68:71], v[176:179], v[216:219], v[68:71]
	v_mfma_f32_16x16x32_bf16 v[64:67], v[184:187], v[216:219], v[64:67]
	s_barrier
	s_add_i32 s47, s38, s26
	v_lshl_add_u64 v[168:169], s[22:23], 0, v[130:131]
	s_mov_b32 m0, s47
	ds_read_b128 v[188:191], v150 offset:16384
	ds_read_b128 v[192:195], v150 offset:17408
	ds_read_b128 v[196:199], v150 offset:18432
	ds_read_b128 v[200:203], v150 offset:19456
	ds_read_b128 v[204:207], v150 offset:20480
	ds_read_b128 v[208:211], v150 offset:21504
	ds_read_b128 v[212:215], v150 offset:22528
	ds_read_b128 v[216:219], v150 offset:23552
	global_load_lds_dwordx4 v[168:169], off
	s_add_i32 m0, s47, 0x2000
	s_add_u32 s48, s22, 0x40000
	v_lshl_add_u64 v[220:221], s[22:23], 0, v[134:135]
	s_addc_u32 s49, s23, 0
	s_add_i32 s47, s39, s26
	global_load_lds_dwordx4 v[220:221], off
	v_lshl_add_u64 v[222:223], s[48:49], 0, v[130:131]
	s_mov_b32 m0, s47
	v_lshl_add_u64 v[224:225], s[24:25], 0, v[132:133]
	global_load_lds_dwordx4 v[222:223], off
	v_lshl_add_u64 v[222:223], s[48:49], 0, v[134:135]
	s_add_i32 m0, s47, 0x2000
	s_nop 0
	global_load_lds_dwordx4 v[222:223], off
	v_lshl_add_u64 v[222:223], s[24:25], 0, v[128:129]
	s_mov_b32 m0, s19
	s_nop 0
	global_load_lds_dwordx4 v[222:223], off
	s_mov_b32 m0, s29
	s_nop 0
	global_load_lds_dwordx4 v[224:225], off
	s_waitcnt vmcnt(8)
	s_waitcnt lgkmcnt(0)
	s_barrier
	v_mfma_f32_16x16x32_bf16 v[60:63], v[152:155], v[188:191], v[60:63]
	v_mfma_f32_16x16x32_bf16 v[56:59], v[160:163], v[188:191], v[56:59]
	v_mfma_f32_16x16x32_bf16 v[52:55], v[152:155], v[196:199], v[52:55]
	v_mfma_f32_16x16x32_bf16 v[44:47], v[160:163], v[196:199], v[44:47]
	v_mfma_f32_16x16x32_bf16 v[36:39], v[152:155], v[204:207], v[36:39]
	v_mfma_f32_16x16x32_bf16 v[28:31], v[160:163], v[204:207], v[28:31]
	v_mfma_f32_16x16x32_bf16 v[20:23], v[152:155], v[212:215], v[20:23]
	v_mfma_f32_16x16x32_bf16 v[12:15], v[160:163], v[212:215], v[12:15]
	v_mfma_f32_16x16x32_bf16 v[60:63], v[156:159], v[192:195], v[60:63]
	v_mfma_f32_16x16x32_bf16 v[56:59], v[164:167], v[192:195], v[56:59]
	v_mfma_f32_16x16x32_bf16 v[52:55], v[156:159], v[200:203], v[52:55]
	v_mfma_f32_16x16x32_bf16 v[44:47], v[164:167], v[200:203], v[44:47]
	v_mfma_f32_16x16x32_bf16 v[36:39], v[156:159], v[208:211], v[36:39]
	v_mfma_f32_16x16x32_bf16 v[28:31], v[164:167], v[208:211], v[28:31]
	v_mfma_f32_16x16x32_bf16 v[20:23], v[156:159], v[216:219], v[20:23]
	v_mfma_f32_16x16x32_bf16 v[12:15], v[164:167], v[216:219], v[12:15]
	v_mfma_f32_16x16x32_bf16 v[48:51], v[172:175], v[188:191], v[48:51]
	v_mfma_f32_16x16x32_bf16 v[40:43], v[180:183], v[188:191], v[40:43]
	v_mfma_f32_16x16x32_bf16 v[32:35], v[172:175], v[196:199], v[32:35]
	v_mfma_f32_16x16x32_bf16 v[24:27], v[180:183], v[196:199], v[24:27]
	v_mfma_f32_16x16x32_bf16 v[16:19], v[172:175], v[204:207], v[16:19]
	v_mfma_f32_16x16x32_bf16 v[8:11], v[180:183], v[204:207], v[8:11]
	v_mfma_f32_16x16x32_bf16 v[4:7], v[172:175], v[212:215], v[4:7]
	v_mfma_f32_16x16x32_bf16 v[0:3], v[180:183], v[212:215], v[0:3]
	v_mfma_f32_16x16x32_bf16 v[48:51], v[176:179], v[192:195], v[48:51]
	v_mfma_f32_16x16x32_bf16 v[40:43], v[184:187], v[192:195], v[40:43]
	v_mfma_f32_16x16x32_bf16 v[32:35], v[176:179], v[200:203], v[32:35]
	v_mfma_f32_16x16x32_bf16 v[24:27], v[184:187], v[200:203], v[24:27]
	v_mfma_f32_16x16x32_bf16 v[16:19], v[176:179], v[208:211], v[16:19]
	v_mfma_f32_16x16x32_bf16 v[8:11], v[184:187], v[208:211], v[8:11]
	v_mfma_f32_16x16x32_bf16 v[4:7], v[176:179], v[216:219], v[4:7]
	v_mfma_f32_16x16x32_bf16 v[0:3], v[184:187], v[216:219], v[0:3]
	s_barrier
.Lpeel457_mid:
	s_add_i32 s47, 0, 0x18000
	v_add_u32_e32 v144, s47, v146
	s_add_i32 s48, 0, 0x1c000
	ds_read_b128 v[152:155], v144
	ds_read_b128 v[156:159], v144 offset:1024
	ds_read_b128 v[160:163], v144 offset:2048
	ds_read_b128 v[164:167], v144 offset:3072
	v_add_u32_e32 v144, s48, v146
	ds_read_b128 v[172:175], v144
	ds_read_b128 v[176:179], v144 offset:1024
	ds_read_b128 v[180:183], v144 offset:2048
	ds_read_b128 v[184:187], v144 offset:3072
	s_add_u32 s24, s24, 0x40000
	s_addc_u32 s25, s25, 0
	s_mov_b32 m0, s30
	v_lshl_add_u64 v[226:227], s[24:25], 0, v[128:129]
	ds_read_b128 v[188:191], v150 offset:32768
	ds_read_b128 v[192:195], v150 offset:33792
	ds_read_b128 v[196:199], v150 offset:34816
	ds_read_b128 v[200:203], v150 offset:35840
	ds_read_b128 v[204:207], v150 offset:36864
	ds_read_b128 v[208:211], v150 offset:37888
	ds_read_b128 v[212:215], v150 offset:38912
	ds_read_b128 v[216:219], v150 offset:39936
	global_load_lds_dwordx4 v[226:227], off
	v_lshl_add_u64 v[226:227], s[24:25], 0, v[132:133]
	s_mov_b32 m0, s31
	s_nop 0
	global_load_lds_dwordx4 v[226:227], off
	s_waitcnt vmcnt(8)
	s_waitcnt lgkmcnt(0)
	s_barrier
	v_mfma_f32_16x16x32_bf16 v[124:127], v[152:155], v[188:191], v[124:127]
	v_mfma_f32_16x16x32_bf16 v[120:123], v[160:163], v[188:191], v[120:123]
	v_mfma_f32_16x16x32_bf16 v[116:119], v[152:155], v[196:199], v[116:119]
	v_mfma_f32_16x16x32_bf16 v[108:111], v[160:163], v[196:199], v[108:111]
	v_mfma_f32_16x16x32_bf16 v[100:103], v[152:155], v[204:207], v[100:103]
	v_mfma_f32_16x16x32_bf16 v[92:95], v[160:163], v[204:207], v[92:95]
	v_mfma_f32_16x16x32_bf16 v[84:87], v[152:155], v[212:215], v[84:87]
	v_mfma_f32_16x16x32_bf16 v[76:79], v[160:163], v[212:215], v[76:79]
	v_mfma_f32_16x16x32_bf16 v[124:127], v[156:159], v[192:195], v[124:127]
	v_mfma_f32_16x16x32_bf16 v[120:123], v[164:167], v[192:195], v[120:123]
	v_mfma_f32_16x16x32_bf16 v[116:119], v[156:159], v[200:203], v[116:119]
	v_mfma_f32_16x16x32_bf16 v[108:111], v[164:167], v[200:203], v[108:111]
	v_mfma_f32_16x16x32_bf16 v[100:103], v[156:159], v[208:211], v[100:103]
	v_mfma_f32_16x16x32_bf16 v[92:95], v[164:167], v[208:211], v[92:95]
	v_mfma_f32_16x16x32_bf16 v[84:87], v[156:159], v[216:219], v[84:87]
	v_mfma_f32_16x16x32_bf16 v[76:79], v[164:167], v[216:219], v[76:79]
	v_mfma_f32_16x16x32_bf16 v[112:115], v[172:175], v[188:191], v[112:115]
	v_mfma_f32_16x16x32_bf16 v[104:107], v[180:183], v[188:191], v[104:107]
	v_mfma_f32_16x16x32_bf16 v[96:99], v[172:175], v[196:199], v[96:99]
	v_mfma_f32_16x16x32_bf16 v[88:91], v[180:183], v[196:199], v[88:91]
	v_mfma_f32_16x16x32_bf16 v[80:83], v[172:175], v[204:207], v[80:83]
	v_mfma_f32_16x16x32_bf16 v[72:75], v[180:183], v[204:207], v[72:75]
	v_mfma_f32_16x16x32_bf16 v[68:71], v[172:175], v[212:215], v[68:71]
	v_mfma_f32_16x16x32_bf16 v[64:67], v[180:183], v[212:215], v[64:67]
	v_mfma_f32_16x16x32_bf16 v[112:115], v[176:179], v[192:195], v[112:115]
	v_mfma_f32_16x16x32_bf16 v[104:107], v[184:187], v[192:195], v[104:107]
	v_mfma_f32_16x16x32_bf16 v[96:99], v[176:179], v[200:203], v[96:99]
	v_mfma_f32_16x16x32_bf16 v[88:91], v[184:187], v[200:203], v[88:91]
	v_mfma_f32_16x16x32_bf16 v[80:83], v[176:179], v[208:211], v[80:83]
	v_mfma_f32_16x16x32_bf16 v[72:75], v[184:187], v[208:211], v[72:75]
	v_mfma_f32_16x16x32_bf16 v[68:71], v[176:179], v[216:219], v[68:71]
	v_mfma_f32_16x16x32_bf16 v[64:67], v[184:187], v[216:219], v[64:67]
	s_barrier
	s_add_i32 s24, s47, s26
	v_lshl_add_u64 v[168:169], v[168:169], 0, s[6:7]
	s_mov_b32 m0, s24
	ds_read_b128 v[188:191], v150 offset:49152
	ds_read_b128 v[192:195], v150 offset:50176
	ds_read_b128 v[196:199], v150 offset:51200
	ds_read_b128 v[200:203], v150 offset:52224
	ds_read_b128 v[204:207], v150 offset:53248
	ds_read_b128 v[208:211], v150 offset:54272
	ds_read_b128 v[212:215], v150 offset:55296
	ds_read_b128 v[216:219], v150 offset:56320
	global_load_lds_dwordx4 v[168:169], off
	s_add_i32 m0, s24, 0x2000
	s_add_u32 s22, s22, 0x40080
	v_lshl_add_u64 v[168:169], v[220:221], 0, s[6:7]
	s_addc_u32 s23, s23, 0
	s_add_i32 s24, s48, s26
	global_load_lds_dwordx4 v[168:169], off
	v_lshl_add_u64 v[168:169], s[22:23], 0, v[130:131]
	s_mov_b32 m0, s24
	s_nop 0
	global_load_lds_dwordx4 v[168:169], off
	v_lshl_add_u64 v[168:169], s[22:23], 0, v[134:135]
	s_add_i32 m0, s24, 0x2000
	s_nop 0
	global_load_lds_dwordx4 v[168:169], off
	v_lshl_add_u64 v[168:169], v[222:223], 0, s[6:7]
	s_mov_b32 m0, s35
	s_nop 0
	global_load_lds_dwordx4 v[168:169], off
	v_lshl_add_u64 v[168:169], v[224:225], 0, s[6:7]
	s_mov_b32 m0, s36
	s_nop 0
	global_load_lds_dwordx4 v[168:169], off
	s_waitcnt vmcnt(8)
	s_waitcnt lgkmcnt(0)
	s_barrier
	v_mfma_f32_16x16x32_bf16 v[60:63], v[152:155], v[188:191], v[60:63]
	v_mfma_f32_16x16x32_bf16 v[56:59], v[160:163], v[188:191], v[56:59]
	v_mfma_f32_16x16x32_bf16 v[52:55], v[152:155], v[196:199], v[52:55]
	v_mfma_f32_16x16x32_bf16 v[44:47], v[160:163], v[196:199], v[44:47]
	v_mfma_f32_16x16x32_bf16 v[36:39], v[152:155], v[204:207], v[36:39]
	v_mfma_f32_16x16x32_bf16 v[28:31], v[160:163], v[204:207], v[28:31]
	v_mfma_f32_16x16x32_bf16 v[20:23], v[152:155], v[212:215], v[20:23]
	v_mfma_f32_16x16x32_bf16 v[12:15], v[160:163], v[212:215], v[12:15]
	v_mfma_f32_16x16x32_bf16 v[60:63], v[156:159], v[192:195], v[60:63]
	v_mfma_f32_16x16x32_bf16 v[56:59], v[164:167], v[192:195], v[56:59]
	v_mfma_f32_16x16x32_bf16 v[52:55], v[156:159], v[200:203], v[52:55]
	v_mfma_f32_16x16x32_bf16 v[44:47], v[164:167], v[200:203], v[44:47]
	v_mfma_f32_16x16x32_bf16 v[36:39], v[156:159], v[208:211], v[36:39]
	v_mfma_f32_16x16x32_bf16 v[28:31], v[164:167], v[208:211], v[28:31]
	v_mfma_f32_16x16x32_bf16 v[20:23], v[156:159], v[216:219], v[20:23]
	v_mfma_f32_16x16x32_bf16 v[12:15], v[164:167], v[216:219], v[12:15]
	v_mfma_f32_16x16x32_bf16 v[48:51], v[172:175], v[188:191], v[48:51]
	v_mfma_f32_16x16x32_bf16 v[40:43], v[180:183], v[188:191], v[40:43]
	v_mfma_f32_16x16x32_bf16 v[32:35], v[172:175], v[196:199], v[32:35]
	v_mfma_f32_16x16x32_bf16 v[24:27], v[180:183], v[196:199], v[24:27]
	v_mfma_f32_16x16x32_bf16 v[16:19], v[172:175], v[204:207], v[16:19]
	v_mfma_f32_16x16x32_bf16 v[8:11], v[180:183], v[204:207], v[8:11]
	v_mfma_f32_16x16x32_bf16 v[4:7], v[172:175], v[212:215], v[4:7]
	v_mfma_f32_16x16x32_bf16 v[0:3], v[180:183], v[212:215], v[0:3]
	v_mfma_f32_16x16x32_bf16 v[48:51], v[176:179], v[192:195], v[48:51]
	v_mfma_f32_16x16x32_bf16 v[40:43], v[184:187], v[192:195], v[40:43]
	v_mfma_f32_16x16x32_bf16 v[32:35], v[176:179], v[200:203], v[32:35]
	v_mfma_f32_16x16x32_bf16 v[24:27], v[184:187], v[200:203], v[24:27]
	v_mfma_f32_16x16x32_bf16 v[16:19], v[176:179], v[208:211], v[16:19]
	v_mfma_f32_16x16x32_bf16 v[8:11], v[184:187], v[208:211], v[8:11]
	v_mfma_f32_16x16x32_bf16 v[4:7], v[176:179], v[216:219], v[4:7]
	v_mfma_f32_16x16x32_bf16 v[0:3], v[184:187], v[216:219], v[0:3]
	s_barrier
	s_add_i32 s46, s46, 2
	s_add_u32 s20, s20, 0x100
	s_addc_u32 s21, s21, 0
	s_add_u32 s44, s44, 0x100
	s_addc_u32 s45, s45, 0
	s_cmp_gt_u32 s46, 13
	s_cbranch_scc0 .LBB0_457
	s_and_b64 vcc, exec, s[8:9]
	s_cbranch_vccz .LBB0_460
	s_barrier

.LBB0_645:
	v_readlane_b32 s64, v246, 32
	v_readlane_b32 s65, v246, 33
	s_ashr_i32 s17, s16, 31
	v_readlane_b32 s66, v246, 34
	v_readlane_b32 s67, v246, 35
	s_mov_b64 s[60:61], s[64:65]
	s_andn2_b64 vcc, exec, s[34:35]
	s_lshl_b64 s[20:21], s[16:17], 19
	s_mov_b64 s[62:63], s[66:67]
	s_add_u32 s20, s62, s20
	s_addc_u32 s21, s63, s21
	s_and_b64 s[22:23], s[34:35], exec
	s_cselect_b32 s17, s21, s27
	s_cselect_b32 s50, s20, s26
	s_ashr_i32 s19, s18, 31
	s_lshl_b64 s[22:23], s[18:19], 19
	s_add_u32 s22, s38, s22
	s_addc_u32 s23, s40, s23
	v_cndmask_b32_e64 v0, 0, 1, s[34:35]
	s_and_b64 s[34:35], s[34:35], exec
	s_cselect_b32 s19, s23, s29
	s_cselect_b32 s51, s22, s28
	s_add_u32 s26, s26, 0x40080
	s_addc_u32 s27, s27, 0
	v_cmp_ne_u32_e64 s[0:1], 1, v0
	s_add_u32 s52, s28, 0x100
	s_addc_u32 s53, s29, 0
	s_mov_b32 s54, -2
	ds_read_b128 v[134:137], v156
	ds_read_b128 v[160:163], v156 offset:1024
	ds_read_b128 v[164:167], v156 offset:2048
	ds_read_b128 v[184:187], v156 offset:3072
	ds_read_b128 v[188:191], v157
	ds_read_b128 v[192:195], v157 offset:1024
	ds_read_b128 v[196:199], v157 offset:2048
	ds_read_b128 v[200:203], v157 offset:3072
	s_add_u32 s28, s26, 0xfffc0080
	s_addc_u32 s29, s27, -1
	s_cmp_eq_u32 s54, 12
	s_cselect_b32 s35, s17, s29
	s_cselect_b32 s34, s50, s28
	s_cselect_b32 s29, s19, s53
	s_cselect_b32 s28, s51, s52
	v_lshl_add_u64 v[138:139], s[26:27], 0, v[128:129]
	s_add_i32 m0, s25, 0xc000
	ds_read_b128 v[204:207], v158
	ds_read_b128 v[208:211], v158 offset:1024
	ds_read_b128 v[212:215], v158 offset:2048
	ds_read_b128 v[216:219], v158 offset:3072
	ds_read_b128 v[220:223], v158 offset:4096
	ds_read_b128 v[224:227], v158 offset:5120
	ds_read_b128 v[228:231], v158 offset:6144
	ds_read_b128 v[232:235], v158 offset:7168
	global_load_lds_dwordx4 v[138:139], off
	v_lshl_add_u64 v[138:139], s[26:27], 0, v[132:133]
	s_add_i32 m0, s25, 0xe000
	s_nop 0
	global_load_lds_dwordx4 v[138:139], off
	s_waitcnt vmcnt(8)
	s_waitcnt lgkmcnt(0)
	s_barrier
	v_mfma_f32_16x16x32_bf16 v[124:127], v[134:137], v[204:207], 0
	v_mfma_f32_16x16x32_bf16 v[120:123], v[164:167], v[204:207], 0
	v_mfma_f32_16x16x32_bf16 v[108:111], v[134:137], v[212:215], 0
	v_mfma_f32_16x16x32_bf16 v[104:107], v[164:167], v[212:215], 0
	v_mfma_f32_16x16x32_bf16 v[92:95], v[134:137], v[220:223], 0
	v_mfma_f32_16x16x32_bf16 v[88:91], v[164:167], v[220:223], 0
	v_mfma_f32_16x16x32_bf16 v[76:79], v[134:137], v[228:231], 0
	v_mfma_f32_16x16x32_bf16 v[72:75], v[164:167], v[228:231], 0
	v_mfma_f32_16x16x32_bf16 v[124:127], v[160:163], v[208:211], v[124:127]
	v_mfma_f32_16x16x32_bf16 v[120:123], v[184:187], v[208:211], v[120:123]
	v_mfma_f32_16x16x32_bf16 v[108:111], v[160:163], v[216:219], v[108:111]
	v_mfma_f32_16x16x32_bf16 v[104:107], v[184:187], v[216:219], v[104:107]
	v_mfma_f32_16x16x32_bf16 v[92:95], v[160:163], v[224:227], v[92:95]
	v_mfma_f32_16x16x32_bf16 v[88:91], v[184:187], v[224:227], v[88:91]
	v_mfma_f32_16x16x32_bf16 v[76:79], v[160:163], v[232:235], v[76:79]
	v_mfma_f32_16x16x32_bf16 v[72:75], v[184:187], v[232:235], v[72:75]
	v_mfma_f32_16x16x32_bf16 v[116:119], v[188:191], v[204:207], 0
	v_mfma_f32_16x16x32_bf16 v[112:115], v[196:199], v[204:207], 0
	v_mfma_f32_16x16x32_bf16 v[100:103], v[188:191], v[212:215], 0
	v_mfma_f32_16x16x32_bf16 v[96:99], v[196:199], v[212:215], 0
	v_mfma_f32_16x16x32_bf16 v[84:87], v[188:191], v[220:223], 0
	v_mfma_f32_16x16x32_bf16 v[80:83], v[196:199], v[220:223], 0
	v_mfma_f32_16x16x32_bf16 v[68:71], v[188:191], v[228:231], 0
	v_mfma_f32_16x16x32_bf16 v[64:67], v[196:199], v[228:231], 0
	v_mfma_f32_16x16x32_bf16 v[116:119], v[192:195], v[208:211], v[116:119]
	v_mfma_f32_16x16x32_bf16 v[112:115], v[200:203], v[208:211], v[112:115]
	v_mfma_f32_16x16x32_bf16 v[100:103], v[192:195], v[216:219], v[100:103]
	v_mfma_f32_16x16x32_bf16 v[96:99], v[200:203], v[216:219], v[96:99]
	v_mfma_f32_16x16x32_bf16 v[84:87], v[192:195], v[224:227], v[84:87]
	v_mfma_f32_16x16x32_bf16 v[80:83], v[200:203], v[224:227], v[80:83]
	v_mfma_f32_16x16x32_bf16 v[68:71], v[192:195], v[232:235], v[68:71]
	v_mfma_f32_16x16x32_bf16 v[64:67], v[200:203], v[232:235], v[64:67]
	s_barrier
	s_add_i32 s55, s47, s41
	v_lshl_add_u64 v[138:139], s[28:29], 0, v[142:143]
	s_mov_b32 m0, s55
	ds_read_b128 v[204:207], v158 offset:16384
	ds_read_b128 v[208:211], v158 offset:17408
	ds_read_b128 v[212:215], v158 offset:18432
	ds_read_b128 v[216:219], v158 offset:19456
	ds_read_b128 v[220:223], v158 offset:20480
	ds_read_b128 v[224:227], v158 offset:21504
	ds_read_b128 v[228:231], v158 offset:22528
	ds_read_b128 v[232:235], v158 offset:23552
	global_load_lds_dwordx4 v[138:139], off
	s_add_i32 m0, s55, 0x2000
	s_add_u32 s56, s28, 0x40000
	v_lshl_add_u64 v[168:169], s[28:29], 0, v[146:147]
	s_addc_u32 s57, s29, 0
	s_add_i32 s55, s48, s41
	global_load_lds_dwordx4 v[168:169], off
	v_lshl_add_u64 v[236:237], s[56:57], 0, v[142:143]
	s_mov_b32 m0, s55
	v_lshl_add_u64 v[238:239], s[34:35], 0, v[144:145]
	global_load_lds_dwordx4 v[236:237], off
	v_lshl_add_u64 v[236:237], s[56:57], 0, v[146:147]
	s_add_i32 m0, s55, 0x2000
	s_nop 0
	global_load_lds_dwordx4 v[236:237], off
	v_lshl_add_u64 v[236:237], s[34:35], 0, v[140:141]
	s_mov_b32 m0, s25
	s_nop 0
	global_load_lds_dwordx4 v[236:237], off
	s_mov_b32 m0, s42
	s_nop 0
	global_load_lds_dwordx4 v[238:239], off
	s_waitcnt vmcnt(8)
	s_waitcnt lgkmcnt(0)
	s_barrier
	v_mfma_f32_16x16x32_bf16 v[60:63], v[134:137], v[204:207], 0
	v_mfma_f32_16x16x32_bf16 v[56:59], v[164:167], v[204:207], 0
	v_mfma_f32_16x16x32_bf16 v[44:47], v[134:137], v[212:215], 0
	v_mfma_f32_16x16x32_bf16 v[40:43], v[164:167], v[212:215], 0
	v_mfma_f32_16x16x32_bf16 v[28:31], v[134:137], v[220:223], 0
	v_mfma_f32_16x16x32_bf16 v[24:27], v[164:167], v[220:223], 0
	v_mfma_f32_16x16x32_bf16 v[12:15], v[134:137], v[228:231], 0
	v_mfma_f32_16x16x32_bf16 v[8:11], v[164:167], v[228:231], 0
	v_mfma_f32_16x16x32_bf16 v[60:63], v[160:163], v[208:211], v[60:63]
	v_mfma_f32_16x16x32_bf16 v[56:59], v[184:187], v[208:211], v[56:59]
	v_mfma_f32_16x16x32_bf16 v[44:47], v[160:163], v[216:219], v[44:47]
	v_mfma_f32_16x16x32_bf16 v[40:43], v[184:187], v[216:219], v[40:43]
	v_mfma_f32_16x16x32_bf16 v[28:31], v[160:163], v[224:227], v[28:31]
	v_mfma_f32_16x16x32_bf16 v[24:27], v[184:187], v[224:227], v[24:27]
	v_mfma_f32_16x16x32_bf16 v[12:15], v[160:163], v[232:235], v[12:15]
	v_mfma_f32_16x16x32_bf16 v[8:11], v[184:187], v[232:235], v[8:11]
	v_mfma_f32_16x16x32_bf16 v[52:55], v[188:191], v[204:207], 0
	v_mfma_f32_16x16x32_bf16 v[48:51], v[196:199], v[204:207], 0
	v_mfma_f32_16x16x32_bf16 v[36:39], v[188:191], v[212:215], 0
	v_mfma_f32_16x16x32_bf16 v[32:35], v[196:199], v[212:215], 0
	v_mfma_f32_16x16x32_bf16 v[20:23], v[188:191], v[220:223], 0
	v_mfma_f32_16x16x32_bf16 v[16:19], v[196:199], v[220:223], 0
	v_mfma_f32_16x16x32_bf16 v[4:7], v[188:191], v[228:231], 0
	v_mfma_f32_16x16x32_bf16 v[0:3], v[196:199], v[228:231], 0
	v_mfma_f32_16x16x32_bf16 v[52:55], v[192:195], v[208:211], v[52:55]
	v_mfma_f32_16x16x32_bf16 v[48:51], v[200:203], v[208:211], v[48:51]
	v_mfma_f32_16x16x32_bf16 v[36:39], v[192:195], v[216:219], v[36:39]
	v_mfma_f32_16x16x32_bf16 v[32:35], v[200:203], v[216:219], v[32:35]
	v_mfma_f32_16x16x32_bf16 v[20:23], v[192:195], v[224:227], v[20:23]
	v_mfma_f32_16x16x32_bf16 v[16:19], v[200:203], v[224:227], v[16:19]
	v_mfma_f32_16x16x32_bf16 v[4:7], v[192:195], v[232:235], v[4:7]
	v_mfma_f32_16x16x32_bf16 v[0:3], v[200:203], v[232:235], v[0:3]
	s_barrier
	s_branch .Lpeel646_mid
.LBB0_646:
	ds_read_b128 v[134:137], v156
	ds_read_b128 v[160:163], v156 offset:1024
	ds_read_b128 v[164:167], v156 offset:2048
	ds_read_b128 v[184:187], v156 offset:3072
	ds_read_b128 v[188:191], v157
	ds_read_b128 v[192:195], v157 offset:1024
	ds_read_b128 v[196:199], v157 offset:2048
	ds_read_b128 v[200:203], v157 offset:3072
	s_add_u32 s28, s26, 0xfffc0080
	s_addc_u32 s29, s27, -1
	s_cmp_eq_u32 s54, 12
	s_cselect_b32 s35, s17, s29
	s_cselect_b32 s34, s50, s28
	s_cselect_b32 s29, s19, s53
	s_cselect_b32 s28, s51, s52
	v_lshl_add_u64 v[138:139], s[26:27], 0, v[128:129]
	s_add_i32 m0, s25, 0xc000
	ds_read_b128 v[204:207], v158
	ds_read_b128 v[208:211], v158 offset:1024
	ds_read_b128 v[212:215], v158 offset:2048
	ds_read_b128 v[216:219], v158 offset:3072
	ds_read_b128 v[220:223], v158 offset:4096
	ds_read_b128 v[224:227], v158 offset:5120
	ds_read_b128 v[228:231], v158 offset:6144
	ds_read_b128 v[232:235], v158 offset:7168
	global_load_lds_dwordx4 v[138:139], off
	v_lshl_add_u64 v[138:139], s[26:27], 0, v[132:133]
	s_add_i32 m0, s25, 0xe000
	s_nop 0
	global_load_lds_dwordx4 v[138:139], off
	s_waitcnt vmcnt(8)
	s_waitcnt lgkmcnt(0)
	s_barrier
	v_mfma_f32_16x16x32_bf16 v[124:127], v[134:137], v[204:207], v[124:127]
	v_mfma_f32_16x16x32_bf16 v[120:123], v[164:167], v[204:207], v[120:123]
	v_mfma_f32_16x16x32_bf16 v[108:111], v[134:137], v[212:215], v[108:111]
	v_mfma_f32_16x16x32_bf16 v[104:107], v[164:167], v[212:215], v[104:107]
	v_mfma_f32_16x16x32_bf16 v[92:95], v[134:137], v[220:223], v[92:95]
	v_mfma_f32_16x16x32_bf16 v[88:91], v[164:167], v[220:223], v[88:91]
	v_mfma_f32_16x16x32_bf16 v[76:79], v[134:137], v[228:231], v[76:79]
	v_mfma_f32_16x16x32_bf16 v[72:75], v[164:167], v[228:231], v[72:75]
	v_mfma_f32_16x16x32_bf16 v[124:127], v[160:163], v[208:211], v[124:127]
	v_mfma_f32_16x16x32_bf16 v[120:123], v[184:187], v[208:211], v[120:123]
	v_mfma_f32_16x16x32_bf16 v[108:111], v[160:163], v[216:219], v[108:111]
	v_mfma_f32_16x16x32_bf16 v[104:107], v[184:187], v[216:219], v[104:107]
	v_mfma_f32_16x16x32_bf16 v[92:95], v[160:163], v[224:227], v[92:95]
	v_mfma_f32_16x16x32_bf16 v[88:91], v[184:187], v[224:227], v[88:91]
	v_mfma_f32_16x16x32_bf16 v[76:79], v[160:163], v[232:235], v[76:79]
	v_mfma_f32_16x16x32_bf16 v[72:75], v[184:187], v[232:235], v[72:75]
	v_mfma_f32_16x16x32_bf16 v[116:119], v[188:191], v[204:207], v[116:119]
	v_mfma_f32_16x16x32_bf16 v[112:115], v[196:199], v[204:207], v[112:115]
	v_mfma_f32_16x16x32_bf16 v[100:103], v[188:191], v[212:215], v[100:103]
	v_mfma_f32_16x16x32_bf16 v[96:99], v[196:199], v[212:215], v[96:99]
	v_mfma_f32_16x16x32_bf16 v[84:87], v[188:191], v[220:223], v[84:87]
	v_mfma_f32_16x16x32_bf16 v[80:83], v[196:199], v[220:223], v[80:83]
	v_mfma_f32_16x16x32_bf16 v[68:71], v[188:191], v[228:231], v[68:71]
	v_mfma_f32_16x16x32_bf16 v[64:67], v[196:199], v[228:231], v[64:67]
	v_mfma_f32_16x16x32_bf16 v[116:119], v[192:195], v[208:211], v[116:119]
	v_mfma_f32_16x16x32_bf16 v[112:115], v[200:203], v[208:211], v[112:115]
	v_mfma_f32_16x16x32_bf16 v[100:103], v[192:195], v[216:219], v[100:103]
	v_mfma_f32_16x16x32_bf16 v[96:99], v[200:203], v[216:219], v[96:99]
	v_mfma_f32_16x16x32_bf16 v[84:87], v[192:195], v[224:227], v[84:87]
	v_mfma_f32_16x16x32_bf16 v[80:83], v[200:203], v[224:227], v[80:83]
	v_mfma_f32_16x16x32_bf16 v[68:71], v[192:195], v[232:235], v[68:71]
	v_mfma_f32_16x16x32_bf16 v[64:67], v[200:203], v[232:235], v[64:67]
	s_barrier
	s_add_i32 s55, s47, s41
	v_lshl_add_u64 v[138:139], s[28:29], 0, v[142:143]
	s_mov_b32 m0, s55
	ds_read_b128 v[204:207], v158 offset:16384
	ds_read_b128 v[208:211], v158 offset:17408
	ds_read_b128 v[212:215], v158 offset:18432
	ds_read_b128 v[216:219], v158 offset:19456
	ds_read_b128 v[220:223], v158 offset:20480
	ds_read_b128 v[224:227], v158 offset:21504
	ds_read_b128 v[228:231], v158 offset:22528
	ds_read_b128 v[232:235], v158 offset:23552
	global_load_lds_dwordx4 v[138:139], off
	s_add_i32 m0, s55, 0x2000
	s_add_u32 s56, s28, 0x40000
	v_lshl_add_u64 v[168:169], s[28:29], 0, v[146:147]
	s_addc_u32 s57, s29, 0
	s_add_i32 s55, s48, s41
	global_load_lds_dwordx4 v[168:169], off
	v_lshl_add_u64 v[236:237], s[56:57], 0, v[142:143]
	s_mov_b32 m0, s55
	v_lshl_add_u64 v[238:239], s[34:35], 0, v[144:145]
	global_load_lds_dwordx4 v[236:237], off
	v_lshl_add_u64 v[236:237], s[56:57], 0, v[146:147]
	s_add_i32 m0, s55, 0x2000
	s_nop 0
	global_load_lds_dwordx4 v[236:237], off
	v_lshl_add_u64 v[236:237], s[34:35], 0, v[140:141]
	s_mov_b32 m0, s25
	s_nop 0
	global_load_lds_dwordx4 v[236:237], off
	s_mov_b32 m0, s42
	s_nop 0
	global_load_lds_dwordx4 v[238:239], off
	s_waitcnt vmcnt(8)
	s_waitcnt lgkmcnt(0)
	s_barrier
	v_mfma_f32_16x16x32_bf16 v[60:63], v[134:137], v[204:207], v[60:63]
	v_mfma_f32_16x16x32_bf16 v[56:59], v[164:167], v[204:207], v[56:59]
	v_mfma_f32_16x16x32_bf16 v[44:47], v[134:137], v[212:215], v[44:47]
	v_mfma_f32_16x16x32_bf16 v[40:43], v[164:167], v[212:215], v[40:43]
	v_mfma_f32_16x16x32_bf16 v[28:31], v[134:137], v[220:223], v[28:31]
	v_mfma_f32_16x16x32_bf16 v[24:27], v[164:167], v[220:223], v[24:27]
	v_mfma_f32_16x16x32_bf16 v[12:15], v[134:137], v[228:231], v[12:15]
	v_mfma_f32_16x16x32_bf16 v[8:11], v[164:167], v[228:231], v[8:11]
	v_mfma_f32_16x16x32_bf16 v[60:63], v[160:163], v[208:211], v[60:63]
	v_mfma_f32_16x16x32_bf16 v[56:59], v[184:187], v[208:211], v[56:59]
	v_mfma_f32_16x16x32_bf16 v[44:47], v[160:163], v[216:219], v[44:47]
	v_mfma_f32_16x16x32_bf16 v[40:43], v[184:187], v[216:219], v[40:43]
	v_mfma_f32_16x16x32_bf16 v[28:31], v[160:163], v[224:227], v[28:31]
	v_mfma_f32_16x16x32_bf16 v[24:27], v[184:187], v[224:227], v[24:27]
	v_mfma_f32_16x16x32_bf16 v[12:15], v[160:163], v[232:235], v[12:15]
	v_mfma_f32_16x16x32_bf16 v[8:11], v[184:187], v[232:235], v[8:11]
	v_mfma_f32_16x16x32_bf16 v[52:55], v[188:191], v[204:207], v[52:55]
	v_mfma_f32_16x16x32_bf16 v[48:51], v[196:199], v[204:207], v[48:51]
	v_mfma_f32_16x16x32_bf16 v[36:39], v[188:191], v[212:215], v[36:39]
	v_mfma_f32_16x16x32_bf16 v[32:35], v[196:199], v[212:215], v[32:35]
	v_mfma_f32_16x16x32_bf16 v[20:23], v[188:191], v[220:223], v[20:23]
	v_mfma_f32_16x16x32_bf16 v[16:19], v[196:199], v[220:223], v[16:19]
	v_mfma_f32_16x16x32_bf16 v[4:7], v[188:191], v[228:231], v[4:7]
	v_mfma_f32_16x16x32_bf16 v[0:3], v[196:199], v[228:231], v[0:3]
	v_mfma_f32_16x16x32_bf16 v[52:55], v[192:195], v[208:211], v[52:55]
	v_mfma_f32_16x16x32_bf16 v[48:51], v[200:203], v[208:211], v[48:51]
	v_mfma_f32_16x16x32_bf16 v[36:39], v[192:195], v[216:219], v[36:39]
	v_mfma_f32_16x16x32_bf16 v[32:35], v[200:203], v[216:219], v[32:35]
	v_mfma_f32_16x16x32_bf16 v[20:23], v[192:195], v[224:227], v[20:23]
	v_mfma_f32_16x16x32_bf16 v[16:19], v[200:203], v[224:227], v[16:19]
	v_mfma_f32_16x16x32_bf16 v[4:7], v[192:195], v[232:235], v[4:7]
	v_mfma_f32_16x16x32_bf16 v[0:3], v[200:203], v[232:235], v[0:3]
	s_barrier
.Lpeel646_mid:
	s_add_i32 s55, 0, 0x18000
	v_add_u32_e32 v130, s55, v154
	s_add_i32 s56, 0, 0x1c000
	ds_read_b128 v[134:137], v130
	ds_read_b128 v[160:163], v130 offset:1024
	ds_read_b128 v[164:167], v130 offset:2048
	ds_read_b128 v[184:187], v130 offset:3072
	v_add_u32_e32 v130, s56, v154
	ds_read_b128 v[188:191], v130
	ds_read_b128 v[192:195], v130 offset:1024
	ds_read_b128 v[196:199], v130 offset:2048
	ds_read_b128 v[200:203], v130 offset:3072
	s_add_u32 s34, s34, 0x40000
	s_addc_u32 s35, s35, 0
	s_mov_b32 m0, s43
	v_lshl_add_u64 v[240:241], s[34:35], 0, v[140:141]
	ds_read_b128 v[204:207], v158 offset:32768
	ds_read_b128 v[208:211], v158 offset:33792
	ds_read_b128 v[212:215], v158 offset:34816
	ds_read_b128 v[216:219], v158 offset:35840
	ds_read_b128 v[220:223], v158 offset:36864
	ds_read_b128 v[224:227], v158 offset:37888
	ds_read_b128 v[228:231], v158 offset:38912
	ds_read_b128 v[232:235], v158 offset:39936
	global_load_lds_dwordx4 v[240:241], off
	v_lshl_add_u64 v[240:241], s[34:35], 0, v[144:145]
	s_mov_b32 m0, s44
	s_nop 0
	global_load_lds_dwordx4 v[240:241], off
	s_waitcnt vmcnt(8)
	s_waitcnt lgkmcnt(0)
	s_barrier
	v_mfma_f32_16x16x32_bf16 v[124:127], v[134:137], v[204:207], v[124:127]
	v_mfma_f32_16x16x32_bf16 v[120:123], v[164:167], v[204:207], v[120:123]
	v_mfma_f32_16x16x32_bf16 v[108:111], v[134:137], v[212:215], v[108:111]
	v_mfma_f32_16x16x32_bf16 v[104:107], v[164:167], v[212:215], v[104:107]
	v_mfma_f32_16x16x32_bf16 v[92:95], v[134:137], v[220:223], v[92:95]
	v_mfma_f32_16x16x32_bf16 v[88:91], v[164:167], v[220:223], v[88:91]
	v_mfma_f32_16x16x32_bf16 v[76:79], v[134:137], v[228:231], v[76:79]
	v_mfma_f32_16x16x32_bf16 v[72:75], v[164:167], v[228:231], v[72:75]
	v_mfma_f32_16x16x32_bf16 v[124:127], v[160:163], v[208:211], v[124:127]
	v_mfma_f32_16x16x32_bf16 v[120:123], v[184:187], v[208:211], v[120:123]
	v_mfma_f32_16x16x32_bf16 v[108:111], v[160:163], v[216:219], v[108:111]
	v_mfma_f32_16x16x32_bf16 v[104:107], v[184:187], v[216:219], v[104:107]
	v_mfma_f32_16x16x32_bf16 v[92:95], v[160:163], v[224:227], v[92:95]
	v_mfma_f32_16x16x32_bf16 v[88:91], v[184:187], v[224:227], v[88:91]
	v_mfma_f32_16x16x32_bf16 v[76:79], v[160:163], v[232:235], v[76:79]
	v_mfma_f32_16x16x32_bf16 v[72:75], v[184:187], v[232:235], v[72:75]
	v_mfma_f32_16x16x32_bf16 v[116:119], v[188:191], v[204:207], v[116:119]
	v_mfma_f32_16x16x32_bf16 v[112:115], v[196:199], v[204:207], v[112:115]
	v_mfma_f32_16x16x32_bf16 v[100:103], v[188:191], v[212:215], v[100:103]
	v_mfma_f32_16x16x32_bf16 v[96:99], v[196:199], v[212:215], v[96:99]
	v_mfma_f32_16x16x32_bf16 v[84:87], v[188:191], v[220:223], v[84:87]
	v_mfma_f32_16x16x32_bf16 v[80:83], v[196:199], v[220:223], v[80:83]
	v_mfma_f32_16x16x32_bf16 v[68:71], v[188:191], v[228:231], v[68:71]
	v_mfma_f32_16x16x32_bf16 v[64:67], v[196:199], v[228:231], v[64:67]
	v_mfma_f32_16x16x32_bf16 v[116:119], v[192:195], v[208:211], v[116:119]
	v_mfma_f32_16x16x32_bf16 v[112:115], v[200:203], v[208:211], v[112:115]
	v_mfma_f32_16x16x32_bf16 v[100:103], v[192:195], v[216:219], v[100:103]
	v_mfma_f32_16x16x32_bf16 v[96:99], v[200:203], v[216:219], v[96:99]
	v_mfma_f32_16x16x32_bf16 v[84:87], v[192:195], v[224:227], v[84:87]
	v_mfma_f32_16x16x32_bf16 v[80:83], v[200:203], v[224:227], v[80:83]
	v_mfma_f32_16x16x32_bf16 v[68:71], v[192:195], v[232:235], v[68:71]
	v_mfma_f32_16x16x32_bf16 v[64:67], v[200:203], v[232:235], v[64:67]
	s_barrier
	s_add_i32 s34, s55, s41
	v_lshl_add_u64 v[138:139], v[138:139], 0, s[12:13]
	s_mov_b32 m0, s34
	ds_read_b128 v[204:207], v158 offset:49152
	ds_read_b128 v[208:211], v158 offset:50176
	ds_read_b128 v[212:215], v158 offset:51200
	ds_read_b128 v[216:219], v158 offset:52224
	ds_read_b128 v[220:223], v158 offset:53248
	ds_read_b128 v[224:227], v158 offset:54272
	ds_read_b128 v[228:231], v158 offset:55296
	ds_read_b128 v[232:235], v158 offset:56320
	global_load_lds_dwordx4 v[138:139], off
	s_add_i32 m0, s34, 0x2000
	s_add_u32 s28, s28, 0x40080
	v_lshl_add_u64 v[138:139], v[168:169], 0, s[12:13]
	s_addc_u32 s29, s29, 0
	s_add_i32 s34, s56, s41
	global_load_lds_dwordx4 v[138:139], off
	v_lshl_add_u64 v[138:139], s[28:29], 0, v[142:143]
	s_mov_b32 m0, s34
	s_nop 0
	global_load_lds_dwordx4 v[138:139], off
	v_lshl_add_u64 v[138:139], s[28:29], 0, v[146:147]
	s_add_i32 m0, s34, 0x2000
	s_nop 0
	global_load_lds_dwordx4 v[138:139], off
	v_lshl_add_u64 v[138:139], v[236:237], 0, s[12:13]
	s_mov_b32 m0, s45
	s_nop 0
	global_load_lds_dwordx4 v[138:139], off
	v_lshl_add_u64 v[138:139], v[238:239], 0, s[12:13]
	s_mov_b32 m0, s46
	s_nop 0
	global_load_lds_dwordx4 v[138:139], off
	s_waitcnt vmcnt(8)
	s_waitcnt lgkmcnt(0)
	s_barrier
	v_mfma_f32_16x16x32_bf16 v[60:63], v[134:137], v[204:207], v[60:63]
	v_mfma_f32_16x16x32_bf16 v[56:59], v[164:167], v[204:207], v[56:59]
	v_mfma_f32_16x16x32_bf16 v[44:47], v[134:137], v[212:215], v[44:47]
	v_mfma_f32_16x16x32_bf16 v[40:43], v[164:167], v[212:215], v[40:43]
	v_mfma_f32_16x16x32_bf16 v[28:31], v[134:137], v[220:223], v[28:31]
	v_mfma_f32_16x16x32_bf16 v[24:27], v[164:167], v[220:223], v[24:27]
	v_mfma_f32_16x16x32_bf16 v[12:15], v[134:137], v[228:231], v[12:15]
	v_mfma_f32_16x16x32_bf16 v[8:11], v[164:167], v[228:231], v[8:11]
	v_mfma_f32_16x16x32_bf16 v[60:63], v[160:163], v[208:211], v[60:63]
	v_mfma_f32_16x16x32_bf16 v[56:59], v[184:187], v[208:211], v[56:59]
	v_mfma_f32_16x16x32_bf16 v[44:47], v[160:163], v[216:219], v[44:47]
	v_mfma_f32_16x16x32_bf16 v[40:43], v[184:187], v[216:219], v[40:43]
	v_mfma_f32_16x16x32_bf16 v[28:31], v[160:163], v[224:227], v[28:31]
	v_mfma_f32_16x16x32_bf16 v[24:27], v[184:187], v[224:227], v[24:27]
	v_mfma_f32_16x16x32_bf16 v[12:15], v[160:163], v[232:235], v[12:15]
	v_mfma_f32_16x16x32_bf16 v[8:11], v[184:187], v[232:235], v[8:11]
	v_mfma_f32_16x16x32_bf16 v[52:55], v[188:191], v[204:207], v[52:55]
	v_mfma_f32_16x16x32_bf16 v[48:51], v[196:199], v[204:207], v[48:51]
	v_mfma_f32_16x16x32_bf16 v[36:39], v[188:191], v[212:215], v[36:39]
	v_mfma_f32_16x16x32_bf16 v[32:35], v[196:199], v[212:215], v[32:35]
	v_mfma_f32_16x16x32_bf16 v[20:23], v[188:191], v[220:223], v[20:23]
	v_mfma_f32_16x16x32_bf16 v[16:19], v[196:199], v[220:223], v[16:19]
	v_mfma_f32_16x16x32_bf16 v[4:7], v[188:191], v[228:231], v[4:7]
	v_mfma_f32_16x16x32_bf16 v[0:3], v[196:199], v[228:231], v[0:3]
	v_mfma_f32_16x16x32_bf16 v[52:55], v[192:195], v[208:211], v[52:55]
	v_mfma_f32_16x16x32_bf16 v[48:51], v[200:203], v[208:211], v[48:51]
	v_mfma_f32_16x16x32_bf16 v[36:39], v[192:195], v[216:219], v[36:39]
	v_mfma_f32_16x16x32_bf16 v[32:35], v[200:203], v[216:219], v[32:35]
	v_mfma_f32_16x16x32_bf16 v[20:23], v[192:195], v[224:227], v[20:23]
	v_mfma_f32_16x16x32_bf16 v[16:19], v[200:203], v[224:227], v[16:19]
	v_mfma_f32_16x16x32_bf16 v[4:7], v[192:195], v[232:235], v[4:7]
	v_mfma_f32_16x16x32_bf16 v[0:3], v[200:203], v[232:235], v[0:3]
	s_barrier
	s_add_i32 s54, s54, 2
	s_add_u32 s26, s26, 0x100
	s_addc_u32 s27, s27, 0
	s_add_u32 s52, s52, 0x100
	s_addc_u32 s53, s53, 0
	s_cmp_gt_u32 s54, 13
	s_cbranch_scc0 .LBB0_646
	s_and_b64 vcc, exec, s[14:15]
	s_cbranch_vccz .LBB0_649
	s_barrier

.LBB0_665:
	s_ashr_i32 s19, s18, 31
	s_lshl_b64 s[20:21], s[18:19], 18
	s_add_u32 s20, s30, s20
	s_addc_u32 s21, s31, s21
	s_and_b64 s[22:23], s[2:3], exec
	s_cselect_b32 s19, s21, s27
	s_cselect_b32 s50, s20, s26
	s_ashr_i32 s17, s16, 31
	s_lshl_b64 s[22:23], s[16:17], 18
	v_readlane_b32 s34, v246, 38
	v_readlane_b32 s35, v246, 39
	s_add_u32 s22, s34, s22
	s_addc_u32 s23, s35, s23
	s_and_b64 s[34:35], s[2:3], exec
	s_cselect_b32 s17, s23, s29
	s_cselect_b32 s51, s22, s28
	s_add_u32 s26, s26, 0x20080
	s_addc_u32 s27, s27, 0
	s_add_u32 s52, s28, 0x100
	s_addc_u32 s53, s29, 0
	s_mov_b32 s54, -2
	ds_read_b128 v[128:131], v187
	ds_read_b128 v[132:135], v187 offset:1024
	ds_read_b128 v[136:139], v187 offset:2048
	ds_read_b128 v[164:167], v187 offset:3072
	ds_read_b128 v[190:193], v188
	ds_read_b128 v[194:197], v188 offset:1024
	ds_read_b128 v[198:201], v188 offset:2048
	ds_read_b128 v[202:205], v188 offset:3072
	s_add_u32 s28, s26, 0xfffe0080
	s_addc_u32 s29, s27, -1
	s_cmp_eq_u32 s54, 4
	s_cselect_b32 s35, s19, s29
	s_cselect_b32 s34, s50, s28
	s_cselect_b32 s29, s17, s53
	s_cselect_b32 s28, s51, s52
	v_lshl_add_u64 v[168:169], s[26:27], 0, v[156:157]
	s_add_i32 m0, s25, 0xc000
	ds_read_b128 v[206:209], v189
	ds_read_b128 v[210:213], v189 offset:1024
	ds_read_b128 v[214:217], v189 offset:2048
	ds_read_b128 v[218:221], v189 offset:3072
	ds_read_b128 v[222:225], v189 offset:4096
	ds_read_b128 v[226:229], v189 offset:5120
	ds_read_b128 v[230:233], v189 offset:6144
	ds_read_b128 v[234:237], v189 offset:7168
	global_load_lds_dwordx4 v[168:169], off
	v_lshl_add_u64 v[168:169], s[26:27], 0, v[158:159]
	s_add_i32 m0, s25, 0xe000
	s_nop 0
	global_load_lds_dwordx4 v[168:169], off
	s_waitcnt vmcnt(8)
	s_waitcnt lgkmcnt(0)
	s_barrier
	v_mfma_f32_16x16x32_bf16 v[124:127], v[128:131], v[206:209], 0
	v_mfma_f32_16x16x32_bf16 v[120:123], v[136:139], v[206:209], 0
	v_mfma_f32_16x16x32_bf16 v[112:115], v[128:131], v[214:217], 0
	v_mfma_f32_16x16x32_bf16 v[104:107], v[136:139], v[214:217], 0
	v_mfma_f32_16x16x32_bf16 v[92:95], v[128:131], v[222:225], 0
	v_mfma_f32_16x16x32_bf16 v[88:91], v[136:139], v[222:225], 0
	v_mfma_f32_16x16x32_bf16 v[76:79], v[128:131], v[230:233], 0
	v_mfma_f32_16x16x32_bf16 v[72:75], v[136:139], v[230:233], 0
	v_mfma_f32_16x16x32_bf16 v[124:127], v[132:135], v[210:213], v[124:127]
	v_mfma_f32_16x16x32_bf16 v[120:123], v[164:167], v[210:213], v[120:123]
	v_mfma_f32_16x16x32_bf16 v[112:115], v[132:135], v[218:221], v[112:115]
	v_mfma_f32_16x16x32_bf16 v[104:107], v[164:167], v[218:221], v[104:107]
	v_mfma_f32_16x16x32_bf16 v[92:95], v[132:135], v[226:229], v[92:95]
	v_mfma_f32_16x16x32_bf16 v[88:91], v[164:167], v[226:229], v[88:91]
	v_mfma_f32_16x16x32_bf16 v[76:79], v[132:135], v[234:237], v[76:79]
	v_mfma_f32_16x16x32_bf16 v[72:75], v[164:167], v[234:237], v[72:75]
	v_mfma_f32_16x16x32_bf16 v[116:119], v[190:193], v[206:209], 0
	v_mfma_f32_16x16x32_bf16 v[108:111], v[198:201], v[206:209], 0
	v_mfma_f32_16x16x32_bf16 v[100:103], v[190:193], v[214:217], 0
	v_mfma_f32_16x16x32_bf16 v[96:99], v[198:201], v[214:217], 0
	v_mfma_f32_16x16x32_bf16 v[84:87], v[190:193], v[222:225], 0
	v_mfma_f32_16x16x32_bf16 v[80:83], v[198:201], v[222:225], 0
	v_mfma_f32_16x16x32_bf16 v[68:71], v[190:193], v[230:233], 0
	v_mfma_f32_16x16x32_bf16 v[64:67], v[198:201], v[230:233], 0
	v_mfma_f32_16x16x32_bf16 v[116:119], v[194:197], v[210:213], v[116:119]
	v_mfma_f32_16x16x32_bf16 v[108:111], v[202:205], v[210:213], v[108:111]
	v_mfma_f32_16x16x32_bf16 v[100:103], v[194:197], v[218:221], v[100:103]
	v_mfma_f32_16x16x32_bf16 v[96:99], v[202:205], v[218:221], v[96:99]
	v_mfma_f32_16x16x32_bf16 v[84:87], v[194:197], v[226:229], v[84:87]
	v_mfma_f32_16x16x32_bf16 v[80:83], v[202:205], v[226:229], v[80:83]
	v_mfma_f32_16x16x32_bf16 v[68:71], v[194:197], v[234:237], v[68:71]
	v_mfma_f32_16x16x32_bf16 v[64:67], v[202:205], v[234:237], v[64:67]
	s_barrier
	s_add_i32 s55, s47, s40
	v_lshl_add_u64 v[168:169], s[28:29], 0, v[150:151]
	s_mov_b32 m0, s55
	ds_read_b128 v[206:209], v189 offset:16384
	ds_read_b128 v[210:213], v189 offset:17408
	ds_read_b128 v[214:217], v189 offset:18432
	ds_read_b128 v[218:221], v189 offset:19456
	ds_read_b128 v[222:225], v189 offset:20480
	ds_read_b128 v[226:229], v189 offset:21504
	ds_read_b128 v[230:233], v189 offset:22528
	ds_read_b128 v[234:237], v189 offset:23552
	global_load_lds_dwordx4 v[168:169], off
	s_add_i32 m0, s55, 0x2000
	s_add_u32 s56, s28, 0x20000
	v_lshl_add_u64 v[238:239], s[28:29], 0, v[154:155]
	s_addc_u32 s57, s29, 0
	s_add_i32 s55, s48, s40
	global_load_lds_dwordx4 v[238:239], off
	v_lshl_add_u64 v[240:241], s[56:57], 0, v[150:151]
	s_mov_b32 m0, s55
	v_lshl_add_u64 v[242:243], s[34:35], 0, v[152:153]
	global_load_lds_dwordx4 v[240:241], off
	v_lshl_add_u64 v[240:241], s[56:57], 0, v[154:155]
	s_add_i32 m0, s55, 0x2000
	s_nop 0
	global_load_lds_dwordx4 v[240:241], off
	v_lshl_add_u64 v[240:241], s[34:35], 0, v[148:149]
	s_mov_b32 m0, s25
	s_nop 0
	global_load_lds_dwordx4 v[240:241], off
	s_mov_b32 m0, s41
	s_nop 0
	global_load_lds_dwordx4 v[242:243], off
	s_waitcnt vmcnt(8)
	s_waitcnt lgkmcnt(0)
	s_barrier
	v_mfma_f32_16x16x32_bf16 v[60:63], v[128:131], v[206:209], 0
	v_mfma_f32_16x16x32_bf16 v[56:59], v[136:139], v[206:209], 0
	v_mfma_f32_16x16x32_bf16 v[44:47], v[128:131], v[214:217], 0
	v_mfma_f32_16x16x32_bf16 v[40:43], v[136:139], v[214:217], 0
	v_mfma_f32_16x16x32_bf16 v[36:39], v[128:131], v[222:225], 0
	v_mfma_f32_16x16x32_bf16 v[32:35], v[136:139], v[222:225], 0
	v_mfma_f32_16x16x32_bf16 v[20:23], v[128:131], v[230:233], 0
	v_mfma_f32_16x16x32_bf16 v[16:19], v[136:139], v[230:233], 0
	v_mfma_f32_16x16x32_bf16 v[60:63], v[132:135], v[210:213], v[60:63]
	v_mfma_f32_16x16x32_bf16 v[56:59], v[164:167], v[210:213], v[56:59]
	v_mfma_f32_16x16x32_bf16 v[44:47], v[132:135], v[218:221], v[44:47]
	v_mfma_f32_16x16x32_bf16 v[40:43], v[164:167], v[218:221], v[40:43]
	v_mfma_f32_16x16x32_bf16 v[36:39], v[132:135], v[226:229], v[36:39]
	v_mfma_f32_16x16x32_bf16 v[32:35], v[164:167], v[226:229], v[32:35]
	v_mfma_f32_16x16x32_bf16 v[20:23], v[132:135], v[234:237], v[20:23]
	v_mfma_f32_16x16x32_bf16 v[16:19], v[164:167], v[234:237], v[16:19]
	v_mfma_f32_16x16x32_bf16 v[52:55], v[190:193], v[206:209], 0
	v_mfma_f32_16x16x32_bf16 v[48:51], v[198:201], v[206:209], 0
	v_mfma_f32_16x16x32_bf16 v[28:31], v[190:193], v[214:217], 0
	v_mfma_f32_16x16x32_bf16 v[24:27], v[198:201], v[214:217], 0
	v_mfma_f32_16x16x32_bf16 v[12:15], v[190:193], v[222:225], 0
	v_mfma_f32_16x16x32_bf16 v[8:11], v[198:201], v[222:225], 0
	v_mfma_f32_16x16x32_bf16 v[4:7], v[190:193], v[230:233], 0
	v_mfma_f32_16x16x32_bf16 v[0:3], v[198:201], v[230:233], 0
	v_mfma_f32_16x16x32_bf16 v[52:55], v[194:197], v[210:213], v[52:55]
	v_mfma_f32_16x16x32_bf16 v[48:51], v[202:205], v[210:213], v[48:51]
	v_mfma_f32_16x16x32_bf16 v[28:31], v[194:197], v[218:221], v[28:31]
	v_mfma_f32_16x16x32_bf16 v[24:27], v[202:205], v[218:221], v[24:27]
	v_mfma_f32_16x16x32_bf16 v[12:15], v[194:197], v[226:229], v[12:15]
	v_mfma_f32_16x16x32_bf16 v[8:11], v[202:205], v[226:229], v[8:11]
	v_mfma_f32_16x16x32_bf16 v[4:7], v[194:197], v[234:237], v[4:7]
	v_mfma_f32_16x16x32_bf16 v[0:3], v[202:205], v[234:237], v[0:3]
	s_barrier
	s_branch .Lpeel666_mid
.LBB0_666:
	ds_read_b128 v[128:131], v187
	ds_read_b128 v[132:135], v187 offset:1024
	ds_read_b128 v[136:139], v187 offset:2048
	ds_read_b128 v[164:167], v187 offset:3072
	ds_read_b128 v[190:193], v188
	ds_read_b128 v[194:197], v188 offset:1024
	ds_read_b128 v[198:201], v188 offset:2048
	ds_read_b128 v[202:205], v188 offset:3072
	s_add_u32 s28, s26, 0xfffe0080
	s_addc_u32 s29, s27, -1
	s_cmp_eq_u32 s54, 4
	s_cselect_b32 s35, s19, s29
	s_cselect_b32 s34, s50, s28
	s_cselect_b32 s29, s17, s53
	s_cselect_b32 s28, s51, s52
	v_lshl_add_u64 v[168:169], s[26:27], 0, v[156:157]
	s_add_i32 m0, s25, 0xc000
	ds_read_b128 v[206:209], v189
	ds_read_b128 v[210:213], v189 offset:1024
	ds_read_b128 v[214:217], v189 offset:2048
	ds_read_b128 v[218:221], v189 offset:3072
	ds_read_b128 v[222:225], v189 offset:4096
	ds_read_b128 v[226:229], v189 offset:5120
	ds_read_b128 v[230:233], v189 offset:6144
	ds_read_b128 v[234:237], v189 offset:7168
	global_load_lds_dwordx4 v[168:169], off
	v_lshl_add_u64 v[168:169], s[26:27], 0, v[158:159]
	s_add_i32 m0, s25, 0xe000
	s_nop 0
	global_load_lds_dwordx4 v[168:169], off
	s_waitcnt vmcnt(8)
	s_waitcnt lgkmcnt(0)
	s_barrier
	v_mfma_f32_16x16x32_bf16 v[124:127], v[128:131], v[206:209], v[124:127]
	v_mfma_f32_16x16x32_bf16 v[120:123], v[136:139], v[206:209], v[120:123]
	v_mfma_f32_16x16x32_bf16 v[112:115], v[128:131], v[214:217], v[112:115]
	v_mfma_f32_16x16x32_bf16 v[104:107], v[136:139], v[214:217], v[104:107]
	v_mfma_f32_16x16x32_bf16 v[92:95], v[128:131], v[222:225], v[92:95]
	v_mfma_f32_16x16x32_bf16 v[88:91], v[136:139], v[222:225], v[88:91]
	v_mfma_f32_16x16x32_bf16 v[76:79], v[128:131], v[230:233], v[76:79]
	v_mfma_f32_16x16x32_bf16 v[72:75], v[136:139], v[230:233], v[72:75]
	v_mfma_f32_16x16x32_bf16 v[124:127], v[132:135], v[210:213], v[124:127]
	v_mfma_f32_16x16x32_bf16 v[120:123], v[164:167], v[210:213], v[120:123]
	v_mfma_f32_16x16x32_bf16 v[112:115], v[132:135], v[218:221], v[112:115]
	v_mfma_f32_16x16x32_bf16 v[104:107], v[164:167], v[218:221], v[104:107]
	v_mfma_f32_16x16x32_bf16 v[92:95], v[132:135], v[226:229], v[92:95]
	v_mfma_f32_16x16x32_bf16 v[88:91], v[164:167], v[226:229], v[88:91]
	v_mfma_f32_16x16x32_bf16 v[76:79], v[132:135], v[234:237], v[76:79]
	v_mfma_f32_16x16x32_bf16 v[72:75], v[164:167], v[234:237], v[72:75]
	v_mfma_f32_16x16x32_bf16 v[116:119], v[190:193], v[206:209], v[116:119]
	v_mfma_f32_16x16x32_bf16 v[108:111], v[198:201], v[206:209], v[108:111]
	v_mfma_f32_16x16x32_bf16 v[100:103], v[190:193], v[214:217], v[100:103]
	v_mfma_f32_16x16x32_bf16 v[96:99], v[198:201], v[214:217], v[96:99]
	v_mfma_f32_16x16x32_bf16 v[84:87], v[190:193], v[222:225], v[84:87]
	v_mfma_f32_16x16x32_bf16 v[80:83], v[198:201], v[222:225], v[80:83]
	v_mfma_f32_16x16x32_bf16 v[68:71], v[190:193], v[230:233], v[68:71]
	v_mfma_f32_16x16x32_bf16 v[64:67], v[198:201], v[230:233], v[64:67]
	v_mfma_f32_16x16x32_bf16 v[116:119], v[194:197], v[210:213], v[116:119]
	v_mfma_f32_16x16x32_bf16 v[108:111], v[202:205], v[210:213], v[108:111]
	v_mfma_f32_16x16x32_bf16 v[100:103], v[194:197], v[218:221], v[100:103]
	v_mfma_f32_16x16x32_bf16 v[96:99], v[202:205], v[218:221], v[96:99]
	v_mfma_f32_16x16x32_bf16 v[84:87], v[194:197], v[226:229], v[84:87]
	v_mfma_f32_16x16x32_bf16 v[80:83], v[202:205], v[226:229], v[80:83]
	v_mfma_f32_16x16x32_bf16 v[68:71], v[194:197], v[234:237], v[68:71]
	v_mfma_f32_16x16x32_bf16 v[64:67], v[202:205], v[234:237], v[64:67]
	s_barrier
	s_add_i32 s55, s47, s40
	v_lshl_add_u64 v[168:169], s[28:29], 0, v[150:151]
	s_mov_b32 m0, s55
	ds_read_b128 v[206:209], v189 offset:16384
	ds_read_b128 v[210:213], v189 offset:17408
	ds_read_b128 v[214:217], v189 offset:18432
	ds_read_b128 v[218:221], v189 offset:19456
	ds_read_b128 v[222:225], v189 offset:20480
	ds_read_b128 v[226:229], v189 offset:21504
	ds_read_b128 v[230:233], v189 offset:22528
	ds_read_b128 v[234:237], v189 offset:23552
	global_load_lds_dwordx4 v[168:169], off
	s_add_i32 m0, s55, 0x2000
	s_add_u32 s56, s28, 0x20000
	v_lshl_add_u64 v[238:239], s[28:29], 0, v[154:155]
	s_addc_u32 s57, s29, 0
	s_add_i32 s55, s48, s40
	global_load_lds_dwordx4 v[238:239], off
	v_lshl_add_u64 v[240:241], s[56:57], 0, v[150:151]
	s_mov_b32 m0, s55
	v_lshl_add_u64 v[242:243], s[34:35], 0, v[152:153]
	global_load_lds_dwordx4 v[240:241], off
	v_lshl_add_u64 v[240:241], s[56:57], 0, v[154:155]
	s_add_i32 m0, s55, 0x2000
	s_nop 0
	global_load_lds_dwordx4 v[240:241], off
	v_lshl_add_u64 v[240:241], s[34:35], 0, v[148:149]
	s_mov_b32 m0, s25
	s_nop 0
	global_load_lds_dwordx4 v[240:241], off
	s_mov_b32 m0, s41
	s_nop 0
	global_load_lds_dwordx4 v[242:243], off
	s_waitcnt vmcnt(8)
	s_waitcnt lgkmcnt(0)
	s_barrier
	v_mfma_f32_16x16x32_bf16 v[60:63], v[128:131], v[206:209], v[60:63]
	v_mfma_f32_16x16x32_bf16 v[56:59], v[136:139], v[206:209], v[56:59]
	v_mfma_f32_16x16x32_bf16 v[44:47], v[128:131], v[214:217], v[44:47]
	v_mfma_f32_16x16x32_bf16 v[40:43], v[136:139], v[214:217], v[40:43]
	v_mfma_f32_16x16x32_bf16 v[36:39], v[128:131], v[222:225], v[36:39]
	v_mfma_f32_16x16x32_bf16 v[32:35], v[136:139], v[222:225], v[32:35]
	v_mfma_f32_16x16x32_bf16 v[20:23], v[128:131], v[230:233], v[20:23]
	v_mfma_f32_16x16x32_bf16 v[16:19], v[136:139], v[230:233], v[16:19]
	v_mfma_f32_16x16x32_bf16 v[60:63], v[132:135], v[210:213], v[60:63]
	v_mfma_f32_16x16x32_bf16 v[56:59], v[164:167], v[210:213], v[56:59]
	v_mfma_f32_16x16x32_bf16 v[44:47], v[132:135], v[218:221], v[44:47]
	v_mfma_f32_16x16x32_bf16 v[40:43], v[164:167], v[218:221], v[40:43]
	v_mfma_f32_16x16x32_bf16 v[36:39], v[132:135], v[226:229], v[36:39]
	v_mfma_f32_16x16x32_bf16 v[32:35], v[164:167], v[226:229], v[32:35]
	v_mfma_f32_16x16x32_bf16 v[20:23], v[132:135], v[234:237], v[20:23]
	v_mfma_f32_16x16x32_bf16 v[16:19], v[164:167], v[234:237], v[16:19]
	v_mfma_f32_16x16x32_bf16 v[52:55], v[190:193], v[206:209], v[52:55]
	v_mfma_f32_16x16x32_bf16 v[48:51], v[198:201], v[206:209], v[48:51]
	v_mfma_f32_16x16x32_bf16 v[28:31], v[190:193], v[214:217], v[28:31]
	v_mfma_f32_16x16x32_bf16 v[24:27], v[198:201], v[214:217], v[24:27]
	v_mfma_f32_16x16x32_bf16 v[12:15], v[190:193], v[222:225], v[12:15]
	v_mfma_f32_16x16x32_bf16 v[8:11], v[198:201], v[222:225], v[8:11]
	v_mfma_f32_16x16x32_bf16 v[4:7], v[190:193], v[230:233], v[4:7]
	v_mfma_f32_16x16x32_bf16 v[0:3], v[198:201], v[230:233], v[0:3]
	v_mfma_f32_16x16x32_bf16 v[52:55], v[194:197], v[210:213], v[52:55]
	v_mfma_f32_16x16x32_bf16 v[48:51], v[202:205], v[210:213], v[48:51]
	v_mfma_f32_16x16x32_bf16 v[28:31], v[194:197], v[218:221], v[28:31]
	v_mfma_f32_16x16x32_bf16 v[24:27], v[202:205], v[218:221], v[24:27]
	v_mfma_f32_16x16x32_bf16 v[12:15], v[194:197], v[226:229], v[12:15]
	v_mfma_f32_16x16x32_bf16 v[8:11], v[202:205], v[226:229], v[8:11]
	v_mfma_f32_16x16x32_bf16 v[4:7], v[194:197], v[234:237], v[4:7]
	v_mfma_f32_16x16x32_bf16 v[0:3], v[202:205], v[234:237], v[0:3]
	s_barrier
.Lpeel666_mid:
	s_add_i32 s55, 0, 0x18000
	s_add_i32 s56, 0, 0x1c000
	v_add_u32_e32 v164, s55, v185
	v_add_u32_e32 v202, s56, v185
	ds_read_b128 v[128:131], v164
	ds_read_b128 v[132:135], v164 offset:1024
	ds_read_b128 v[136:139], v164 offset:2048
	ds_read_b128 v[164:167], v164 offset:3072
	ds_read_b128 v[190:193], v202
	ds_read_b128 v[194:197], v202 offset:1024
	ds_read_b128 v[198:201], v202 offset:2048
	ds_read_b128 v[202:205], v202 offset:3072
	s_add_u32 s34, s34, 0x20000
	s_addc_u32 s35, s35, 0
	s_mov_b32 m0, s42
	v_lshl_add_u64 v[244:245], s[34:35], 0, v[148:149]
	ds_read_b128 v[206:209], v189 offset:32768
	ds_read_b128 v[210:213], v189 offset:33792
	ds_read_b128 v[214:217], v189 offset:34816
	ds_read_b128 v[218:221], v189 offset:35840
	ds_read_b128 v[222:225], v189 offset:36864
	ds_read_b128 v[226:229], v189 offset:37888
	ds_read_b128 v[230:233], v189 offset:38912
	ds_read_b128 v[234:237], v189 offset:39936
	global_load_lds_dwordx4 v[244:245], off
	v_lshl_add_u64 v[244:245], s[34:35], 0, v[152:153]
	s_mov_b32 m0, s43
	s_nop 0
	global_load_lds_dwordx4 v[244:245], off
	s_waitcnt vmcnt(8)
	s_waitcnt lgkmcnt(0)
	s_barrier
	v_mfma_f32_16x16x32_bf16 v[124:127], v[128:131], v[206:209], v[124:127]
	v_mfma_f32_16x16x32_bf16 v[120:123], v[136:139], v[206:209], v[120:123]
	v_mfma_f32_16x16x32_bf16 v[112:115], v[128:131], v[214:217], v[112:115]
	v_mfma_f32_16x16x32_bf16 v[104:107], v[136:139], v[214:217], v[104:107]
	v_mfma_f32_16x16x32_bf16 v[92:95], v[128:131], v[222:225], v[92:95]
	v_mfma_f32_16x16x32_bf16 v[88:91], v[136:139], v[222:225], v[88:91]
	v_mfma_f32_16x16x32_bf16 v[76:79], v[128:131], v[230:233], v[76:79]
	v_mfma_f32_16x16x32_bf16 v[72:75], v[136:139], v[230:233], v[72:75]
	v_mfma_f32_16x16x32_bf16 v[124:127], v[132:135], v[210:213], v[124:127]
	v_mfma_f32_16x16x32_bf16 v[120:123], v[164:167], v[210:213], v[120:123]
	v_mfma_f32_16x16x32_bf16 v[112:115], v[132:135], v[218:221], v[112:115]
	v_mfma_f32_16x16x32_bf16 v[104:107], v[164:167], v[218:221], v[104:107]
	v_mfma_f32_16x16x32_bf16 v[92:95], v[132:135], v[226:229], v[92:95]
	v_mfma_f32_16x16x32_bf16 v[88:91], v[164:167], v[226:229], v[88:91]
	v_mfma_f32_16x16x32_bf16 v[76:79], v[132:135], v[234:237], v[76:79]
	v_mfma_f32_16x16x32_bf16 v[72:75], v[164:167], v[234:237], v[72:75]
	v_mfma_f32_16x16x32_bf16 v[116:119], v[190:193], v[206:209], v[116:119]
	v_mfma_f32_16x16x32_bf16 v[108:111], v[198:201], v[206:209], v[108:111]
	v_mfma_f32_16x16x32_bf16 v[100:103], v[190:193], v[214:217], v[100:103]
	v_mfma_f32_16x16x32_bf16 v[96:99], v[198:201], v[214:217], v[96:99]
	v_mfma_f32_16x16x32_bf16 v[84:87], v[190:193], v[222:225], v[84:87]
	v_mfma_f32_16x16x32_bf16 v[80:83], v[198:201], v[222:225], v[80:83]
	v_mfma_f32_16x16x32_bf16 v[68:71], v[190:193], v[230:233], v[68:71]
	v_mfma_f32_16x16x32_bf16 v[64:67], v[198:201], v[230:233], v[64:67]
	v_mfma_f32_16x16x32_bf16 v[116:119], v[194:197], v[210:213], v[116:119]
	v_mfma_f32_16x16x32_bf16 v[108:111], v[202:205], v[210:213], v[108:111]
	v_mfma_f32_16x16x32_bf16 v[100:103], v[194:197], v[218:221], v[100:103]
	v_mfma_f32_16x16x32_bf16 v[96:99], v[202:205], v[218:221], v[96:99]
	v_mfma_f32_16x16x32_bf16 v[84:87], v[194:197], v[226:229], v[84:87]
	v_mfma_f32_16x16x32_bf16 v[80:83], v[202:205], v[226:229], v[80:83]
	v_mfma_f32_16x16x32_bf16 v[68:71], v[194:197], v[234:237], v[68:71]
	v_mfma_f32_16x16x32_bf16 v[64:67], v[202:205], v[234:237], v[64:67]
	s_barrier
	s_add_i32 s34, s55, s40
	v_lshl_add_u64 v[168:169], v[168:169], 0, s[12:13]
	s_mov_b32 m0, s34
	ds_read_b128 v[206:209], v189 offset:49152
	ds_read_b128 v[210:213], v189 offset:50176
	ds_read_b128 v[214:217], v189 offset:51200
	ds_read_b128 v[218:221], v189 offset:52224
	ds_read_b128 v[222:225], v189 offset:53248
	ds_read_b128 v[226:229], v189 offset:54272
	ds_read_b128 v[230:233], v189 offset:55296
	ds_read_b128 v[234:237], v189 offset:56320
	global_load_lds_dwordx4 v[168:169], off
	s_add_i32 m0, s34, 0x2000
	s_add_u32 s28, s28, 0x20080
	v_lshl_add_u64 v[168:169], v[238:239], 0, s[12:13]
	s_addc_u32 s29, s29, 0
	s_add_i32 s34, s56, s40
	global_load_lds_dwordx4 v[168:169], off
	v_lshl_add_u64 v[168:169], s[28:29], 0, v[150:151]
	s_mov_b32 m0, s34
	s_nop 0
	global_load_lds_dwordx4 v[168:169], off
	v_lshl_add_u64 v[168:169], s[28:29], 0, v[154:155]
	s_add_i32 m0, s34, 0x2000
	s_nop 0
	global_load_lds_dwordx4 v[168:169], off
	v_lshl_add_u64 v[168:169], v[240:241], 0, s[12:13]
	s_mov_b32 m0, s45
	s_nop 0
	global_load_lds_dwordx4 v[168:169], off
	v_lshl_add_u64 v[168:169], v[242:243], 0, s[12:13]
	s_mov_b32 m0, s46
	s_nop 0
	global_load_lds_dwordx4 v[168:169], off
	s_waitcnt vmcnt(8)
	s_waitcnt lgkmcnt(0)
	s_barrier
	v_mfma_f32_16x16x32_bf16 v[60:63], v[128:131], v[206:209], v[60:63]
	v_mfma_f32_16x16x32_bf16 v[56:59], v[136:139], v[206:209], v[56:59]
	v_mfma_f32_16x16x32_bf16 v[44:47], v[128:131], v[214:217], v[44:47]
	v_mfma_f32_16x16x32_bf16 v[40:43], v[136:139], v[214:217], v[40:43]
	v_mfma_f32_16x16x32_bf16 v[36:39], v[128:131], v[222:225], v[36:39]
	v_mfma_f32_16x16x32_bf16 v[32:35], v[136:139], v[222:225], v[32:35]
	v_mfma_f32_16x16x32_bf16 v[20:23], v[128:131], v[230:233], v[20:23]
	v_mfma_f32_16x16x32_bf16 v[16:19], v[136:139], v[230:233], v[16:19]
	v_mfma_f32_16x16x32_bf16 v[60:63], v[132:135], v[210:213], v[60:63]
	v_mfma_f32_16x16x32_bf16 v[56:59], v[164:167], v[210:213], v[56:59]
	v_mfma_f32_16x16x32_bf16 v[44:47], v[132:135], v[218:221], v[44:47]
	v_mfma_f32_16x16x32_bf16 v[40:43], v[164:167], v[218:221], v[40:43]
	v_mfma_f32_16x16x32_bf16 v[36:39], v[132:135], v[226:229], v[36:39]
	v_mfma_f32_16x16x32_bf16 v[32:35], v[164:167], v[226:229], v[32:35]
	v_mfma_f32_16x16x32_bf16 v[20:23], v[132:135], v[234:237], v[20:23]
	v_mfma_f32_16x16x32_bf16 v[16:19], v[164:167], v[234:237], v[16:19]
	v_mfma_f32_16x16x32_bf16 v[52:55], v[190:193], v[206:209], v[52:55]
	v_mfma_f32_16x16x32_bf16 v[48:51], v[198:201], v[206:209], v[48:51]
	v_mfma_f32_16x16x32_bf16 v[28:31], v[190:193], v[214:217], v[28:31]
	v_mfma_f32_16x16x32_bf16 v[24:27], v[198:201], v[214:217], v[24:27]
	v_mfma_f32_16x16x32_bf16 v[12:15], v[190:193], v[222:225], v[12:15]
	v_mfma_f32_16x16x32_bf16 v[8:11], v[198:201], v[222:225], v[8:11]
	v_mfma_f32_16x16x32_bf16 v[4:7], v[190:193], v[230:233], v[4:7]
	v_mfma_f32_16x16x32_bf16 v[0:3], v[198:201], v[230:233], v[0:3]
	v_mfma_f32_16x16x32_bf16 v[52:55], v[194:197], v[210:213], v[52:55]
	v_mfma_f32_16x16x32_bf16 v[48:51], v[202:205], v[210:213], v[48:51]
	v_mfma_f32_16x16x32_bf16 v[28:31], v[194:197], v[218:221], v[28:31]
	v_mfma_f32_16x16x32_bf16 v[24:27], v[202:205], v[218:221], v[24:27]
	v_mfma_f32_16x16x32_bf16 v[12:15], v[194:197], v[226:229], v[12:15]
	v_mfma_f32_16x16x32_bf16 v[8:11], v[202:205], v[226:229], v[8:11]
	v_mfma_f32_16x16x32_bf16 v[4:7], v[194:197], v[234:237], v[4:7]
	v_mfma_f32_16x16x32_bf16 v[0:3], v[202:205], v[234:237], v[0:3]
	s_barrier
	s_add_i32 s54, s54, 2
	s_add_u32 s26, s26, 0x100
	s_addc_u32 s27, s27, 0
	s_add_u32 s52, s52, 0x100
	s_addc_u32 s53, s53, 0
	s_cmp_gt_u32 s54, 5
	s_cbranch_scc0 .LBB0_666
	s_and_b64 vcc, exec, s[14:15]
	s_cbranch_vccz .LBB0_669
	s_barrier

.LBB0_685:
	s_ashr_i32 s23, s22, 31
	s_lshl_b64 s[24:25], s[22:23], 19
	s_add_u32 s24, s72, s24
	s_addc_u32 s25, s73, s25
	s_and_b64 s[26:27], s[0:1], exec
	s_cselect_b32 s23, s25, s31
	s_cselect_b32 s49, s24, s30
	s_ashr_i32 s21, s20, 31
	s_lshl_b64 s[26:27], s[20:21], 19
	v_readlane_b32 s36, v246, 40
	v_readlane_b32 s37, v246, 41
	s_add_u32 s26, s36, s26
	s_addc_u32 s27, s37, s27
	s_and_b64 s[36:37], s[0:1], exec
	s_cselect_b32 s21, s27, s35
	s_cselect_b32 s50, s26, s34
	s_add_u32 s30, s30, 0x40080
	s_addc_u32 s31, s31, 0
	s_add_u32 s51, s34, 0x100
	s_addc_u32 s52, s35, 0
	s_mov_b32 s53, -2
	ds_read_b128 v[136:139], v153
	ds_read_b128 v[156:159], v153 offset:1024
	ds_read_b128 v[160:163], v153 offset:2048
	ds_read_b128 v[164:167], v153 offset:3072
	ds_read_b128 v[180:183], v154
	ds_read_b128 v[184:187], v154 offset:1024
	ds_read_b128 v[188:191], v154 offset:2048
	ds_read_b128 v[192:195], v154 offset:3072
	s_add_u32 s34, s30, 0xfffc0080
	s_addc_u32 s35, s31, -1
	s_cmp_eq_u32 s53, 12
	s_cselect_b32 s37, s23, s35
	s_cselect_b32 s36, s49, s34
	s_cselect_b32 s35, s21, s52
	s_cselect_b32 s34, s50, s51
	v_lshl_add_u64 v[148:149], s[30:31], 0, v[128:129]
	s_add_i32 m0, s29, 0xc000
	ds_read_b128 v[196:199], v155
	ds_read_b128 v[200:203], v155 offset:1024
	ds_read_b128 v[204:207], v155 offset:2048
	ds_read_b128 v[208:211], v155 offset:3072
	ds_read_b128 v[212:215], v155 offset:4096
	ds_read_b128 v[216:219], v155 offset:5120
	ds_read_b128 v[220:223], v155 offset:6144
	ds_read_b128 v[224:227], v155 offset:7168
	global_load_lds_dwordx4 v[148:149], off
	v_lshl_add_u64 v[148:149], s[30:31], 0, v[130:131]
	s_add_i32 m0, s29, 0xe000
	s_nop 0
	global_load_lds_dwordx4 v[148:149], off
	s_waitcnt vmcnt(8)
	s_waitcnt lgkmcnt(0)
	s_barrier
	v_mfma_f32_16x16x32_bf16 v[124:127], v[136:139], v[196:199], 0
	v_mfma_f32_16x16x32_bf16 v[120:123], v[160:163], v[196:199], 0
	v_mfma_f32_16x16x32_bf16 v[108:111], v[136:139], v[204:207], 0
	v_mfma_f32_16x16x32_bf16 v[104:107], v[160:163], v[204:207], 0
	v_mfma_f32_16x16x32_bf16 v[92:95], v[136:139], v[212:215], 0
	v_mfma_f32_16x16x32_bf16 v[88:91], v[160:163], v[212:215], 0
	v_mfma_f32_16x16x32_bf16 v[76:79], v[136:139], v[220:223], 0
	v_mfma_f32_16x16x32_bf16 v[72:75], v[160:163], v[220:223], 0
	v_mfma_f32_16x16x32_bf16 v[124:127], v[156:159], v[200:203], v[124:127]
	v_mfma_f32_16x16x32_bf16 v[120:123], v[164:167], v[200:203], v[120:123]
	v_mfma_f32_16x16x32_bf16 v[108:111], v[156:159], v[208:211], v[108:111]
	v_mfma_f32_16x16x32_bf16 v[104:107], v[164:167], v[208:211], v[104:107]
	v_mfma_f32_16x16x32_bf16 v[92:95], v[156:159], v[216:219], v[92:95]
	v_mfma_f32_16x16x32_bf16 v[88:91], v[164:167], v[216:219], v[88:91]
	v_mfma_f32_16x16x32_bf16 v[76:79], v[156:159], v[224:227], v[76:79]
	v_mfma_f32_16x16x32_bf16 v[72:75], v[164:167], v[224:227], v[72:75]
	v_mfma_f32_16x16x32_bf16 v[116:119], v[180:183], v[196:199], 0
	v_mfma_f32_16x16x32_bf16 v[112:115], v[188:191], v[196:199], 0
	v_mfma_f32_16x16x32_bf16 v[100:103], v[180:183], v[204:207], 0
	v_mfma_f32_16x16x32_bf16 v[96:99], v[188:191], v[204:207], 0
	v_mfma_f32_16x16x32_bf16 v[84:87], v[180:183], v[212:215], 0
	v_mfma_f32_16x16x32_bf16 v[80:83], v[188:191], v[212:215], 0
	v_mfma_f32_16x16x32_bf16 v[68:71], v[180:183], v[220:223], 0
	v_mfma_f32_16x16x32_bf16 v[64:67], v[188:191], v[220:223], 0
	v_mfma_f32_16x16x32_bf16 v[116:119], v[184:187], v[200:203], v[116:119]
	v_mfma_f32_16x16x32_bf16 v[112:115], v[192:195], v[200:203], v[112:115]
	v_mfma_f32_16x16x32_bf16 v[100:103], v[184:187], v[208:211], v[100:103]
	v_mfma_f32_16x16x32_bf16 v[96:99], v[192:195], v[208:211], v[96:99]
	v_mfma_f32_16x16x32_bf16 v[84:87], v[184:187], v[216:219], v[84:87]
	v_mfma_f32_16x16x32_bf16 v[80:83], v[192:195], v[216:219], v[80:83]
	v_mfma_f32_16x16x32_bf16 v[68:71], v[184:187], v[224:227], v[68:71]
	v_mfma_f32_16x16x32_bf16 v[64:67], v[192:195], v[224:227], v[64:67]
	s_barrier
	s_add_i32 s54, s46, s40
	v_lshl_add_u64 v[148:149], s[34:35], 0, v[142:143]
	s_mov_b32 m0, s54
	ds_read_b128 v[196:199], v155 offset:16384
	ds_read_b128 v[200:203], v155 offset:17408
	ds_read_b128 v[204:207], v155 offset:18432
	ds_read_b128 v[208:211], v155 offset:19456
	ds_read_b128 v[212:215], v155 offset:20480
	ds_read_b128 v[216:219], v155 offset:21504
	ds_read_b128 v[220:223], v155 offset:22528
	ds_read_b128 v[224:227], v155 offset:23552
	global_load_lds_dwordx4 v[148:149], off
	s_add_i32 m0, s54, 0x2000
	s_add_u32 s54, s34, 0x40000
	v_lshl_add_u64 v[168:169], s[34:35], 0, v[146:147]
	s_addc_u32 s55, s35, 0
	s_add_i32 s56, s47, s40
	global_load_lds_dwordx4 v[168:169], off
	v_lshl_add_u64 v[228:229], s[54:55], 0, v[142:143]
	s_mov_b32 m0, s56
	v_lshl_add_u64 v[230:231], s[36:37], 0, v[144:145]
	global_load_lds_dwordx4 v[228:229], off
	v_lshl_add_u64 v[228:229], s[54:55], 0, v[146:147]
	s_add_i32 m0, s56, 0x2000
	s_nop 0
	global_load_lds_dwordx4 v[228:229], off
	v_lshl_add_u64 v[228:229], s[36:37], 0, v[140:141]
	s_mov_b32 m0, s29
	s_nop 0
	global_load_lds_dwordx4 v[228:229], off
	s_mov_b32 m0, s39
	s_nop 0
	global_load_lds_dwordx4 v[230:231], off
	s_waitcnt vmcnt(8)
	s_waitcnt lgkmcnt(0)
	s_barrier
	v_mfma_f32_16x16x32_bf16 v[60:63], v[136:139], v[196:199], 0
	v_mfma_f32_16x16x32_bf16 v[56:59], v[160:163], v[196:199], 0
	v_mfma_f32_16x16x32_bf16 v[44:47], v[136:139], v[204:207], 0
	v_mfma_f32_16x16x32_bf16 v[40:43], v[160:163], v[204:207], 0
	v_mfma_f32_16x16x32_bf16 v[28:31], v[136:139], v[212:215], 0
	v_mfma_f32_16x16x32_bf16 v[24:27], v[160:163], v[212:215], 0
	v_mfma_f32_16x16x32_bf16 v[12:15], v[136:139], v[220:223], 0
	v_mfma_f32_16x16x32_bf16 v[8:11], v[160:163], v[220:223], 0
	v_mfma_f32_16x16x32_bf16 v[60:63], v[156:159], v[200:203], v[60:63]
	v_mfma_f32_16x16x32_bf16 v[56:59], v[164:167], v[200:203], v[56:59]
	v_mfma_f32_16x16x32_bf16 v[44:47], v[156:159], v[208:211], v[44:47]
	v_mfma_f32_16x16x32_bf16 v[40:43], v[164:167], v[208:211], v[40:43]
	v_mfma_f32_16x16x32_bf16 v[28:31], v[156:159], v[216:219], v[28:31]
	v_mfma_f32_16x16x32_bf16 v[24:27], v[164:167], v[216:219], v[24:27]
	v_mfma_f32_16x16x32_bf16 v[12:15], v[156:159], v[224:227], v[12:15]
	v_mfma_f32_16x16x32_bf16 v[8:11], v[164:167], v[224:227], v[8:11]
	v_mfma_f32_16x16x32_bf16 v[52:55], v[180:183], v[196:199], 0
	v_mfma_f32_16x16x32_bf16 v[48:51], v[188:191], v[196:199], 0
	v_mfma_f32_16x16x32_bf16 v[36:39], v[180:183], v[204:207], 0
	v_mfma_f32_16x16x32_bf16 v[32:35], v[188:191], v[204:207], 0
	v_mfma_f32_16x16x32_bf16 v[20:23], v[180:183], v[212:215], 0
	v_mfma_f32_16x16x32_bf16 v[16:19], v[188:191], v[212:215], 0
	v_mfma_f32_16x16x32_bf16 v[4:7], v[180:183], v[220:223], 0
	v_mfma_f32_16x16x32_bf16 v[0:3], v[188:191], v[220:223], 0
	v_mfma_f32_16x16x32_bf16 v[52:55], v[184:187], v[200:203], v[52:55]
	v_mfma_f32_16x16x32_bf16 v[48:51], v[192:195], v[200:203], v[48:51]
	v_mfma_f32_16x16x32_bf16 v[36:39], v[184:187], v[208:211], v[36:39]
	v_mfma_f32_16x16x32_bf16 v[32:35], v[192:195], v[208:211], v[32:35]
	v_mfma_f32_16x16x32_bf16 v[20:23], v[184:187], v[216:219], v[20:23]
	v_mfma_f32_16x16x32_bf16 v[16:19], v[192:195], v[216:219], v[16:19]
	v_mfma_f32_16x16x32_bf16 v[4:7], v[184:187], v[224:227], v[4:7]
	v_mfma_f32_16x16x32_bf16 v[0:3], v[192:195], v[224:227], v[0:3]
	s_barrier
	s_branch .Lpeel686_mid
.LBB0_686:
	ds_read_b128 v[136:139], v153
	ds_read_b128 v[156:159], v153 offset:1024
	ds_read_b128 v[160:163], v153 offset:2048
	ds_read_b128 v[164:167], v153 offset:3072
	ds_read_b128 v[180:183], v154
	ds_read_b128 v[184:187], v154 offset:1024
	ds_read_b128 v[188:191], v154 offset:2048
	ds_read_b128 v[192:195], v154 offset:3072
	s_add_u32 s34, s30, 0xfffc0080
	s_addc_u32 s35, s31, -1
	s_cmp_eq_u32 s53, 12
	s_cselect_b32 s37, s23, s35
	s_cselect_b32 s36, s49, s34
	s_cselect_b32 s35, s21, s52
	s_cselect_b32 s34, s50, s51
	v_lshl_add_u64 v[148:149], s[30:31], 0, v[128:129]
	s_add_i32 m0, s29, 0xc000
	ds_read_b128 v[196:199], v155
	ds_read_b128 v[200:203], v155 offset:1024
	ds_read_b128 v[204:207], v155 offset:2048
	ds_read_b128 v[208:211], v155 offset:3072
	ds_read_b128 v[212:215], v155 offset:4096
	ds_read_b128 v[216:219], v155 offset:5120
	ds_read_b128 v[220:223], v155 offset:6144
	ds_read_b128 v[224:227], v155 offset:7168
	global_load_lds_dwordx4 v[148:149], off
	v_lshl_add_u64 v[148:149], s[30:31], 0, v[130:131]
	s_add_i32 m0, s29, 0xe000
	s_nop 0
	global_load_lds_dwordx4 v[148:149], off
	s_waitcnt vmcnt(8)
	s_waitcnt lgkmcnt(0)
	s_barrier
	v_mfma_f32_16x16x32_bf16 v[124:127], v[136:139], v[196:199], v[124:127]
	v_mfma_f32_16x16x32_bf16 v[120:123], v[160:163], v[196:199], v[120:123]
	v_mfma_f32_16x16x32_bf16 v[108:111], v[136:139], v[204:207], v[108:111]
	v_mfma_f32_16x16x32_bf16 v[104:107], v[160:163], v[204:207], v[104:107]
	v_mfma_f32_16x16x32_bf16 v[92:95], v[136:139], v[212:215], v[92:95]
	v_mfma_f32_16x16x32_bf16 v[88:91], v[160:163], v[212:215], v[88:91]
	v_mfma_f32_16x16x32_bf16 v[76:79], v[136:139], v[220:223], v[76:79]
	v_mfma_f32_16x16x32_bf16 v[72:75], v[160:163], v[220:223], v[72:75]
	v_mfma_f32_16x16x32_bf16 v[124:127], v[156:159], v[200:203], v[124:127]
	v_mfma_f32_16x16x32_bf16 v[120:123], v[164:167], v[200:203], v[120:123]
	v_mfma_f32_16x16x32_bf16 v[108:111], v[156:159], v[208:211], v[108:111]
	v_mfma_f32_16x16x32_bf16 v[104:107], v[164:167], v[208:211], v[104:107]
	v_mfma_f32_16x16x32_bf16 v[92:95], v[156:159], v[216:219], v[92:95]
	v_mfma_f32_16x16x32_bf16 v[88:91], v[164:167], v[216:219], v[88:91]
	v_mfma_f32_16x16x32_bf16 v[76:79], v[156:159], v[224:227], v[76:79]
	v_mfma_f32_16x16x32_bf16 v[72:75], v[164:167], v[224:227], v[72:75]
	v_mfma_f32_16x16x32_bf16 v[116:119], v[180:183], v[196:199], v[116:119]
	v_mfma_f32_16x16x32_bf16 v[112:115], v[188:191], v[196:199], v[112:115]
	v_mfma_f32_16x16x32_bf16 v[100:103], v[180:183], v[204:207], v[100:103]
	v_mfma_f32_16x16x32_bf16 v[96:99], v[188:191], v[204:207], v[96:99]
	v_mfma_f32_16x16x32_bf16 v[84:87], v[180:183], v[212:215], v[84:87]
	v_mfma_f32_16x16x32_bf16 v[80:83], v[188:191], v[212:215], v[80:83]
	v_mfma_f32_16x16x32_bf16 v[68:71], v[180:183], v[220:223], v[68:71]
	v_mfma_f32_16x16x32_bf16 v[64:67], v[188:191], v[220:223], v[64:67]
	v_mfma_f32_16x16x32_bf16 v[116:119], v[184:187], v[200:203], v[116:119]
	v_mfma_f32_16x16x32_bf16 v[112:115], v[192:195], v[200:203], v[112:115]
	v_mfma_f32_16x16x32_bf16 v[100:103], v[184:187], v[208:211], v[100:103]
	v_mfma_f32_16x16x32_bf16 v[96:99], v[192:195], v[208:211], v[96:99]
	v_mfma_f32_16x16x32_bf16 v[84:87], v[184:187], v[216:219], v[84:87]
	v_mfma_f32_16x16x32_bf16 v[80:83], v[192:195], v[216:219], v[80:83]
	v_mfma_f32_16x16x32_bf16 v[68:71], v[184:187], v[224:227], v[68:71]
	v_mfma_f32_16x16x32_bf16 v[64:67], v[192:195], v[224:227], v[64:67]
	s_barrier
	s_add_i32 s54, s46, s40
	v_lshl_add_u64 v[148:149], s[34:35], 0, v[142:143]
	s_mov_b32 m0, s54
	ds_read_b128 v[196:199], v155 offset:16384
	ds_read_b128 v[200:203], v155 offset:17408
	ds_read_b128 v[204:207], v155 offset:18432
	ds_read_b128 v[208:211], v155 offset:19456
	ds_read_b128 v[212:215], v155 offset:20480
	ds_read_b128 v[216:219], v155 offset:21504
	ds_read_b128 v[220:223], v155 offset:22528
	ds_read_b128 v[224:227], v155 offset:23552
	global_load_lds_dwordx4 v[148:149], off
	s_add_i32 m0, s54, 0x2000
	s_add_u32 s54, s34, 0x40000
	v_lshl_add_u64 v[168:169], s[34:35], 0, v[146:147]
	s_addc_u32 s55, s35, 0
	s_add_i32 s56, s47, s40
	global_load_lds_dwordx4 v[168:169], off
	v_lshl_add_u64 v[228:229], s[54:55], 0, v[142:143]
	s_mov_b32 m0, s56
	v_lshl_add_u64 v[230:231], s[36:37], 0, v[144:145]
	global_load_lds_dwordx4 v[228:229], off
	v_lshl_add_u64 v[228:229], s[54:55], 0, v[146:147]
	s_add_i32 m0, s56, 0x2000
	s_nop 0
	global_load_lds_dwordx4 v[228:229], off
	v_lshl_add_u64 v[228:229], s[36:37], 0, v[140:141]
	s_mov_b32 m0, s29
	s_nop 0
	global_load_lds_dwordx4 v[228:229], off
	s_mov_b32 m0, s39
	s_nop 0
	global_load_lds_dwordx4 v[230:231], off
	s_waitcnt vmcnt(8)
	s_waitcnt lgkmcnt(0)
	s_barrier
	v_mfma_f32_16x16x32_bf16 v[60:63], v[136:139], v[196:199], v[60:63]
	v_mfma_f32_16x16x32_bf16 v[56:59], v[160:163], v[196:199], v[56:59]
	v_mfma_f32_16x16x32_bf16 v[44:47], v[136:139], v[204:207], v[44:47]
	v_mfma_f32_16x16x32_bf16 v[40:43], v[160:163], v[204:207], v[40:43]
	v_mfma_f32_16x16x32_bf16 v[28:31], v[136:139], v[212:215], v[28:31]
	v_mfma_f32_16x16x32_bf16 v[24:27], v[160:163], v[212:215], v[24:27]
	v_mfma_f32_16x16x32_bf16 v[12:15], v[136:139], v[220:223], v[12:15]
	v_mfma_f32_16x16x32_bf16 v[8:11], v[160:163], v[220:223], v[8:11]
	v_mfma_f32_16x16x32_bf16 v[60:63], v[156:159], v[200:203], v[60:63]
	v_mfma_f32_16x16x32_bf16 v[56:59], v[164:167], v[200:203], v[56:59]
	v_mfma_f32_16x16x32_bf16 v[44:47], v[156:159], v[208:211], v[44:47]
	v_mfma_f32_16x16x32_bf16 v[40:43], v[164:167], v[208:211], v[40:43]
	v_mfma_f32_16x16x32_bf16 v[28:31], v[156:159], v[216:219], v[28:31]
	v_mfma_f32_16x16x32_bf16 v[24:27], v[164:167], v[216:219], v[24:27]
	v_mfma_f32_16x16x32_bf16 v[12:15], v[156:159], v[224:227], v[12:15]
	v_mfma_f32_16x16x32_bf16 v[8:11], v[164:167], v[224:227], v[8:11]
	v_mfma_f32_16x16x32_bf16 v[52:55], v[180:183], v[196:199], v[52:55]
	v_mfma_f32_16x16x32_bf16 v[48:51], v[188:191], v[196:199], v[48:51]
	v_mfma_f32_16x16x32_bf16 v[36:39], v[180:183], v[204:207], v[36:39]
	v_mfma_f32_16x16x32_bf16 v[32:35], v[188:191], v[204:207], v[32:35]
	v_mfma_f32_16x16x32_bf16 v[20:23], v[180:183], v[212:215], v[20:23]
	v_mfma_f32_16x16x32_bf16 v[16:19], v[188:191], v[212:215], v[16:19]
	v_mfma_f32_16x16x32_bf16 v[4:7], v[180:183], v[220:223], v[4:7]
	v_mfma_f32_16x16x32_bf16 v[0:3], v[188:191], v[220:223], v[0:3]
	v_mfma_f32_16x16x32_bf16 v[52:55], v[184:187], v[200:203], v[52:55]
	v_mfma_f32_16x16x32_bf16 v[48:51], v[192:195], v[200:203], v[48:51]
	v_mfma_f32_16x16x32_bf16 v[36:39], v[184:187], v[208:211], v[36:39]
	v_mfma_f32_16x16x32_bf16 v[32:35], v[192:195], v[208:211], v[32:35]
	v_mfma_f32_16x16x32_bf16 v[20:23], v[184:187], v[216:219], v[20:23]
	v_mfma_f32_16x16x32_bf16 v[16:19], v[192:195], v[216:219], v[16:19]
	v_mfma_f32_16x16x32_bf16 v[4:7], v[184:187], v[224:227], v[4:7]
	v_mfma_f32_16x16x32_bf16 v[0:3], v[192:195], v[224:227], v[0:3]
	s_barrier
.Lpeel686_mid:
	s_add_i32 s54, 0, 0x18000
	s_add_i32 s55, 0, 0x1c000
	v_add_u32_e32 v164, s54, v151
	v_add_u32_e32 v179, s55, v151
	ds_read_b128 v[136:139], v164
	ds_read_b128 v[156:159], v164 offset:1024
	ds_read_b128 v[160:163], v164 offset:2048
	ds_read_b128 v[164:167], v164 offset:3072
	ds_read_b128 v[180:183], v179
	ds_read_b128 v[184:187], v179 offset:1024
	ds_read_b128 v[188:191], v179 offset:2048
	ds_read_b128 v[192:195], v179 offset:3072
	s_add_u32 s36, s36, 0x40000
	s_addc_u32 s37, s37, 0
	s_mov_b32 m0, s41
	v_lshl_add_u64 v[232:233], s[36:37], 0, v[140:141]
	ds_read_b128 v[196:199], v155 offset:32768
	ds_read_b128 v[200:203], v155 offset:33792
	ds_read_b128 v[204:207], v155 offset:34816
	ds_read_b128 v[208:211], v155 offset:35840
	ds_read_b128 v[212:215], v155 offset:36864
	ds_read_b128 v[216:219], v155 offset:37888
	ds_read_b128 v[220:223], v155 offset:38912
	ds_read_b128 v[224:227], v155 offset:39936
	global_load_lds_dwordx4 v[232:233], off
	v_lshl_add_u64 v[232:233], s[36:37], 0, v[144:145]
	s_mov_b32 m0, s42
	s_nop 0
	global_load_lds_dwordx4 v[232:233], off
	s_waitcnt vmcnt(8)
	s_waitcnt lgkmcnt(0)
	s_barrier
	v_mfma_f32_16x16x32_bf16 v[124:127], v[136:139], v[196:199], v[124:127]
	v_mfma_f32_16x16x32_bf16 v[120:123], v[160:163], v[196:199], v[120:123]
	v_mfma_f32_16x16x32_bf16 v[108:111], v[136:139], v[204:207], v[108:111]
	v_mfma_f32_16x16x32_bf16 v[104:107], v[160:163], v[204:207], v[104:107]
	v_mfma_f32_16x16x32_bf16 v[92:95], v[136:139], v[212:215], v[92:95]
	v_mfma_f32_16x16x32_bf16 v[88:91], v[160:163], v[212:215], v[88:91]
	v_mfma_f32_16x16x32_bf16 v[76:79], v[136:139], v[220:223], v[76:79]
	v_mfma_f32_16x16x32_bf16 v[72:75], v[160:163], v[220:223], v[72:75]
	v_mfma_f32_16x16x32_bf16 v[124:127], v[156:159], v[200:203], v[124:127]
	v_mfma_f32_16x16x32_bf16 v[120:123], v[164:167], v[200:203], v[120:123]
	v_mfma_f32_16x16x32_bf16 v[108:111], v[156:159], v[208:211], v[108:111]
	v_mfma_f32_16x16x32_bf16 v[104:107], v[164:167], v[208:211], v[104:107]
	v_mfma_f32_16x16x32_bf16 v[92:95], v[156:159], v[216:219], v[92:95]
	v_mfma_f32_16x16x32_bf16 v[88:91], v[164:167], v[216:219], v[88:91]
	v_mfma_f32_16x16x32_bf16 v[76:79], v[156:159], v[224:227], v[76:79]
	v_mfma_f32_16x16x32_bf16 v[72:75], v[164:167], v[224:227], v[72:75]
	v_mfma_f32_16x16x32_bf16 v[116:119], v[180:183], v[196:199], v[116:119]
	v_mfma_f32_16x16x32_bf16 v[112:115], v[188:191], v[196:199], v[112:115]
	v_mfma_f32_16x16x32_bf16 v[100:103], v[180:183], v[204:207], v[100:103]
	v_mfma_f32_16x16x32_bf16 v[96:99], v[188:191], v[204:207], v[96:99]
	v_mfma_f32_16x16x32_bf16 v[84:87], v[180:183], v[212:215], v[84:87]
	v_mfma_f32_16x16x32_bf16 v[80:83], v[188:191], v[212:215], v[80:83]
	v_mfma_f32_16x16x32_bf16 v[68:71], v[180:183], v[220:223], v[68:71]
	v_mfma_f32_16x16x32_bf16 v[64:67], v[188:191], v[220:223], v[64:67]
	v_mfma_f32_16x16x32_bf16 v[116:119], v[184:187], v[200:203], v[116:119]
	v_mfma_f32_16x16x32_bf16 v[112:115], v[192:195], v[200:203], v[112:115]
	v_mfma_f32_16x16x32_bf16 v[100:103], v[184:187], v[208:211], v[100:103]
	v_mfma_f32_16x16x32_bf16 v[96:99], v[192:195], v[208:211], v[96:99]
	v_mfma_f32_16x16x32_bf16 v[84:87], v[184:187], v[216:219], v[84:87]
	v_mfma_f32_16x16x32_bf16 v[80:83], v[192:195], v[216:219], v[80:83]
	v_mfma_f32_16x16x32_bf16 v[68:71], v[184:187], v[224:227], v[68:71]
	v_mfma_f32_16x16x32_bf16 v[64:67], v[192:195], v[224:227], v[64:67]
	s_barrier
	s_add_i32 s36, s54, s40
	v_lshl_add_u64 v[148:149], v[148:149], 0, s[10:11]
	s_mov_b32 m0, s36
	ds_read_b128 v[196:199], v155 offset:49152
	ds_read_b128 v[200:203], v155 offset:50176
	ds_read_b128 v[204:207], v155 offset:51200
	ds_read_b128 v[208:211], v155 offset:52224
	ds_read_b128 v[212:215], v155 offset:53248
	ds_read_b128 v[216:219], v155 offset:54272
	ds_read_b128 v[220:223], v155 offset:55296
	ds_read_b128 v[224:227], v155 offset:56320
	global_load_lds_dwordx4 v[148:149], off
	s_add_i32 m0, s36, 0x2000
	s_add_u32 s34, s34, 0x40080
	v_lshl_add_u64 v[148:149], v[168:169], 0, s[10:11]
	s_addc_u32 s35, s35, 0
	s_add_i32 s36, s55, s40
	global_load_lds_dwordx4 v[148:149], off
	v_lshl_add_u64 v[148:149], s[34:35], 0, v[142:143]
	s_mov_b32 m0, s36
	s_nop 0
	global_load_lds_dwordx4 v[148:149], off
	v_lshl_add_u64 v[148:149], s[34:35], 0, v[146:147]
	s_add_i32 m0, s36, 0x2000
	s_nop 0
	global_load_lds_dwordx4 v[148:149], off
	v_lshl_add_u64 v[148:149], v[228:229], 0, s[10:11]
	s_mov_b32 m0, s44
	s_nop 0
	global_load_lds_dwordx4 v[148:149], off
	v_lshl_add_u64 v[148:149], v[230:231], 0, s[10:11]
	s_mov_b32 m0, s45
	s_nop 0
	global_load_lds_dwordx4 v[148:149], off
	s_waitcnt vmcnt(8)
	s_waitcnt lgkmcnt(0)
	s_barrier
	v_mfma_f32_16x16x32_bf16 v[60:63], v[136:139], v[196:199], v[60:63]
	v_mfma_f32_16x16x32_bf16 v[56:59], v[160:163], v[196:199], v[56:59]
	v_mfma_f32_16x16x32_bf16 v[44:47], v[136:139], v[204:207], v[44:47]
	v_mfma_f32_16x16x32_bf16 v[40:43], v[160:163], v[204:207], v[40:43]
	v_mfma_f32_16x16x32_bf16 v[28:31], v[136:139], v[212:215], v[28:31]
	v_mfma_f32_16x16x32_bf16 v[24:27], v[160:163], v[212:215], v[24:27]
	v_mfma_f32_16x16x32_bf16 v[12:15], v[136:139], v[220:223], v[12:15]
	v_mfma_f32_16x16x32_bf16 v[8:11], v[160:163], v[220:223], v[8:11]
	v_mfma_f32_16x16x32_bf16 v[60:63], v[156:159], v[200:203], v[60:63]
	v_mfma_f32_16x16x32_bf16 v[56:59], v[164:167], v[200:203], v[56:59]
	v_mfma_f32_16x16x32_bf16 v[44:47], v[156:159], v[208:211], v[44:47]
	v_mfma_f32_16x16x32_bf16 v[40:43], v[164:167], v[208:211], v[40:43]
	v_mfma_f32_16x16x32_bf16 v[28:31], v[156:159], v[216:219], v[28:31]
	v_mfma_f32_16x16x32_bf16 v[24:27], v[164:167], v[216:219], v[24:27]
	v_mfma_f32_16x16x32_bf16 v[12:15], v[156:159], v[224:227], v[12:15]
	v_mfma_f32_16x16x32_bf16 v[8:11], v[164:167], v[224:227], v[8:11]
	v_mfma_f32_16x16x32_bf16 v[52:55], v[180:183], v[196:199], v[52:55]
	v_mfma_f32_16x16x32_bf16 v[48:51], v[188:191], v[196:199], v[48:51]
	v_mfma_f32_16x16x32_bf16 v[36:39], v[180:183], v[204:207], v[36:39]
	v_mfma_f32_16x16x32_bf16 v[32:35], v[188:191], v[204:207], v[32:35]
	v_mfma_f32_16x16x32_bf16 v[20:23], v[180:183], v[212:215], v[20:23]
	v_mfma_f32_16x16x32_bf16 v[16:19], v[188:191], v[212:215], v[16:19]
	v_mfma_f32_16x16x32_bf16 v[4:7], v[180:183], v[220:223], v[4:7]
	v_mfma_f32_16x16x32_bf16 v[0:3], v[188:191], v[220:223], v[0:3]
	v_mfma_f32_16x16x32_bf16 v[52:55], v[184:187], v[200:203], v[52:55]
	v_mfma_f32_16x16x32_bf16 v[48:51], v[192:195], v[200:203], v[48:51]
	v_mfma_f32_16x16x32_bf16 v[36:39], v[184:187], v[208:211], v[36:39]
	v_mfma_f32_16x16x32_bf16 v[32:35], v[192:195], v[208:211], v[32:35]
	v_mfma_f32_16x16x32_bf16 v[20:23], v[184:187], v[216:219], v[20:23]
	v_mfma_f32_16x16x32_bf16 v[16:19], v[192:195], v[216:219], v[16:19]
	v_mfma_f32_16x16x32_bf16 v[4:7], v[184:187], v[224:227], v[4:7]
	v_mfma_f32_16x16x32_bf16 v[0:3], v[192:195], v[224:227], v[0:3]
	s_barrier
	s_add_i32 s53, s53, 2
	s_add_u32 s30, s30, 0x100
	s_addc_u32 s31, s31, 0
	s_add_u32 s51, s51, 0x100
	s_addc_u32 s52, s52, 0
	s_cmp_gt_u32 s53, 13
	s_cbranch_scc0 .LBB0_686
	s_and_b64 vcc, exec, s[12:13]
	s_cbranch_vccz .LBB0_689
	s_barrier

.LBB0_758:
	ds_read_b128 v[140:143], v183
	ds_read_b128 v[144:147], v183 offset:1024
	ds_read_b128 v[148:151], v183 offset:2048
	ds_read_b128 v[152:155], v183 offset:3072
	ds_read_b128 v[156:159], v184
	ds_read_b128 v[160:163], v184 offset:1024
	ds_read_b128 v[164:167], v184 offset:2048
	ds_read_b128 v[186:189], v184 offset:3072
	s_add_u32 s36, s34, 0xfffc0080
	s_addc_u32 s37, s35, -1
	s_cmp_eq_u32 s60, 12
	s_cselect_b32 s39, s25, s37
	s_cselect_b32 s38, s54, s36
	s_cselect_b32 s37, s23, s57
	s_cselect_b32 s36, s55, s56
	v_lshl_add_u64 v[222:223], s[34:35], 0, v[132:133]
	s_add_i32 m0, s31, 0xc000
	ds_read_b128 v[190:193], v185
	ds_read_b128 v[194:197], v185 offset:1024
	ds_read_b128 v[198:201], v185 offset:2048
	ds_read_b128 v[202:205], v185 offset:3072
	ds_read_b128 v[206:209], v185 offset:4096
	ds_read_b128 v[210:213], v185 offset:5120
	ds_read_b128 v[214:217], v185 offset:6144
	ds_read_b128 v[218:221], v185 offset:7168
	global_load_lds_dwordx4 v[222:223], off
	v_lshl_add_u64 v[222:223], s[34:35], 0, v[134:135]
	s_add_i32 m0, s31, 0xe000
	s_nop 0
	global_load_lds_dwordx4 v[222:223], off
	s_waitcnt vmcnt(8)
	s_waitcnt lgkmcnt(0)
	s_barrier
	v_mfma_f32_16x16x32_bf16 v[124:127], v[140:143], v[190:193], v[124:127]
	v_mfma_f32_16x16x32_bf16 v[120:123], v[148:151], v[190:193], v[120:123]
	v_mfma_f32_16x16x32_bf16 v[108:111], v[140:143], v[198:201], v[108:111]
	v_mfma_f32_16x16x32_bf16 v[104:107], v[148:151], v[198:201], v[104:107]
	v_mfma_f32_16x16x32_bf16 v[92:95], v[140:143], v[206:209], v[92:95]
	v_mfma_f32_16x16x32_bf16 v[88:91], v[148:151], v[206:209], v[88:91]
	v_mfma_f32_16x16x32_bf16 v[76:79], v[140:143], v[214:217], v[76:79]
	v_mfma_f32_16x16x32_bf16 v[72:75], v[148:151], v[214:217], v[72:75]
	v_mfma_f32_16x16x32_bf16 v[124:127], v[144:147], v[194:197], v[124:127]
	v_mfma_f32_16x16x32_bf16 v[120:123], v[152:155], v[194:197], v[120:123]
	v_mfma_f32_16x16x32_bf16 v[108:111], v[144:147], v[202:205], v[108:111]
	v_mfma_f32_16x16x32_bf16 v[104:107], v[152:155], v[202:205], v[104:107]
	v_mfma_f32_16x16x32_bf16 v[92:95], v[144:147], v[210:213], v[92:95]
	v_mfma_f32_16x16x32_bf16 v[88:91], v[152:155], v[210:213], v[88:91]
	v_mfma_f32_16x16x32_bf16 v[76:79], v[144:147], v[218:221], v[76:79]
	v_mfma_f32_16x16x32_bf16 v[72:75], v[152:155], v[218:221], v[72:75]
	v_mfma_f32_16x16x32_bf16 v[116:119], v[156:159], v[190:193], v[116:119]
	v_mfma_f32_16x16x32_bf16 v[112:115], v[164:167], v[190:193], v[112:115]
	v_mfma_f32_16x16x32_bf16 v[100:103], v[156:159], v[198:201], v[100:103]
	v_mfma_f32_16x16x32_bf16 v[96:99], v[164:167], v[198:201], v[96:99]
	v_mfma_f32_16x16x32_bf16 v[84:87], v[156:159], v[206:209], v[84:87]
	v_mfma_f32_16x16x32_bf16 v[80:83], v[164:167], v[206:209], v[80:83]
	v_mfma_f32_16x16x32_bf16 v[68:71], v[156:159], v[214:217], v[68:71]
	v_mfma_f32_16x16x32_bf16 v[64:67], v[164:167], v[214:217], v[64:67]
	v_mfma_f32_16x16x32_bf16 v[116:119], v[160:163], v[194:197], v[116:119]
	v_mfma_f32_16x16x32_bf16 v[112:115], v[186:189], v[194:197], v[112:115]
	v_mfma_f32_16x16x32_bf16 v[100:103], v[160:163], v[202:205], v[100:103]
	v_mfma_f32_16x16x32_bf16 v[96:99], v[186:189], v[202:205], v[96:99]
	v_mfma_f32_16x16x32_bf16 v[84:87], v[160:163], v[210:213], v[84:87]
	v_mfma_f32_16x16x32_bf16 v[80:83], v[186:189], v[210:213], v[80:83]
	v_mfma_f32_16x16x32_bf16 v[68:71], v[160:163], v[218:221], v[68:71]
	v_mfma_f32_16x16x32_bf16 v[64:67], v[186:189], v[218:221], v[64:67]
	s_barrier
	s_add_i32 s61, s51, s42
	v_lshl_add_u64 v[222:223], s[36:37], 0, v[128:129]
	s_mov_b32 m0, s61
	ds_read_b128 v[190:193], v185 offset:16384
	ds_read_b128 v[194:197], v185 offset:17408
	ds_read_b128 v[198:201], v185 offset:18432
	ds_read_b128 v[202:205], v185 offset:19456
	ds_read_b128 v[206:209], v185 offset:20480
	ds_read_b128 v[210:213], v185 offset:21504
	ds_read_b128 v[214:217], v185 offset:22528
	ds_read_b128 v[218:221], v185 offset:23552
	global_load_lds_dwordx4 v[222:223], off
	s_add_i32 m0, s61, 0x2000
	s_add_u32 s62, s36, 0x40000
	v_lshl_add_u64 v[224:225], s[36:37], 0, v[130:131]
	s_addc_u32 s63, s37, 0
	s_add_i32 s61, s52, s42
	global_load_lds_dwordx4 v[224:225], off
	v_lshl_add_u64 v[226:227], s[62:63], 0, v[128:129]
	s_mov_b32 m0, s61
	v_lshl_add_u64 v[228:229], s[38:39], 0, v[130:131]
	global_load_lds_dwordx4 v[226:227], off
	v_lshl_add_u64 v[226:227], s[62:63], 0, v[130:131]
	s_add_i32 m0, s61, 0x2000
	s_nop 0
	global_load_lds_dwordx4 v[226:227], off
	v_lshl_add_u64 v[226:227], s[38:39], 0, v[128:129]
	s_mov_b32 m0, s31
	s_nop 0
	global_load_lds_dwordx4 v[226:227], off
	s_mov_b32 m0, s43
	s_nop 0
	global_load_lds_dwordx4 v[228:229], off
	s_waitcnt vmcnt(8)
	s_waitcnt lgkmcnt(0)
	s_barrier
	v_mfma_f32_16x16x32_bf16 v[60:63], v[140:143], v[190:193], v[60:63]
	v_mfma_f32_16x16x32_bf16 v[56:59], v[148:151], v[190:193], v[56:59]
	v_mfma_f32_16x16x32_bf16 v[44:47], v[140:143], v[198:201], v[44:47]
	v_mfma_f32_16x16x32_bf16 v[40:43], v[148:151], v[198:201], v[40:43]
	v_mfma_f32_16x16x32_bf16 v[28:31], v[140:143], v[206:209], v[28:31]
	v_mfma_f32_16x16x32_bf16 v[24:27], v[148:151], v[206:209], v[24:27]
	v_mfma_f32_16x16x32_bf16 v[12:15], v[140:143], v[214:217], v[12:15]
	v_mfma_f32_16x16x32_bf16 v[8:11], v[148:151], v[214:217], v[8:11]
	v_mfma_f32_16x16x32_bf16 v[60:63], v[144:147], v[194:197], v[60:63]
	v_mfma_f32_16x16x32_bf16 v[56:59], v[152:155], v[194:197], v[56:59]
	v_mfma_f32_16x16x32_bf16 v[44:47], v[144:147], v[202:205], v[44:47]
	v_mfma_f32_16x16x32_bf16 v[40:43], v[152:155], v[202:205], v[40:43]
	v_mfma_f32_16x16x32_bf16 v[28:31], v[144:147], v[210:213], v[28:31]
	v_mfma_f32_16x16x32_bf16 v[24:27], v[152:155], v[210:213], v[24:27]
	v_mfma_f32_16x16x32_bf16 v[12:15], v[144:147], v[218:221], v[12:15]
	v_mfma_f32_16x16x32_bf16 v[8:11], v[152:155], v[218:221], v[8:11]
	v_mfma_f32_16x16x32_bf16 v[52:55], v[156:159], v[190:193], v[52:55]
	v_mfma_f32_16x16x32_bf16 v[48:51], v[164:167], v[190:193], v[48:51]
	v_mfma_f32_16x16x32_bf16 v[36:39], v[156:159], v[198:201], v[36:39]
	v_mfma_f32_16x16x32_bf16 v[32:35], v[164:167], v[198:201], v[32:35]
	v_mfma_f32_16x16x32_bf16 v[20:23], v[156:159], v[206:209], v[20:23]
	v_mfma_f32_16x16x32_bf16 v[16:19], v[164:167], v[206:209], v[16:19]
	v_mfma_f32_16x16x32_bf16 v[4:7], v[156:159], v[214:217], v[4:7]
	v_mfma_f32_16x16x32_bf16 v[0:3], v[164:167], v[214:217], v[0:3]
	v_mfma_f32_16x16x32_bf16 v[52:55], v[160:163], v[194:197], v[52:55]
	v_mfma_f32_16x16x32_bf16 v[48:51], v[186:189], v[194:197], v[48:51]
	v_mfma_f32_16x16x32_bf16 v[36:39], v[160:163], v[202:205], v[36:39]
	v_mfma_f32_16x16x32_bf16 v[32:35], v[186:189], v[202:205], v[32:35]
	v_mfma_f32_16x16x32_bf16 v[20:23], v[160:163], v[210:213], v[20:23]
	v_mfma_f32_16x16x32_bf16 v[16:19], v[186:189], v[210:213], v[16:19]
	v_mfma_f32_16x16x32_bf16 v[4:7], v[160:163], v[218:221], v[4:7]
	v_mfma_f32_16x16x32_bf16 v[0:3], v[186:189], v[218:221], v[0:3]
	s_barrier
	s_add_i32 s61, 0, 0x18000
	s_add_i32 s62, 0, 0x1c000
	v_add_u32_e32 v152, s61, v181
	v_add_u32_e32 v186, s62, v181
	ds_read_b128 v[140:143], v152
	ds_read_b128 v[144:147], v152 offset:1024
	ds_read_b128 v[148:151], v152 offset:2048
	ds_read_b128 v[152:155], v152 offset:3072
	ds_read_b128 v[156:159], v186
	ds_read_b128 v[160:163], v186 offset:1024
	ds_read_b128 v[164:167], v186 offset:2048
	ds_read_b128 v[186:189], v186 offset:3072
	s_add_u32 s38, s38, 0x40000
	s_addc_u32 s39, s39, 0
	s_mov_b32 m0, s44
	v_lshl_add_u64 v[230:231], s[38:39], 0, v[128:129]
	ds_read_b128 v[190:193], v185 offset:32768
	ds_read_b128 v[194:197], v185 offset:33792
	ds_read_b128 v[198:201], v185 offset:34816
	ds_read_b128 v[202:205], v185 offset:35840
	ds_read_b128 v[206:209], v185 offset:36864
	ds_read_b128 v[210:213], v185 offset:37888
	ds_read_b128 v[214:217], v185 offset:38912
	ds_read_b128 v[218:221], v185 offset:39936
	global_load_lds_dwordx4 v[230:231], off
	v_lshl_add_u64 v[230:231], s[38:39], 0, v[130:131]
	s_mov_b32 m0, s45
	s_nop 0
	global_load_lds_dwordx4 v[230:231], off
	s_waitcnt vmcnt(8)
	s_waitcnt lgkmcnt(0)
	s_barrier
	v_mfma_f32_16x16x32_bf16 v[124:127], v[140:143], v[190:193], v[124:127]
	v_mfma_f32_16x16x32_bf16 v[120:123], v[148:151], v[190:193], v[120:123]
	v_mfma_f32_16x16x32_bf16 v[108:111], v[140:143], v[198:201], v[108:111]
	v_mfma_f32_16x16x32_bf16 v[104:107], v[148:151], v[198:201], v[104:107]
	v_mfma_f32_16x16x32_bf16 v[92:95], v[140:143], v[206:209], v[92:95]
	v_mfma_f32_16x16x32_bf16 v[88:91], v[148:151], v[206:209], v[88:91]
	v_mfma_f32_16x16x32_bf16 v[76:79], v[140:143], v[214:217], v[76:79]
	v_mfma_f32_16x16x32_bf16 v[72:75], v[148:151], v[214:217], v[72:75]
	v_mfma_f32_16x16x32_bf16 v[124:127], v[144:147], v[194:197], v[124:127]
	v_mfma_f32_16x16x32_bf16 v[120:123], v[152:155], v[194:197], v[120:123]
	v_mfma_f32_16x16x32_bf16 v[108:111], v[144:147], v[202:205], v[108:111]
	v_mfma_f32_16x16x32_bf16 v[104:107], v[152:155], v[202:205], v[104:107]
	v_mfma_f32_16x16x32_bf16 v[92:95], v[144:147], v[210:213], v[92:95]
	v_mfma_f32_16x16x32_bf16 v[88:91], v[152:155], v[210:213], v[88:91]
	v_mfma_f32_16x16x32_bf16 v[76:79], v[144:147], v[218:221], v[76:79]
	v_mfma_f32_16x16x32_bf16 v[72:75], v[152:155], v[218:221], v[72:75]
	v_mfma_f32_16x16x32_bf16 v[116:119], v[156:159], v[190:193], v[116:119]
	v_mfma_f32_16x16x32_bf16 v[112:115], v[164:167], v[190:193], v[112:115]
	v_mfma_f32_16x16x32_bf16 v[100:103], v[156:159], v[198:201], v[100:103]
	v_mfma_f32_16x16x32_bf16 v[96:99], v[164:167], v[198:201], v[96:99]
	v_mfma_f32_16x16x32_bf16 v[84:87], v[156:159], v[206:209], v[84:87]
	v_mfma_f32_16x16x32_bf16 v[80:83], v[164:167], v[206:209], v[80:83]
	v_mfma_f32_16x16x32_bf16 v[68:71], v[156:159], v[214:217], v[68:71]
	v_mfma_f32_16x16x32_bf16 v[64:67], v[164:167], v[214:217], v[64:67]
	v_mfma_f32_16x16x32_bf16 v[116:119], v[160:163], v[194:197], v[116:119]
	v_mfma_f32_16x16x32_bf16 v[112:115], v[186:189], v[194:197], v[112:115]
	v_mfma_f32_16x16x32_bf16 v[100:103], v[160:163], v[202:205], v[100:103]
	v_mfma_f32_16x16x32_bf16 v[96:99], v[186:189], v[202:205], v[96:99]
	v_mfma_f32_16x16x32_bf16 v[84:87], v[160:163], v[210:213], v[84:87]
	v_mfma_f32_16x16x32_bf16 v[80:83], v[186:189], v[210:213], v[80:83]
	v_mfma_f32_16x16x32_bf16 v[68:71], v[160:163], v[218:221], v[68:71]
	v_mfma_f32_16x16x32_bf16 v[64:67], v[186:189], v[218:221], v[64:67]
	s_barrier
	s_add_i32 s38, s61, s42
	v_lshl_add_u64 v[222:223], v[222:223], 0, s[12:13]
	s_mov_b32 m0, s38
	ds_read_b128 v[190:193], v185 offset:49152
	ds_read_b128 v[194:197], v185 offset:50176
	ds_read_b128 v[198:201], v185 offset:51200
	ds_read_b128 v[202:205], v185 offset:52224
	ds_read_b128 v[206:209], v185 offset:53248
	ds_read_b128 v[210:213], v185 offset:54272
	ds_read_b128 v[214:217], v185 offset:55296
	ds_read_b128 v[218:221], v185 offset:56320
	global_load_lds_dwordx4 v[222:223], off
	s_add_i32 m0, s38, 0x2000
	s_add_u32 s36, s36, 0x40080
	v_lshl_add_u64 v[222:223], v[224:225], 0, s[12:13]
	s_addc_u32 s37, s37, 0
	s_add_i32 s38, s62, s42
	global_load_lds_dwordx4 v[222:223], off
	v_lshl_add_u64 v[222:223], s[36:37], 0, v[128:129]
	s_mov_b32 m0, s38
	s_nop 0
	global_load_lds_dwordx4 v[222:223], off
	v_lshl_add_u64 v[222:223], s[36:37], 0, v[130:131]
	s_add_i32 m0, s38, 0x2000
	s_nop 0
	global_load_lds_dwordx4 v[222:223], off
	v_lshl_add_u64 v[222:223], v[226:227], 0, s[12:13]
	s_mov_b32 m0, s48
	s_nop 0
	global_load_lds_dwordx4 v[222:223], off
	v_lshl_add_u64 v[222:223], v[228:229], 0, s[12:13]
	s_mov_b32 m0, s49
	s_nop 0
	global_load_lds_dwordx4 v[222:223], off
	s_waitcnt vmcnt(8)
	s_waitcnt lgkmcnt(0)
	s_barrier
	v_mfma_f32_16x16x32_bf16 v[60:63], v[140:143], v[190:193], v[60:63]
	v_mfma_f32_16x16x32_bf16 v[56:59], v[148:151], v[190:193], v[56:59]
	v_mfma_f32_16x16x32_bf16 v[44:47], v[140:143], v[198:201], v[44:47]
	v_mfma_f32_16x16x32_bf16 v[40:43], v[148:151], v[198:201], v[40:43]
	v_mfma_f32_16x16x32_bf16 v[28:31], v[140:143], v[206:209], v[28:31]
	v_mfma_f32_16x16x32_bf16 v[24:27], v[148:151], v[206:209], v[24:27]
	v_mfma_f32_16x16x32_bf16 v[12:15], v[140:143], v[214:217], v[12:15]
	v_mfma_f32_16x16x32_bf16 v[8:11], v[148:151], v[214:217], v[8:11]
	v_mfma_f32_16x16x32_bf16 v[60:63], v[144:147], v[194:197], v[60:63]
	v_mfma_f32_16x16x32_bf16 v[56:59], v[152:155], v[194:197], v[56:59]
	v_mfma_f32_16x16x32_bf16 v[44:47], v[144:147], v[202:205], v[44:47]
	v_mfma_f32_16x16x32_bf16 v[40:43], v[152:155], v[202:205], v[40:43]
	v_mfma_f32_16x16x32_bf16 v[28:31], v[144:147], v[210:213], v[28:31]
	v_mfma_f32_16x16x32_bf16 v[24:27], v[152:155], v[210:213], v[24:27]
	v_mfma_f32_16x16x32_bf16 v[12:15], v[144:147], v[218:221], v[12:15]
	v_mfma_f32_16x16x32_bf16 v[8:11], v[152:155], v[218:221], v[8:11]
	v_mfma_f32_16x16x32_bf16 v[52:55], v[156:159], v[190:193], v[52:55]
	v_mfma_f32_16x16x32_bf16 v[48:51], v[164:167], v[190:193], v[48:51]
	v_mfma_f32_16x16x32_bf16 v[36:39], v[156:159], v[198:201], v[36:39]
	v_mfma_f32_16x16x32_bf16 v[32:35], v[164:167], v[198:201], v[32:35]
	v_mfma_f32_16x16x32_bf16 v[20:23], v[156:159], v[206:209], v[20:23]
	v_mfma_f32_16x16x32_bf16 v[16:19], v[164:167], v[206:209], v[16:19]
	v_mfma_f32_16x16x32_bf16 v[4:7], v[156:159], v[214:217], v[4:7]
	v_mfma_f32_16x16x32_bf16 v[0:3], v[164:167], v[214:217], v[0:3]
	v_mfma_f32_16x16x32_bf16 v[52:55], v[160:163], v[194:197], v[52:55]
	v_mfma_f32_16x16x32_bf16 v[48:51], v[186:189], v[194:197], v[48:51]
	v_mfma_f32_16x16x32_bf16 v[36:39], v[160:163], v[202:205], v[36:39]
	v_mfma_f32_16x16x32_bf16 v[32:35], v[186:189], v[202:205], v[32:35]
	v_mfma_f32_16x16x32_bf16 v[20:23], v[160:163], v[210:213], v[20:23]
	v_mfma_f32_16x16x32_bf16 v[16:19], v[186:189], v[210:213], v[16:19]
	v_mfma_f32_16x16x32_bf16 v[4:7], v[160:163], v[218:221], v[4:7]
	v_mfma_f32_16x16x32_bf16 v[0:3], v[186:189], v[218:221], v[0:3]
	s_barrier
	s_add_i32 s60, s60, 2
	s_add_u32 s34, s34, 0x100
	s_addc_u32 s35, s35, 0
	s_add_u32 s56, s56, 0x100
	s_addc_u32 s57, s57, 0
	s_cmp_gt_u32 s60, 13
	s_cbranch_scc0 .LBB0_758
	s_and_b64 vcc, exec, s[14:15]
	s_cbranch_vccz .LBB0_761
	s_barrier

.LBB0_778:
	v_add_u32_e32 v147, s43, v145
	ds_read_b128 v[148:151], v147
	ds_read_b128 v[152:155], v147 offset:1024
	ds_read_b128 v[156:159], v147 offset:2048
	ds_read_b128 v[160:163], v147 offset:3072
	v_add_u32_e32 v147, s44, v145
	s_add_u32 s26, s12, s24
	ds_read_b128 v[164:167], v147
	ds_read_b128 v[180:183], v147 offset:1024
	ds_read_b128 v[184:187], v147 offset:2048
	ds_read_b128 v[188:191], v147 offset:3072
	s_addc_u32 s27, s13, s25
	s_add_u32 s26, s26, 0x100
	s_addc_u32 s27, s27, 0
	s_add_u32 s51, s46, s24
	s_addc_u32 s52, s47, s25
	s_cmpk_eq_i32 s24, 0x700
	s_cselect_b32 s29, s19, s27
	s_cselect_b32 s28, s48, s26
	s_cselect_b32 s27, s17, s52
	s_cselect_b32 s26, s49, s51
	v_lshl_add_u64 v[168:169], v[140:141], 0, s[24:25]
	s_add_i32 m0, s11, 0xc000
	ds_read_b128 v[192:195], v146
	ds_read_b128 v[196:199], v146 offset:1024
	ds_read_b128 v[200:203], v146 offset:2048
	ds_read_b128 v[204:207], v146 offset:3072
	ds_read_b128 v[208:211], v146 offset:4096
	ds_read_b128 v[212:215], v146 offset:5120
	ds_read_b128 v[216:219], v146 offset:6144
	ds_read_b128 v[220:223], v146 offset:7168
	global_load_lds_dwordx4 v[168:169], off
	v_lshl_add_u64 v[168:169], v[142:143], 0, s[24:25]
	s_add_i32 m0, s11, 0xe000
	s_nop 0
	global_load_lds_dwordx4 v[168:169], off
	s_waitcnt vmcnt(8)
	s_waitcnt lgkmcnt(0)
	s_barrier
	v_mfma_f32_16x16x32_bf16 v[100:103], v[148:151], v[192:195], v[100:103]
	v_mfma_f32_16x16x32_bf16 v[96:99], v[156:159], v[192:195], v[96:99]
	v_mfma_f32_16x16x32_bf16 v[108:111], v[148:151], v[200:203], v[108:111]
	v_mfma_f32_16x16x32_bf16 v[84:87], v[156:159], v[200:203], v[84:87]
	v_mfma_f32_16x16x32_bf16 v[116:119], v[148:151], v[208:211], v[116:119]
	v_mfma_f32_16x16x32_bf16 v[112:115], v[156:159], v[208:211], v[112:115]
	v_mfma_f32_16x16x32_bf16 v[124:127], v[148:151], v[216:219], v[124:127]
	v_mfma_f32_16x16x32_bf16 v[120:123], v[156:159], v[216:219], v[120:123]
	v_mfma_f32_16x16x32_bf16 v[100:103], v[152:155], v[196:199], v[100:103]
	v_mfma_f32_16x16x32_bf16 v[96:99], v[160:163], v[196:199], v[96:99]
	v_mfma_f32_16x16x32_bf16 v[108:111], v[152:155], v[204:207], v[108:111]
	v_mfma_f32_16x16x32_bf16 v[84:87], v[160:163], v[204:207], v[84:87]
	v_mfma_f32_16x16x32_bf16 v[116:119], v[152:155], v[212:215], v[116:119]
	v_mfma_f32_16x16x32_bf16 v[112:115], v[160:163], v[212:215], v[112:115]
	v_mfma_f32_16x16x32_bf16 v[124:127], v[152:155], v[220:223], v[124:127]
	v_mfma_f32_16x16x32_bf16 v[120:123], v[160:163], v[220:223], v[120:123]
	v_mfma_f32_16x16x32_bf16 v[76:79], v[164:167], v[192:195], v[76:79]
	v_mfma_f32_16x16x32_bf16 v[68:71], v[184:187], v[192:195], v[68:71]
	v_mfma_f32_16x16x32_bf16 v[72:75], v[164:167], v[200:203], v[72:75]
	v_mfma_f32_16x16x32_bf16 v[64:67], v[184:187], v[200:203], v[64:67]
	v_mfma_f32_16x16x32_bf16 v[88:91], v[164:167], v[208:211], v[88:91]
	v_mfma_f32_16x16x32_bf16 v[80:83], v[184:187], v[208:211], v[80:83]
	v_mfma_f32_16x16x32_bf16 v[104:107], v[164:167], v[216:219], v[104:107]
	v_mfma_f32_16x16x32_bf16 v[92:95], v[184:187], v[216:219], v[92:95]
	v_mfma_f32_16x16x32_bf16 v[76:79], v[180:183], v[196:199], v[76:79]
	v_mfma_f32_16x16x32_bf16 v[68:71], v[188:191], v[196:199], v[68:71]
	v_mfma_f32_16x16x32_bf16 v[72:75], v[180:183], v[204:207], v[72:75]
	v_mfma_f32_16x16x32_bf16 v[64:67], v[188:191], v[204:207], v[64:67]
	v_mfma_f32_16x16x32_bf16 v[88:91], v[180:183], v[212:215], v[88:91]
	v_mfma_f32_16x16x32_bf16 v[80:83], v[188:191], v[212:215], v[80:83]
	v_mfma_f32_16x16x32_bf16 v[104:107], v[180:183], v[220:223], v[104:107]
	v_mfma_f32_16x16x32_bf16 v[92:95], v[188:191], v[220:223], v[92:95]
	s_barrier
	s_add_i32 s51, s43, s35
	v_lshl_add_u64 v[168:169], s[26:27], 0, v[128:129]
	s_mov_b32 m0, s51
	ds_read_b128 v[192:195], v146 offset:16384
	ds_read_b128 v[196:199], v146 offset:17408
	ds_read_b128 v[200:203], v146 offset:18432
	ds_read_b128 v[204:207], v146 offset:19456
	ds_read_b128 v[208:211], v146 offset:20480
	ds_read_b128 v[212:215], v146 offset:21504
	ds_read_b128 v[216:219], v146 offset:22528
	ds_read_b128 v[220:223], v146 offset:23552
	global_load_lds_dwordx4 v[168:169], off
	s_add_i32 m0, s51, 0x2000
	s_add_u32 s52, s26, 0x40000
	v_lshl_add_u64 v[224:225], s[26:27], 0, v[130:131]
	s_addc_u32 s53, s27, 0
	s_add_i32 s51, s44, s35
	global_load_lds_dwordx4 v[224:225], off
	v_lshl_add_u64 v[226:227], s[52:53], 0, v[128:129]
	s_mov_b32 m0, s51
	v_lshl_add_u64 v[228:229], s[28:29], 0, v[130:131]
	global_load_lds_dwordx4 v[226:227], off
	v_lshl_add_u64 v[226:227], s[52:53], 0, v[130:131]
	s_add_i32 m0, s51, 0x2000
	s_nop 0
	global_load_lds_dwordx4 v[226:227], off
	v_lshl_add_u64 v[226:227], s[28:29], 0, v[128:129]
	s_mov_b32 m0, s11
	s_nop 0
	global_load_lds_dwordx4 v[226:227], off
	s_mov_b32 m0, s36
	s_nop 0
	global_load_lds_dwordx4 v[228:229], off
	s_waitcnt vmcnt(8)
	s_waitcnt lgkmcnt(0)
	s_barrier
	v_mfma_f32_16x16x32_bf16 v[60:63], v[148:151], v[192:195], v[60:63]
	v_mfma_f32_16x16x32_bf16 v[56:59], v[156:159], v[192:195], v[56:59]
	v_mfma_f32_16x16x32_bf16 v[44:47], v[148:151], v[200:203], v[44:47]
	v_mfma_f32_16x16x32_bf16 v[40:43], v[156:159], v[200:203], v[40:43]
	v_mfma_f32_16x16x32_bf16 v[28:31], v[148:151], v[208:211], v[28:31]
	v_mfma_f32_16x16x32_bf16 v[24:27], v[156:159], v[208:211], v[24:27]
	v_mfma_f32_16x16x32_bf16 v[12:15], v[148:151], v[216:219], v[12:15]
	v_mfma_f32_16x16x32_bf16 v[8:11], v[156:159], v[216:219], v[8:11]
	v_mfma_f32_16x16x32_bf16 v[60:63], v[152:155], v[196:199], v[60:63]
	v_mfma_f32_16x16x32_bf16 v[56:59], v[160:163], v[196:199], v[56:59]
	v_mfma_f32_16x16x32_bf16 v[44:47], v[152:155], v[204:207], v[44:47]
	v_mfma_f32_16x16x32_bf16 v[40:43], v[160:163], v[204:207], v[40:43]
	v_mfma_f32_16x16x32_bf16 v[28:31], v[152:155], v[212:215], v[28:31]
	v_mfma_f32_16x16x32_bf16 v[24:27], v[160:163], v[212:215], v[24:27]
	v_mfma_f32_16x16x32_bf16 v[12:15], v[152:155], v[220:223], v[12:15]
	v_mfma_f32_16x16x32_bf16 v[8:11], v[160:163], v[220:223], v[8:11]
	v_mfma_f32_16x16x32_bf16 v[52:55], v[164:167], v[192:195], v[52:55]
	v_mfma_f32_16x16x32_bf16 v[48:51], v[184:187], v[192:195], v[48:51]
	v_mfma_f32_16x16x32_bf16 v[36:39], v[164:167], v[200:203], v[36:39]
	v_mfma_f32_16x16x32_bf16 v[32:35], v[184:187], v[200:203], v[32:35]
	v_mfma_f32_16x16x32_bf16 v[20:23], v[164:167], v[208:211], v[20:23]
	v_mfma_f32_16x16x32_bf16 v[16:19], v[184:187], v[208:211], v[16:19]
	v_mfma_f32_16x16x32_bf16 v[4:7], v[164:167], v[216:219], v[4:7]
	v_mfma_f32_16x16x32_bf16 v[0:3], v[184:187], v[216:219], v[0:3]
	v_mfma_f32_16x16x32_bf16 v[52:55], v[180:183], v[196:199], v[52:55]
	v_mfma_f32_16x16x32_bf16 v[48:51], v[188:191], v[196:199], v[48:51]
	v_mfma_f32_16x16x32_bf16 v[36:39], v[180:183], v[204:207], v[36:39]
	v_mfma_f32_16x16x32_bf16 v[32:35], v[188:191], v[204:207], v[32:35]
	v_mfma_f32_16x16x32_bf16 v[20:23], v[180:183], v[212:215], v[20:23]
	v_mfma_f32_16x16x32_bf16 v[16:19], v[188:191], v[212:215], v[16:19]
	v_mfma_f32_16x16x32_bf16 v[4:7], v[180:183], v[220:223], v[4:7]
	v_mfma_f32_16x16x32_bf16 v[0:3], v[188:191], v[220:223], v[0:3]
	s_barrier
	s_add_i32 s51, 0, 0x18000
	v_add_u32_e32 v147, s51, v145
	s_add_i32 s52, 0, 0x1c000
	ds_read_b128 v[148:151], v147
	ds_read_b128 v[152:155], v147 offset:1024
	ds_read_b128 v[156:159], v147 offset:2048
	ds_read_b128 v[160:163], v147 offset:3072
	v_add_u32_e32 v147, s52, v145
	ds_read_b128 v[164:167], v147
	ds_read_b128 v[180:183], v147 offset:1024
	ds_read_b128 v[184:187], v147 offset:2048
	ds_read_b128 v[188:191], v147 offset:3072
	s_add_u32 s28, s28, 0x40000
	s_addc_u32 s29, s29, 0
	s_mov_b32 m0, s37
	v_lshl_add_u64 v[230:231], s[28:29], 0, v[128:129]
	ds_read_b128 v[192:195], v146 offset:32768
	ds_read_b128 v[196:199], v146 offset:33792
	ds_read_b128 v[200:203], v146 offset:34816
	ds_read_b128 v[204:207], v146 offset:35840
	ds_read_b128 v[208:211], v146 offset:36864
	ds_read_b128 v[212:215], v146 offset:37888
	ds_read_b128 v[216:219], v146 offset:38912
	ds_read_b128 v[220:223], v146 offset:39936
	global_load_lds_dwordx4 v[230:231], off
	v_lshl_add_u64 v[230:231], s[28:29], 0, v[130:131]
	s_mov_b32 m0, s38
	s_nop 0
	global_load_lds_dwordx4 v[230:231], off
	s_waitcnt vmcnt(8)
	s_waitcnt lgkmcnt(0)
	s_barrier
	v_mfma_f32_16x16x32_bf16 v[100:103], v[148:151], v[192:195], v[100:103]
	v_mfma_f32_16x16x32_bf16 v[96:99], v[156:159], v[192:195], v[96:99]
	v_mfma_f32_16x16x32_bf16 v[108:111], v[148:151], v[200:203], v[108:111]
	v_mfma_f32_16x16x32_bf16 v[84:87], v[156:159], v[200:203], v[84:87]
	v_mfma_f32_16x16x32_bf16 v[116:119], v[148:151], v[208:211], v[116:119]
	v_mfma_f32_16x16x32_bf16 v[112:115], v[156:159], v[208:211], v[112:115]
	v_mfma_f32_16x16x32_bf16 v[124:127], v[148:151], v[216:219], v[124:127]
	v_mfma_f32_16x16x32_bf16 v[120:123], v[156:159], v[216:219], v[120:123]
	v_mfma_f32_16x16x32_bf16 v[100:103], v[152:155], v[196:199], v[100:103]
	v_mfma_f32_16x16x32_bf16 v[96:99], v[160:163], v[196:199], v[96:99]
	v_mfma_f32_16x16x32_bf16 v[108:111], v[152:155], v[204:207], v[108:111]
	v_mfma_f32_16x16x32_bf16 v[84:87], v[160:163], v[204:207], v[84:87]
	v_mfma_f32_16x16x32_bf16 v[116:119], v[152:155], v[212:215], v[116:119]
	v_mfma_f32_16x16x32_bf16 v[112:115], v[160:163], v[212:215], v[112:115]
	v_mfma_f32_16x16x32_bf16 v[124:127], v[152:155], v[220:223], v[124:127]
	v_mfma_f32_16x16x32_bf16 v[120:123], v[160:163], v[220:223], v[120:123]
	v_mfma_f32_16x16x32_bf16 v[76:79], v[164:167], v[192:195], v[76:79]
	v_mfma_f32_16x16x32_bf16 v[68:71], v[184:187], v[192:195], v[68:71]
	v_mfma_f32_16x16x32_bf16 v[72:75], v[164:167], v[200:203], v[72:75]
	v_mfma_f32_16x16x32_bf16 v[64:67], v[184:187], v[200:203], v[64:67]
	v_mfma_f32_16x16x32_bf16 v[88:91], v[164:167], v[208:211], v[88:91]
	v_mfma_f32_16x16x32_bf16 v[80:83], v[184:187], v[208:211], v[80:83]
	v_mfma_f32_16x16x32_bf16 v[104:107], v[164:167], v[216:219], v[104:107]
	v_mfma_f32_16x16x32_bf16 v[92:95], v[184:187], v[216:219], v[92:95]
	v_mfma_f32_16x16x32_bf16 v[76:79], v[180:183], v[196:199], v[76:79]
	v_mfma_f32_16x16x32_bf16 v[68:71], v[188:191], v[196:199], v[68:71]
	v_mfma_f32_16x16x32_bf16 v[72:75], v[180:183], v[204:207], v[72:75]
	v_mfma_f32_16x16x32_bf16 v[64:67], v[188:191], v[204:207], v[64:67]
	v_mfma_f32_16x16x32_bf16 v[88:91], v[180:183], v[212:215], v[88:91]
	v_mfma_f32_16x16x32_bf16 v[80:83], v[188:191], v[212:215], v[80:83]
	v_mfma_f32_16x16x32_bf16 v[104:107], v[180:183], v[220:223], v[104:107]
	v_mfma_f32_16x16x32_bf16 v[92:95], v[188:191], v[220:223], v[92:95]
	s_barrier
	s_add_i32 s28, s51, s35
	v_lshl_add_u64 v[168:169], v[168:169], 0, s[14:15]
	s_mov_b32 m0, s28
	ds_read_b128 v[192:195], v146 offset:49152
	ds_read_b128 v[196:199], v146 offset:50176
	ds_read_b128 v[200:203], v146 offset:51200
	ds_read_b128 v[204:207], v146 offset:52224
	ds_read_b128 v[208:211], v146 offset:53248
	ds_read_b128 v[212:215], v146 offset:54272
	ds_read_b128 v[216:219], v146 offset:55296
	ds_read_b128 v[220:223], v146 offset:56320
	global_load_lds_dwordx4 v[168:169], off
	s_add_i32 m0, s28, 0x2000
	s_add_u32 s26, s26, 0x40080
	v_lshl_add_u64 v[168:169], v[224:225], 0, s[14:15]
	s_addc_u32 s27, s27, 0
	s_add_i32 s28, s52, s35
	global_load_lds_dwordx4 v[168:169], off
	v_lshl_add_u64 v[168:169], s[26:27], 0, v[128:129]
	s_mov_b32 m0, s28
	s_nop 0
	global_load_lds_dwordx4 v[168:169], off
	v_lshl_add_u64 v[168:169], s[26:27], 0, v[130:131]
	s_add_i32 m0, s28, 0x2000
	s_nop 0
	global_load_lds_dwordx4 v[168:169], off
	v_lshl_add_u64 v[168:169], v[226:227], 0, s[14:15]
	s_mov_b32 m0, s41
	s_nop 0
	global_load_lds_dwordx4 v[168:169], off
	v_lshl_add_u64 v[168:169], v[228:229], 0, s[14:15]
	s_mov_b32 m0, s42
	s_nop 0
	global_load_lds_dwordx4 v[168:169], off
	s_waitcnt vmcnt(8)
	s_waitcnt lgkmcnt(0)
	s_barrier
	v_mfma_f32_16x16x32_bf16 v[60:63], v[148:151], v[192:195], v[60:63]
	v_mfma_f32_16x16x32_bf16 v[56:59], v[156:159], v[192:195], v[56:59]
	v_mfma_f32_16x16x32_bf16 v[44:47], v[148:151], v[200:203], v[44:47]
	v_mfma_f32_16x16x32_bf16 v[40:43], v[156:159], v[200:203], v[40:43]
	v_mfma_f32_16x16x32_bf16 v[28:31], v[148:151], v[208:211], v[28:31]
	v_mfma_f32_16x16x32_bf16 v[24:27], v[156:159], v[208:211], v[24:27]
	v_mfma_f32_16x16x32_bf16 v[12:15], v[148:151], v[216:219], v[12:15]
	v_mfma_f32_16x16x32_bf16 v[8:11], v[156:159], v[216:219], v[8:11]
	v_mfma_f32_16x16x32_bf16 v[60:63], v[152:155], v[196:199], v[60:63]
	v_mfma_f32_16x16x32_bf16 v[56:59], v[160:163], v[196:199], v[56:59]
	v_mfma_f32_16x16x32_bf16 v[44:47], v[152:155], v[204:207], v[44:47]
	v_mfma_f32_16x16x32_bf16 v[40:43], v[160:163], v[204:207], v[40:43]
	v_mfma_f32_16x16x32_bf16 v[28:31], v[152:155], v[212:215], v[28:31]
	v_mfma_f32_16x16x32_bf16 v[24:27], v[160:163], v[212:215], v[24:27]
	v_mfma_f32_16x16x32_bf16 v[12:15], v[152:155], v[220:223], v[12:15]
	v_mfma_f32_16x16x32_bf16 v[8:11], v[160:163], v[220:223], v[8:11]
	v_mfma_f32_16x16x32_bf16 v[52:55], v[164:167], v[192:195], v[52:55]
	v_mfma_f32_16x16x32_bf16 v[48:51], v[184:187], v[192:195], v[48:51]
	v_mfma_f32_16x16x32_bf16 v[36:39], v[164:167], v[200:203], v[36:39]
	v_mfma_f32_16x16x32_bf16 v[32:35], v[184:187], v[200:203], v[32:35]
	v_mfma_f32_16x16x32_bf16 v[20:23], v[164:167], v[208:211], v[20:23]
	v_mfma_f32_16x16x32_bf16 v[16:19], v[184:187], v[208:211], v[16:19]
	v_mfma_f32_16x16x32_bf16 v[4:7], v[164:167], v[216:219], v[4:7]
	v_mfma_f32_16x16x32_bf16 v[0:3], v[184:187], v[216:219], v[0:3]
	v_mfma_f32_16x16x32_bf16 v[52:55], v[180:183], v[196:199], v[52:55]
	v_mfma_f32_16x16x32_bf16 v[48:51], v[188:191], v[196:199], v[48:51]
	v_mfma_f32_16x16x32_bf16 v[36:39], v[180:183], v[204:207], v[36:39]
	v_mfma_f32_16x16x32_bf16 v[32:35], v[188:191], v[204:207], v[32:35]
	v_mfma_f32_16x16x32_bf16 v[20:23], v[180:183], v[212:215], v[20:23]
	v_mfma_f32_16x16x32_bf16 v[16:19], v[188:191], v[212:215], v[16:19]
	v_mfma_f32_16x16x32_bf16 v[4:7], v[180:183], v[220:223], v[4:7]
	v_mfma_f32_16x16x32_bf16 v[0:3], v[188:191], v[220:223], v[0:3]
	s_barrier
	s_add_i32 s50, s50, 2
	s_add_u32 s24, s24, 0x100
	s_addc_u32 s25, s25, 0
	s_cmp_gt_u32 s50, 13
	s_cbranch_scc0 .LBB0_778
	s_add_u32 s24, s46, 0xffffff00
	s_addc_u32 s25, s47, -1
	s_andn2_b64 vcc, exec, s[2:3]
	s_cbranch_vccnz .LBB0_781
	v_mov_b64_e32 v[0:1], 0
	s_mov_b32 s4, s16
	s_mov_b32 s10, s18
	s_mov_b64 s[12:13], s[22:23]
	s_mov_b32 s40, s45
	v_mov_b64_e32 v[2:3], 0
	v_mov_b64_e32 v[4:5], 0
	v_mov_b64_e32 v[6:7], 0
	v_mov_b64_e32 v[16:17], 0
	v_mov_b64_e32 v[18:19], 0
	v_mov_b64_e32 v[20:21], 0
	v_mov_b64_e32 v[22:23], 0
	v_mov_b64_e32 v[32:33], 0
	v_mov_b64_e32 v[34:35], 0
	v_mov_b64_e32 v[36:37], 0
	v_mov_b64_e32 v[38:39], 0
	v_mov_b64_e32 v[48:49], 0
	v_mov_b64_e32 v[50:51], 0
	v_mov_b64_e32 v[52:53], 0
	v_mov_b64_e32 v[54:55], 0
	v_mov_b64_e32 v[8:9], 0
	v_mov_b64_e32 v[10:11], 0
	v_mov_b64_e32 v[12:13], 0
	v_mov_b64_e32 v[14:15], 0
	v_mov_b64_e32 v[24:25], 0
	v_mov_b64_e32 v[26:27], 0
	v_mov_b64_e32 v[28:29], 0
	v_mov_b64_e32 v[30:31], 0
	v_mov_b64_e32 v[40:41], 0
	v_mov_b64_e32 v[42:43], 0
	v_mov_b64_e32 v[44:45], 0
	v_mov_b64_e32 v[46:47], 0
	v_mov_b64_e32 v[56:57], 0
	v_mov_b64_e32 v[58:59], 0
	v_mov_b64_e32 v[60:61], 0
	v_mov_b64_e32 v[62:63], 0
	v_mov_b64_e32 v[92:93], 0
	v_mov_b64_e32 v[94:95], 0
	v_mov_b64_e32 v[104:105], 0
	v_mov_b64_e32 v[106:107], 0
	v_mov_b64_e32 v[80:81], 0
	v_mov_b64_e32 v[82:83], 0
	v_mov_b64_e32 v[88:89], 0
	v_mov_b64_e32 v[90:91], 0
	v_mov_b64_e32 v[64:65], 0
	v_mov_b64_e32 v[66:67], 0
	v_mov_b64_e32 v[72:73], 0
	v_mov_b64_e32 v[74:75], 0
	v_mov_b64_e32 v[68:69], 0
	v_mov_b64_e32 v[70:71], 0
	v_mov_b64_e32 v[76:77], 0
	v_mov_b64_e32 v[78:79], 0
	v_mov_b64_e32 v[120:121], 0
	v_mov_b64_e32 v[122:123], 0
	v_mov_b64_e32 v[124:125], 0
	v_mov_b64_e32 v[126:127], 0
	v_mov_b64_e32 v[112:113], 0
	v_mov_b64_e32 v[114:115], 0
	v_mov_b64_e32 v[116:117], 0
	v_mov_b64_e32 v[118:119], 0
	v_mov_b64_e32 v[84:85], 0
	v_mov_b64_e32 v[86:87], 0
	v_mov_b64_e32 v[108:109], 0
	v_mov_b64_e32 v[110:111], 0
	v_mov_b64_e32 v[96:97], 0
	v_mov_b64_e32 v[98:99], 0
	v_mov_b64_e32 v[100:101], 0
	v_mov_b64_e32 v[102:103], 0
	s_branch .LBB0_782

.LBB0_941:
	v_readlane_b32 s56, v246, 32
	v_readlane_b32 s57, v246, 33
	s_ashr_i32 s15, s14, 31
	v_readlane_b32 s58, v246, 34
	v_readlane_b32 s59, v246, 35
	s_mov_b64 s[48:49], s[56:57]
	s_lshl_b64 s[16:17], s[14:15], 19
	s_mov_b64 s[50:51], s[58:59]
	s_add_u32 s16, s50, s16
	s_addc_u32 s17, s51, s17
	s_and_b64 s[18:19], s[0:1], exec
	s_cselect_b32 s15, s17, s23
	s_cselect_b32 s44, s16, s22
	s_ashr_i32 s13, s12, 31
	s_lshl_b64 s[18:19], s[12:13], 19
	v_readlane_b32 s26, v246, 44
	v_readlane_b32 s27, v246, 45
	s_add_u32 s18, s26, s18
	s_addc_u32 s19, s27, s19
	s_and_b64 s[26:27], s[0:1], exec
	s_cselect_b32 s13, s19, s25
	s_cselect_b32 s45, s18, s24
	s_add_u32 s22, s22, 0x40080
	s_addc_u32 s23, s23, 0
	s_add_u32 s46, s24, 0x100
	s_addc_u32 s47, s25, 0
	s_mov_b32 s48, -2
	ds_read_b128 v[150:153], v147
	ds_read_b128 v[154:157], v147 offset:1024
	ds_read_b128 v[158:161], v147 offset:2048
	ds_read_b128 v[162:165], v147 offset:3072
	ds_read_b128 v[166:169], v148
	ds_read_b128 v[180:183], v148 offset:1024
	ds_read_b128 v[184:187], v148 offset:2048
	ds_read_b128 v[188:191], v148 offset:3072
	s_add_u32 s24, s22, 0xfffc0080
	s_addc_u32 s25, s23, -1
	s_cmp_eq_u32 s48, 12
	s_cselect_b32 s27, s15, s25
	s_cselect_b32 s26, s44, s24
	s_cselect_b32 s25, s13, s47
	s_cselect_b32 s24, s45, s46
	v_lshl_add_u64 v[224:225], s[22:23], 0, v[136:137]
	s_add_i32 m0, s21, 0xc000
	ds_read_b128 v[192:195], v149
	ds_read_b128 v[196:199], v149 offset:1024
	ds_read_b128 v[200:203], v149 offset:2048
	ds_read_b128 v[204:207], v149 offset:3072
	ds_read_b128 v[208:211], v149 offset:4096
	ds_read_b128 v[212:215], v149 offset:5120
	ds_read_b128 v[216:219], v149 offset:6144
	ds_read_b128 v[220:223], v149 offset:7168
	global_load_lds_dwordx4 v[224:225], off
	v_lshl_add_u64 v[224:225], s[22:23], 0, v[138:139]
	s_add_i32 m0, s21, 0xe000
	s_nop 0
	global_load_lds_dwordx4 v[224:225], off
	s_waitcnt vmcnt(8)
	s_waitcnt lgkmcnt(0)
	s_barrier
	v_mfma_f32_16x16x32_bf16 v[124:127], v[150:153], v[192:195], 0
	v_mfma_f32_16x16x32_bf16 v[120:123], v[158:161], v[192:195], 0
	v_mfma_f32_16x16x32_bf16 v[108:111], v[150:153], v[200:203], 0
	v_mfma_f32_16x16x32_bf16 v[104:107], v[158:161], v[200:203], 0
	v_mfma_f32_16x16x32_bf16 v[92:95], v[150:153], v[208:211], 0
	v_mfma_f32_16x16x32_bf16 v[88:91], v[158:161], v[208:211], 0
	v_mfma_f32_16x16x32_bf16 v[76:79], v[150:153], v[216:219], 0
	v_mfma_f32_16x16x32_bf16 v[72:75], v[158:161], v[216:219], 0
	v_mfma_f32_16x16x32_bf16 v[124:127], v[154:157], v[196:199], v[124:127]
	v_mfma_f32_16x16x32_bf16 v[120:123], v[162:165], v[196:199], v[120:123]
	v_mfma_f32_16x16x32_bf16 v[108:111], v[154:157], v[204:207], v[108:111]
	v_mfma_f32_16x16x32_bf16 v[104:107], v[162:165], v[204:207], v[104:107]
	v_mfma_f32_16x16x32_bf16 v[92:95], v[154:157], v[212:215], v[92:95]
	v_mfma_f32_16x16x32_bf16 v[88:91], v[162:165], v[212:215], v[88:91]
	v_mfma_f32_16x16x32_bf16 v[76:79], v[154:157], v[220:223], v[76:79]
	v_mfma_f32_16x16x32_bf16 v[72:75], v[162:165], v[220:223], v[72:75]
	v_mfma_f32_16x16x32_bf16 v[116:119], v[166:169], v[192:195], 0
	v_mfma_f32_16x16x32_bf16 v[112:115], v[184:187], v[192:195], 0
	v_mfma_f32_16x16x32_bf16 v[100:103], v[166:169], v[200:203], 0
	v_mfma_f32_16x16x32_bf16 v[96:99], v[184:187], v[200:203], 0
	v_mfma_f32_16x16x32_bf16 v[84:87], v[166:169], v[208:211], 0
	v_mfma_f32_16x16x32_bf16 v[80:83], v[184:187], v[208:211], 0
	v_mfma_f32_16x16x32_bf16 v[68:71], v[166:169], v[216:219], 0
	v_mfma_f32_16x16x32_bf16 v[64:67], v[184:187], v[216:219], 0
	v_mfma_f32_16x16x32_bf16 v[116:119], v[180:183], v[196:199], v[116:119]
	v_mfma_f32_16x16x32_bf16 v[112:115], v[188:191], v[196:199], v[112:115]
	v_mfma_f32_16x16x32_bf16 v[100:103], v[180:183], v[204:207], v[100:103]
	v_mfma_f32_16x16x32_bf16 v[96:99], v[188:191], v[204:207], v[96:99]
	v_mfma_f32_16x16x32_bf16 v[84:87], v[180:183], v[212:215], v[84:87]
	v_mfma_f32_16x16x32_bf16 v[80:83], v[188:191], v[212:215], v[80:83]
	v_mfma_f32_16x16x32_bf16 v[68:71], v[180:183], v[220:223], v[68:71]
	v_mfma_f32_16x16x32_bf16 v[64:67], v[188:191], v[220:223], v[64:67]
	s_barrier
	s_add_i32 s49, s40, s28
	v_lshl_add_u64 v[224:225], s[24:25], 0, v[130:131]
	s_mov_b32 m0, s49
	ds_read_b128 v[192:195], v149 offset:16384
	ds_read_b128 v[196:199], v149 offset:17408
	ds_read_b128 v[200:203], v149 offset:18432
	ds_read_b128 v[204:207], v149 offset:19456
	ds_read_b128 v[208:211], v149 offset:20480
	ds_read_b128 v[212:215], v149 offset:21504
	ds_read_b128 v[216:219], v149 offset:22528
	ds_read_b128 v[220:223], v149 offset:23552
	global_load_lds_dwordx4 v[224:225], off
	s_add_i32 m0, s49, 0x2000
	s_add_u32 s50, s24, 0x40000
	v_lshl_add_u64 v[226:227], s[24:25], 0, v[134:135]
	s_addc_u32 s51, s25, 0
	s_add_i32 s49, s41, s28
	global_load_lds_dwordx4 v[226:227], off
	v_lshl_add_u64 v[228:229], s[50:51], 0, v[130:131]
	s_mov_b32 m0, s49
	v_lshl_add_u64 v[230:231], s[26:27], 0, v[132:133]
	global_load_lds_dwordx4 v[228:229], off
	v_lshl_add_u64 v[228:229], s[50:51], 0, v[134:135]
	s_add_i32 m0, s49, 0x2000
	s_nop 0
	global_load_lds_dwordx4 v[228:229], off
	v_lshl_add_u64 v[228:229], s[26:27], 0, v[128:129]
	s_mov_b32 m0, s21
	s_nop 0
	global_load_lds_dwordx4 v[228:229], off
	s_mov_b32 m0, s31
	s_nop 0
	global_load_lds_dwordx4 v[230:231], off
	s_waitcnt vmcnt(8)
	s_waitcnt lgkmcnt(0)
	s_barrier
	v_mfma_f32_16x16x32_bf16 v[60:63], v[150:153], v[192:195], 0
	v_mfma_f32_16x16x32_bf16 v[56:59], v[158:161], v[192:195], 0
	v_mfma_f32_16x16x32_bf16 v[44:47], v[150:153], v[200:203], 0
	v_mfma_f32_16x16x32_bf16 v[40:43], v[158:161], v[200:203], 0
	v_mfma_f32_16x16x32_bf16 v[28:31], v[150:153], v[208:211], 0
	v_mfma_f32_16x16x32_bf16 v[24:27], v[158:161], v[208:211], 0
	v_mfma_f32_16x16x32_bf16 v[12:15], v[150:153], v[216:219], 0
	v_mfma_f32_16x16x32_bf16 v[8:11], v[158:161], v[216:219], 0
	v_mfma_f32_16x16x32_bf16 v[60:63], v[154:157], v[196:199], v[60:63]
	v_mfma_f32_16x16x32_bf16 v[56:59], v[162:165], v[196:199], v[56:59]
	v_mfma_f32_16x16x32_bf16 v[44:47], v[154:157], v[204:207], v[44:47]
	v_mfma_f32_16x16x32_bf16 v[40:43], v[162:165], v[204:207], v[40:43]
	v_mfma_f32_16x16x32_bf16 v[28:31], v[154:157], v[212:215], v[28:31]
	v_mfma_f32_16x16x32_bf16 v[24:27], v[162:165], v[212:215], v[24:27]
	v_mfma_f32_16x16x32_bf16 v[12:15], v[154:157], v[220:223], v[12:15]
	v_mfma_f32_16x16x32_bf16 v[8:11], v[162:165], v[220:223], v[8:11]
	v_mfma_f32_16x16x32_bf16 v[52:55], v[166:169], v[192:195], 0
	v_mfma_f32_16x16x32_bf16 v[48:51], v[184:187], v[192:195], 0
	v_mfma_f32_16x16x32_bf16 v[36:39], v[166:169], v[200:203], 0
	v_mfma_f32_16x16x32_bf16 v[32:35], v[184:187], v[200:203], 0
	v_mfma_f32_16x16x32_bf16 v[20:23], v[166:169], v[208:211], 0
	v_mfma_f32_16x16x32_bf16 v[16:19], v[184:187], v[208:211], 0
	v_mfma_f32_16x16x32_bf16 v[4:7], v[166:169], v[216:219], 0
	v_mfma_f32_16x16x32_bf16 v[0:3], v[184:187], v[216:219], 0
	v_mfma_f32_16x16x32_bf16 v[52:55], v[180:183], v[196:199], v[52:55]
	v_mfma_f32_16x16x32_bf16 v[48:51], v[188:191], v[196:199], v[48:51]
	v_mfma_f32_16x16x32_bf16 v[36:39], v[180:183], v[204:207], v[36:39]
	v_mfma_f32_16x16x32_bf16 v[32:35], v[188:191], v[204:207], v[32:35]
	v_mfma_f32_16x16x32_bf16 v[20:23], v[180:183], v[212:215], v[20:23]
	v_mfma_f32_16x16x32_bf16 v[16:19], v[188:191], v[212:215], v[16:19]
	v_mfma_f32_16x16x32_bf16 v[4:7], v[180:183], v[220:223], v[4:7]
	v_mfma_f32_16x16x32_bf16 v[0:3], v[188:191], v[220:223], v[0:3]
	s_barrier
	s_branch .Lpeel942_mid
.LBB0_942:
	ds_read_b128 v[150:153], v147
	ds_read_b128 v[154:157], v147 offset:1024
	ds_read_b128 v[158:161], v147 offset:2048
	ds_read_b128 v[162:165], v147 offset:3072
	ds_read_b128 v[166:169], v148
	ds_read_b128 v[180:183], v148 offset:1024
	ds_read_b128 v[184:187], v148 offset:2048
	ds_read_b128 v[188:191], v148 offset:3072
	s_add_u32 s24, s22, 0xfffc0080
	s_addc_u32 s25, s23, -1
	s_cmp_eq_u32 s48, 12
	s_cselect_b32 s27, s15, s25
	s_cselect_b32 s26, s44, s24
	s_cselect_b32 s25, s13, s47
	s_cselect_b32 s24, s45, s46
	v_lshl_add_u64 v[224:225], s[22:23], 0, v[136:137]
	s_add_i32 m0, s21, 0xc000
	ds_read_b128 v[192:195], v149
	ds_read_b128 v[196:199], v149 offset:1024
	ds_read_b128 v[200:203], v149 offset:2048
	ds_read_b128 v[204:207], v149 offset:3072
	ds_read_b128 v[208:211], v149 offset:4096
	ds_read_b128 v[212:215], v149 offset:5120
	ds_read_b128 v[216:219], v149 offset:6144
	ds_read_b128 v[220:223], v149 offset:7168
	global_load_lds_dwordx4 v[224:225], off
	v_lshl_add_u64 v[224:225], s[22:23], 0, v[138:139]
	s_add_i32 m0, s21, 0xe000
	s_nop 0
	global_load_lds_dwordx4 v[224:225], off
	s_waitcnt vmcnt(8)
	s_waitcnt lgkmcnt(0)
	s_barrier
	v_mfma_f32_16x16x32_bf16 v[124:127], v[150:153], v[192:195], v[124:127]
	v_mfma_f32_16x16x32_bf16 v[120:123], v[158:161], v[192:195], v[120:123]
	v_mfma_f32_16x16x32_bf16 v[108:111], v[150:153], v[200:203], v[108:111]
	v_mfma_f32_16x16x32_bf16 v[104:107], v[158:161], v[200:203], v[104:107]
	v_mfma_f32_16x16x32_bf16 v[92:95], v[150:153], v[208:211], v[92:95]
	v_mfma_f32_16x16x32_bf16 v[88:91], v[158:161], v[208:211], v[88:91]
	v_mfma_f32_16x16x32_bf16 v[76:79], v[150:153], v[216:219], v[76:79]
	v_mfma_f32_16x16x32_bf16 v[72:75], v[158:161], v[216:219], v[72:75]
	v_mfma_f32_16x16x32_bf16 v[124:127], v[154:157], v[196:199], v[124:127]
	v_mfma_f32_16x16x32_bf16 v[120:123], v[162:165], v[196:199], v[120:123]
	v_mfma_f32_16x16x32_bf16 v[108:111], v[154:157], v[204:207], v[108:111]
	v_mfma_f32_16x16x32_bf16 v[104:107], v[162:165], v[204:207], v[104:107]
	v_mfma_f32_16x16x32_bf16 v[92:95], v[154:157], v[212:215], v[92:95]
	v_mfma_f32_16x16x32_bf16 v[88:91], v[162:165], v[212:215], v[88:91]
	v_mfma_f32_16x16x32_bf16 v[76:79], v[154:157], v[220:223], v[76:79]
	v_mfma_f32_16x16x32_bf16 v[72:75], v[162:165], v[220:223], v[72:75]
	v_mfma_f32_16x16x32_bf16 v[116:119], v[166:169], v[192:195], v[116:119]
	v_mfma_f32_16x16x32_bf16 v[112:115], v[184:187], v[192:195], v[112:115]
	v_mfma_f32_16x16x32_bf16 v[100:103], v[166:169], v[200:203], v[100:103]
	v_mfma_f32_16x16x32_bf16 v[96:99], v[184:187], v[200:203], v[96:99]
	v_mfma_f32_16x16x32_bf16 v[84:87], v[166:169], v[208:211], v[84:87]
	v_mfma_f32_16x16x32_bf16 v[80:83], v[184:187], v[208:211], v[80:83]
	v_mfma_f32_16x16x32_bf16 v[68:71], v[166:169], v[216:219], v[68:71]
	v_mfma_f32_16x16x32_bf16 v[64:67], v[184:187], v[216:219], v[64:67]
	v_mfma_f32_16x16x32_bf16 v[116:119], v[180:183], v[196:199], v[116:119]
	v_mfma_f32_16x16x32_bf16 v[112:115], v[188:191], v[196:199], v[112:115]
	v_mfma_f32_16x16x32_bf16 v[100:103], v[180:183], v[204:207], v[100:103]
	v_mfma_f32_16x16x32_bf16 v[96:99], v[188:191], v[204:207], v[96:99]
	v_mfma_f32_16x16x32_bf16 v[84:87], v[180:183], v[212:215], v[84:87]
	v_mfma_f32_16x16x32_bf16 v[80:83], v[188:191], v[212:215], v[80:83]
	v_mfma_f32_16x16x32_bf16 v[68:71], v[180:183], v[220:223], v[68:71]
	v_mfma_f32_16x16x32_bf16 v[64:67], v[188:191], v[220:223], v[64:67]
	s_barrier
	s_add_i32 s49, s40, s28
	v_lshl_add_u64 v[224:225], s[24:25], 0, v[130:131]
	s_mov_b32 m0, s49
	ds_read_b128 v[192:195], v149 offset:16384
	ds_read_b128 v[196:199], v149 offset:17408
	ds_read_b128 v[200:203], v149 offset:18432
	ds_read_b128 v[204:207], v149 offset:19456
	ds_read_b128 v[208:211], v149 offset:20480
	ds_read_b128 v[212:215], v149 offset:21504
	ds_read_b128 v[216:219], v149 offset:22528
	ds_read_b128 v[220:223], v149 offset:23552
	global_load_lds_dwordx4 v[224:225], off
	s_add_i32 m0, s49, 0x2000
	s_add_u32 s50, s24, 0x40000
	v_lshl_add_u64 v[226:227], s[24:25], 0, v[134:135]
	s_addc_u32 s51, s25, 0
	s_add_i32 s49, s41, s28
	global_load_lds_dwordx4 v[226:227], off
	v_lshl_add_u64 v[228:229], s[50:51], 0, v[130:131]
	s_mov_b32 m0, s49
	v_lshl_add_u64 v[230:231], s[26:27], 0, v[132:133]
	global_load_lds_dwordx4 v[228:229], off
	v_lshl_add_u64 v[228:229], s[50:51], 0, v[134:135]
	s_add_i32 m0, s49, 0x2000
	s_nop 0
	global_load_lds_dwordx4 v[228:229], off
	v_lshl_add_u64 v[228:229], s[26:27], 0, v[128:129]
	s_mov_b32 m0, s21
	s_nop 0
	global_load_lds_dwordx4 v[228:229], off
	s_mov_b32 m0, s31
	s_nop 0
	global_load_lds_dwordx4 v[230:231], off
	s_waitcnt vmcnt(8)
	s_waitcnt lgkmcnt(0)
	s_barrier
	v_mfma_f32_16x16x32_bf16 v[60:63], v[150:153], v[192:195], v[60:63]
	v_mfma_f32_16x16x32_bf16 v[56:59], v[158:161], v[192:195], v[56:59]
	v_mfma_f32_16x16x32_bf16 v[44:47], v[150:153], v[200:203], v[44:47]
	v_mfma_f32_16x16x32_bf16 v[40:43], v[158:161], v[200:203], v[40:43]
	v_mfma_f32_16x16x32_bf16 v[28:31], v[150:153], v[208:211], v[28:31]
	v_mfma_f32_16x16x32_bf16 v[24:27], v[158:161], v[208:211], v[24:27]
	v_mfma_f32_16x16x32_bf16 v[12:15], v[150:153], v[216:219], v[12:15]
	v_mfma_f32_16x16x32_bf16 v[8:11], v[158:161], v[216:219], v[8:11]
	v_mfma_f32_16x16x32_bf16 v[60:63], v[154:157], v[196:199], v[60:63]
	v_mfma_f32_16x16x32_bf16 v[56:59], v[162:165], v[196:199], v[56:59]
	v_mfma_f32_16x16x32_bf16 v[44:47], v[154:157], v[204:207], v[44:47]
	v_mfma_f32_16x16x32_bf16 v[40:43], v[162:165], v[204:207], v[40:43]
	v_mfma_f32_16x16x32_bf16 v[28:31], v[154:157], v[212:215], v[28:31]
	v_mfma_f32_16x16x32_bf16 v[24:27], v[162:165], v[212:215], v[24:27]
	v_mfma_f32_16x16x32_bf16 v[12:15], v[154:157], v[220:223], v[12:15]
	v_mfma_f32_16x16x32_bf16 v[8:11], v[162:165], v[220:223], v[8:11]
	v_mfma_f32_16x16x32_bf16 v[52:55], v[166:169], v[192:195], v[52:55]
	v_mfma_f32_16x16x32_bf16 v[48:51], v[184:187], v[192:195], v[48:51]
	v_mfma_f32_16x16x32_bf16 v[36:39], v[166:169], v[200:203], v[36:39]
	v_mfma_f32_16x16x32_bf16 v[32:35], v[184:187], v[200:203], v[32:35]
	v_mfma_f32_16x16x32_bf16 v[20:23], v[166:169], v[208:211], v[20:23]
	v_mfma_f32_16x16x32_bf16 v[16:19], v[184:187], v[208:211], v[16:19]
	v_mfma_f32_16x16x32_bf16 v[4:7], v[166:169], v[216:219], v[4:7]
	v_mfma_f32_16x16x32_bf16 v[0:3], v[184:187], v[216:219], v[0:3]
	v_mfma_f32_16x16x32_bf16 v[52:55], v[180:183], v[196:199], v[52:55]
	v_mfma_f32_16x16x32_bf16 v[48:51], v[188:191], v[196:199], v[48:51]
	v_mfma_f32_16x16x32_bf16 v[36:39], v[180:183], v[204:207], v[36:39]
	v_mfma_f32_16x16x32_bf16 v[32:35], v[188:191], v[204:207], v[32:35]
	v_mfma_f32_16x16x32_bf16 v[20:23], v[180:183], v[212:215], v[20:23]
	v_mfma_f32_16x16x32_bf16 v[16:19], v[188:191], v[212:215], v[16:19]
	v_mfma_f32_16x16x32_bf16 v[4:7], v[180:183], v[220:223], v[4:7]
	v_mfma_f32_16x16x32_bf16 v[0:3], v[188:191], v[220:223], v[0:3]
	s_barrier
.Lpeel942_mid:
	s_add_i32 s49, 0, 0x18000
	s_add_i32 s50, 0, 0x1c000
	v_add_u32_e32 v162, s49, v145
	v_add_u32_e32 v179, s50, v145
	ds_read_b128 v[150:153], v162
	ds_read_b128 v[154:157], v162 offset:1024
	ds_read_b128 v[158:161], v162 offset:2048
	ds_read_b128 v[162:165], v162 offset:3072
	ds_read_b128 v[166:169], v179
	ds_read_b128 v[180:183], v179 offset:1024
	ds_read_b128 v[184:187], v179 offset:2048
	ds_read_b128 v[188:191], v179 offset:3072
	s_add_u32 s26, s26, 0x40000
	s_addc_u32 s27, s27, 0
	s_mov_b32 m0, s33
	v_lshl_add_u64 v[232:233], s[26:27], 0, v[128:129]
	ds_read_b128 v[192:195], v149 offset:32768
	ds_read_b128 v[196:199], v149 offset:33792
	ds_read_b128 v[200:203], v149 offset:34816
	ds_read_b128 v[204:207], v149 offset:35840
	ds_read_b128 v[208:211], v149 offset:36864
	ds_read_b128 v[212:215], v149 offset:37888
	ds_read_b128 v[216:219], v149 offset:38912
	ds_read_b128 v[220:223], v149 offset:39936
	global_load_lds_dwordx4 v[232:233], off
	v_lshl_add_u64 v[232:233], s[26:27], 0, v[132:133]
	s_mov_b32 m0, s34
	s_nop 0
	global_load_lds_dwordx4 v[232:233], off
	s_waitcnt vmcnt(8)
	s_waitcnt lgkmcnt(0)
	s_barrier
	v_mfma_f32_16x16x32_bf16 v[124:127], v[150:153], v[192:195], v[124:127]
	v_mfma_f32_16x16x32_bf16 v[120:123], v[158:161], v[192:195], v[120:123]
	v_mfma_f32_16x16x32_bf16 v[108:111], v[150:153], v[200:203], v[108:111]
	v_mfma_f32_16x16x32_bf16 v[104:107], v[158:161], v[200:203], v[104:107]
	v_mfma_f32_16x16x32_bf16 v[92:95], v[150:153], v[208:211], v[92:95]
	v_mfma_f32_16x16x32_bf16 v[88:91], v[158:161], v[208:211], v[88:91]
	v_mfma_f32_16x16x32_bf16 v[76:79], v[150:153], v[216:219], v[76:79]
	v_mfma_f32_16x16x32_bf16 v[72:75], v[158:161], v[216:219], v[72:75]
	v_mfma_f32_16x16x32_bf16 v[124:127], v[154:157], v[196:199], v[124:127]
	v_mfma_f32_16x16x32_bf16 v[120:123], v[162:165], v[196:199], v[120:123]
	v_mfma_f32_16x16x32_bf16 v[108:111], v[154:157], v[204:207], v[108:111]
	v_mfma_f32_16x16x32_bf16 v[104:107], v[162:165], v[204:207], v[104:107]
	v_mfma_f32_16x16x32_bf16 v[92:95], v[154:157], v[212:215], v[92:95]
	v_mfma_f32_16x16x32_bf16 v[88:91], v[162:165], v[212:215], v[88:91]
	v_mfma_f32_16x16x32_bf16 v[76:79], v[154:157], v[220:223], v[76:79]
	v_mfma_f32_16x16x32_bf16 v[72:75], v[162:165], v[220:223], v[72:75]
	v_mfma_f32_16x16x32_bf16 v[116:119], v[166:169], v[192:195], v[116:119]
	v_mfma_f32_16x16x32_bf16 v[112:115], v[184:187], v[192:195], v[112:115]
	v_mfma_f32_16x16x32_bf16 v[100:103], v[166:169], v[200:203], v[100:103]
	v_mfma_f32_16x16x32_bf16 v[96:99], v[184:187], v[200:203], v[96:99]
	v_mfma_f32_16x16x32_bf16 v[84:87], v[166:169], v[208:211], v[84:87]
	v_mfma_f32_16x16x32_bf16 v[80:83], v[184:187], v[208:211], v[80:83]
	v_mfma_f32_16x16x32_bf16 v[68:71], v[166:169], v[216:219], v[68:71]
	v_mfma_f32_16x16x32_bf16 v[64:67], v[184:187], v[216:219], v[64:67]
	v_mfma_f32_16x16x32_bf16 v[116:119], v[180:183], v[196:199], v[116:119]
	v_mfma_f32_16x16x32_bf16 v[112:115], v[188:191], v[196:199], v[112:115]
	v_mfma_f32_16x16x32_bf16 v[100:103], v[180:183], v[204:207], v[100:103]
	v_mfma_f32_16x16x32_bf16 v[96:99], v[188:191], v[204:207], v[96:99]
	v_mfma_f32_16x16x32_bf16 v[84:87], v[180:183], v[212:215], v[84:87]
	v_mfma_f32_16x16x32_bf16 v[80:83], v[188:191], v[212:215], v[80:83]
	v_mfma_f32_16x16x32_bf16 v[68:71], v[180:183], v[220:223], v[68:71]
	v_mfma_f32_16x16x32_bf16 v[64:67], v[188:191], v[220:223], v[64:67]
	s_barrier
	s_add_i32 s26, s49, s28
	v_lshl_add_u64 v[224:225], v[224:225], 0, s[8:9]
	s_mov_b32 m0, s26
	ds_read_b128 v[192:195], v149 offset:49152
	ds_read_b128 v[196:199], v149 offset:50176
	ds_read_b128 v[200:203], v149 offset:51200
	ds_read_b128 v[204:207], v149 offset:52224
	ds_read_b128 v[208:211], v149 offset:53248
	ds_read_b128 v[212:215], v149 offset:54272
	ds_read_b128 v[216:219], v149 offset:55296
	ds_read_b128 v[220:223], v149 offset:56320
	global_load_lds_dwordx4 v[224:225], off
	s_add_i32 m0, s26, 0x2000
	s_add_u32 s24, s24, 0x40080
	v_lshl_add_u64 v[224:225], v[226:227], 0, s[8:9]
	s_addc_u32 s25, s25, 0
	s_add_i32 s26, s50, s28
	global_load_lds_dwordx4 v[224:225], off
	v_lshl_add_u64 v[224:225], s[24:25], 0, v[130:131]
	s_mov_b32 m0, s26
	s_nop 0
	global_load_lds_dwordx4 v[224:225], off
	v_lshl_add_u64 v[224:225], s[24:25], 0, v[134:135]
	s_add_i32 m0, s26, 0x2000
	s_nop 0
	global_load_lds_dwordx4 v[224:225], off
	v_lshl_add_u64 v[224:225], v[228:229], 0, s[8:9]
	s_mov_b32 m0, s37
	s_nop 0
	global_load_lds_dwordx4 v[224:225], off
	v_lshl_add_u64 v[224:225], v[230:231], 0, s[8:9]
	s_mov_b32 m0, s38
	s_nop 0
	global_load_lds_dwordx4 v[224:225], off
	s_waitcnt vmcnt(8)
	s_waitcnt lgkmcnt(0)
	s_barrier
	v_mfma_f32_16x16x32_bf16 v[60:63], v[150:153], v[192:195], v[60:63]
	v_mfma_f32_16x16x32_bf16 v[56:59], v[158:161], v[192:195], v[56:59]
	v_mfma_f32_16x16x32_bf16 v[44:47], v[150:153], v[200:203], v[44:47]
	v_mfma_f32_16x16x32_bf16 v[40:43], v[158:161], v[200:203], v[40:43]
	v_mfma_f32_16x16x32_bf16 v[28:31], v[150:153], v[208:211], v[28:31]
	v_mfma_f32_16x16x32_bf16 v[24:27], v[158:161], v[208:211], v[24:27]
	v_mfma_f32_16x16x32_bf16 v[12:15], v[150:153], v[216:219], v[12:15]
	v_mfma_f32_16x16x32_bf16 v[8:11], v[158:161], v[216:219], v[8:11]
	v_mfma_f32_16x16x32_bf16 v[60:63], v[154:157], v[196:199], v[60:63]
	v_mfma_f32_16x16x32_bf16 v[56:59], v[162:165], v[196:199], v[56:59]
	v_mfma_f32_16x16x32_bf16 v[44:47], v[154:157], v[204:207], v[44:47]
	v_mfma_f32_16x16x32_bf16 v[40:43], v[162:165], v[204:207], v[40:43]
	v_mfma_f32_16x16x32_bf16 v[28:31], v[154:157], v[212:215], v[28:31]
	v_mfma_f32_16x16x32_bf16 v[24:27], v[162:165], v[212:215], v[24:27]
	v_mfma_f32_16x16x32_bf16 v[12:15], v[154:157], v[220:223], v[12:15]
	v_mfma_f32_16x16x32_bf16 v[8:11], v[162:165], v[220:223], v[8:11]
	v_mfma_f32_16x16x32_bf16 v[52:55], v[166:169], v[192:195], v[52:55]
	v_mfma_f32_16x16x32_bf16 v[48:51], v[184:187], v[192:195], v[48:51]
	v_mfma_f32_16x16x32_bf16 v[36:39], v[166:169], v[200:203], v[36:39]
	v_mfma_f32_16x16x32_bf16 v[32:35], v[184:187], v[200:203], v[32:35]
	v_mfma_f32_16x16x32_bf16 v[20:23], v[166:169], v[208:211], v[20:23]
	v_mfma_f32_16x16x32_bf16 v[16:19], v[184:187], v[208:211], v[16:19]
	v_mfma_f32_16x16x32_bf16 v[4:7], v[166:169], v[216:219], v[4:7]
	v_mfma_f32_16x16x32_bf16 v[0:3], v[184:187], v[216:219], v[0:3]
	v_mfma_f32_16x16x32_bf16 v[52:55], v[180:183], v[196:199], v[52:55]
	v_mfma_f32_16x16x32_bf16 v[48:51], v[188:191], v[196:199], v[48:51]
	v_mfma_f32_16x16x32_bf16 v[36:39], v[180:183], v[204:207], v[36:39]
	v_mfma_f32_16x16x32_bf16 v[32:35], v[188:191], v[204:207], v[32:35]
	v_mfma_f32_16x16x32_bf16 v[20:23], v[180:183], v[212:215], v[20:23]
	v_mfma_f32_16x16x32_bf16 v[16:19], v[188:191], v[212:215], v[16:19]
	v_mfma_f32_16x16x32_bf16 v[4:7], v[180:183], v[220:223], v[4:7]
	v_mfma_f32_16x16x32_bf16 v[0:3], v[188:191], v[220:223], v[0:3]
	s_barrier
	s_add_i32 s48, s48, 2
	s_add_u32 s22, s22, 0x100
	s_addc_u32 s23, s23, 0
	s_add_u32 s46, s46, 0x100
	s_addc_u32 s47, s47, 0
	s_cmp_gt_u32 s48, 13
	s_cbranch_scc0 .LBB0_942
	s_and_b64 vcc, exec, s[10:11]
	s_cbranch_vccz .LBB0_945
	s_barrier

.LBB0_1018:
	ds_read_b128 v[152:155], v149
	ds_read_b128 v[156:159], v149 offset:1024
	ds_read_b128 v[160:163], v149 offset:2048
	ds_read_b128 v[164:167], v149 offset:3072
	ds_read_b128 v[174:177], v150
	ds_read_b128 v[178:181], v150 offset:1024
	ds_read_b128 v[182:185], v150 offset:2048
	ds_read_b128 v[186:189], v150 offset:3072
	s_add_u32 s34, s30, 0xfff50080
	s_addc_u32 s35, s31, -1
	s_cmp_eq_u32 s60, 40
	s_cselect_b32 s37, s5, s35
	s_cselect_b32 s36, s4, s34
	s_cselect_b32 s35, s29, s57
	s_cselect_b32 s34, s28, s56
	v_lshl_add_u64 v[140:141], s[30:31], 0, v[132:133]
	s_add_i32 m0, s41, 0xc000
	ds_read_b128 v[190:193], v151
	ds_read_b128 v[194:197], v151 offset:1024
	ds_read_b128 v[198:201], v151 offset:2048
	ds_read_b128 v[202:205], v151 offset:3072
	ds_read_b128 v[206:209], v151 offset:4096
	ds_read_b128 v[210:213], v151 offset:5120
	ds_read_b128 v[214:217], v151 offset:6144
	ds_read_b128 v[218:221], v151 offset:7168
	global_load_lds_dwordx4 v[140:141], off
	v_lshl_add_u64 v[140:141], s[30:31], 0, v[134:135]
	s_add_i32 m0, s41, 0xe000
	s_nop 0
	global_load_lds_dwordx4 v[140:141], off
	s_waitcnt vmcnt(8)
	s_waitcnt lgkmcnt(0)
	s_barrier
	v_mfma_f32_16x16x32_bf16 v[124:127], v[152:155], v[190:193], v[124:127]
	v_mfma_f32_16x16x32_bf16 v[120:123], v[160:163], v[190:193], v[120:123]
	v_mfma_f32_16x16x32_bf16 v[112:115], v[152:155], v[198:201], v[112:115]
	v_mfma_f32_16x16x32_bf16 v[108:111], v[160:163], v[198:201], v[108:111]
	v_mfma_f32_16x16x32_bf16 v[96:99], v[152:155], v[206:209], v[96:99]
	v_mfma_f32_16x16x32_bf16 v[92:95], v[160:163], v[206:209], v[92:95]
	v_mfma_f32_16x16x32_bf16 v[80:83], v[152:155], v[214:217], v[80:83]
	v_mfma_f32_16x16x32_bf16 v[76:79], v[160:163], v[214:217], v[76:79]
	v_mfma_f32_16x16x32_bf16 v[124:127], v[156:159], v[194:197], v[124:127]
	v_mfma_f32_16x16x32_bf16 v[120:123], v[164:167], v[194:197], v[120:123]
	v_mfma_f32_16x16x32_bf16 v[112:115], v[156:159], v[202:205], v[112:115]
	v_mfma_f32_16x16x32_bf16 v[108:111], v[164:167], v[202:205], v[108:111]
	v_mfma_f32_16x16x32_bf16 v[96:99], v[156:159], v[210:213], v[96:99]
	v_mfma_f32_16x16x32_bf16 v[92:95], v[164:167], v[210:213], v[92:95]
	v_mfma_f32_16x16x32_bf16 v[80:83], v[156:159], v[218:221], v[80:83]
	v_mfma_f32_16x16x32_bf16 v[76:79], v[164:167], v[218:221], v[76:79]
	v_mfma_f32_16x16x32_bf16 v[116:119], v[174:177], v[190:193], v[116:119]
	v_mfma_f32_16x16x32_bf16 v[104:107], v[182:185], v[190:193], v[104:107]
	v_mfma_f32_16x16x32_bf16 v[100:103], v[174:177], v[198:201], v[100:103]
	v_mfma_f32_16x16x32_bf16 v[88:91], v[182:185], v[198:201], v[88:91]
	v_mfma_f32_16x16x32_bf16 v[84:87], v[174:177], v[206:209], v[84:87]
	v_mfma_f32_16x16x32_bf16 v[72:75], v[182:185], v[206:209], v[72:75]
	v_mfma_f32_16x16x32_bf16 v[68:71], v[174:177], v[214:217], v[68:71]
	v_mfma_f32_16x16x32_bf16 v[64:67], v[182:185], v[214:217], v[64:67]
	v_mfma_f32_16x16x32_bf16 v[116:119], v[178:181], v[194:197], v[116:119]
	v_mfma_f32_16x16x32_bf16 v[104:107], v[186:189], v[194:197], v[104:107]
	v_mfma_f32_16x16x32_bf16 v[100:103], v[178:181], v[202:205], v[100:103]
	v_mfma_f32_16x16x32_bf16 v[88:91], v[186:189], v[202:205], v[88:91]
	v_mfma_f32_16x16x32_bf16 v[84:87], v[178:181], v[210:213], v[84:87]
	v_mfma_f32_16x16x32_bf16 v[72:75], v[186:189], v[210:213], v[72:75]
	v_mfma_f32_16x16x32_bf16 v[68:71], v[178:181], v[218:221], v[68:71]
	v_mfma_f32_16x16x32_bf16 v[64:67], v[186:189], v[218:221], v[64:67]
	s_barrier
	s_add_i32 s61, s50, s40
	v_lshl_add_u64 v[140:141], s[34:35], 0, v[128:129]
	s_mov_b32 m0, s61
	ds_read_b128 v[190:193], v151 offset:16384
	ds_read_b128 v[194:197], v151 offset:17408
	ds_read_b128 v[198:201], v151 offset:18432
	ds_read_b128 v[202:205], v151 offset:19456
	ds_read_b128 v[206:209], v151 offset:20480
	ds_read_b128 v[210:213], v151 offset:21504
	ds_read_b128 v[214:217], v151 offset:22528
	ds_read_b128 v[218:221], v151 offset:23552
	global_load_lds_dwordx4 v[140:141], off
	s_add_i32 m0, s61, 0x2000
	s_add_u32 s62, s34, 0xb0000
	v_lshl_add_u64 v[168:169], s[34:35], 0, v[130:131]
	s_addc_u32 s63, s35, 0
	s_add_i32 s61, s51, s40
	global_load_lds_dwordx4 v[168:169], off
	v_lshl_add_u64 v[222:223], s[62:63], 0, v[128:129]
	s_mov_b32 m0, s61
	v_lshl_add_u64 v[224:225], s[36:37], 0, v[130:131]
	global_load_lds_dwordx4 v[222:223], off
	v_lshl_add_u64 v[222:223], s[62:63], 0, v[130:131]
	s_add_i32 m0, s61, 0x2000
	s_nop 0
	global_load_lds_dwordx4 v[222:223], off
	v_lshl_add_u64 v[222:223], s[36:37], 0, v[128:129]
	s_mov_b32 m0, s41
	s_nop 0
	global_load_lds_dwordx4 v[222:223], off
	s_mov_b32 m0, s42
	s_nop 0
	global_load_lds_dwordx4 v[224:225], off
	s_waitcnt vmcnt(8)
	s_waitcnt lgkmcnt(0)
	s_barrier
	v_mfma_f32_16x16x32_bf16 v[60:63], v[152:155], v[190:193], v[60:63]
	v_mfma_f32_16x16x32_bf16 v[56:59], v[160:163], v[190:193], v[56:59]
	v_mfma_f32_16x16x32_bf16 v[48:51], v[152:155], v[198:201], v[48:51]
	v_mfma_f32_16x16x32_bf16 v[44:47], v[160:163], v[198:201], v[44:47]
	v_mfma_f32_16x16x32_bf16 v[32:35], v[152:155], v[206:209], v[32:35]
	v_mfma_f32_16x16x32_bf16 v[28:31], v[160:163], v[206:209], v[28:31]
	v_mfma_f32_16x16x32_bf16 v[16:19], v[152:155], v[214:217], v[16:19]
	v_mfma_f32_16x16x32_bf16 v[8:11], v[160:163], v[214:217], v[8:11]
	v_mfma_f32_16x16x32_bf16 v[60:63], v[156:159], v[194:197], v[60:63]
	v_mfma_f32_16x16x32_bf16 v[56:59], v[164:167], v[194:197], v[56:59]
	v_mfma_f32_16x16x32_bf16 v[48:51], v[156:159], v[202:205], v[48:51]
	v_mfma_f32_16x16x32_bf16 v[44:47], v[164:167], v[202:205], v[44:47]
	v_mfma_f32_16x16x32_bf16 v[32:35], v[156:159], v[210:213], v[32:35]
	v_mfma_f32_16x16x32_bf16 v[28:31], v[164:167], v[210:213], v[28:31]
	v_mfma_f32_16x16x32_bf16 v[16:19], v[156:159], v[218:221], v[16:19]
	v_mfma_f32_16x16x32_bf16 v[8:11], v[164:167], v[218:221], v[8:11]
	v_mfma_f32_16x16x32_bf16 v[52:55], v[174:177], v[190:193], v[52:55]
	v_mfma_f32_16x16x32_bf16 v[40:43], v[182:185], v[190:193], v[40:43]
	v_mfma_f32_16x16x32_bf16 v[36:39], v[174:177], v[198:201], v[36:39]
	v_mfma_f32_16x16x32_bf16 v[24:27], v[182:185], v[198:201], v[24:27]
	v_mfma_f32_16x16x32_bf16 v[20:23], v[174:177], v[206:209], v[20:23]
	v_mfma_f32_16x16x32_bf16 v[12:15], v[182:185], v[206:209], v[12:15]
	v_mfma_f32_16x16x32_bf16 v[4:7], v[174:177], v[214:217], v[4:7]
	v_mfma_f32_16x16x32_bf16 v[0:3], v[182:185], v[214:217], v[0:3]
	v_mfma_f32_16x16x32_bf16 v[52:55], v[178:181], v[194:197], v[52:55]
	v_mfma_f32_16x16x32_bf16 v[40:43], v[186:189], v[194:197], v[40:43]
	v_mfma_f32_16x16x32_bf16 v[36:39], v[178:181], v[202:205], v[36:39]
	v_mfma_f32_16x16x32_bf16 v[24:27], v[186:189], v[202:205], v[24:27]
	v_mfma_f32_16x16x32_bf16 v[20:23], v[178:181], v[210:213], v[20:23]
	v_mfma_f32_16x16x32_bf16 v[12:15], v[186:189], v[210:213], v[12:15]
	v_mfma_f32_16x16x32_bf16 v[4:7], v[178:181], v[218:221], v[4:7]
	v_mfma_f32_16x16x32_bf16 v[0:3], v[186:189], v[218:221], v[0:3]
	s_barrier
	s_add_i32 s61, 0, 0x18000
	s_add_i32 s62, 0, 0x1c000
	v_add_u32_e32 v164, s61, v147
	v_add_u32_e32 v186, s62, v147
	ds_read_b128 v[152:155], v164
	ds_read_b128 v[156:159], v164 offset:1024
	ds_read_b128 v[160:163], v164 offset:2048
	ds_read_b128 v[164:167], v164 offset:3072
	ds_read_b128 v[174:177], v186
	ds_read_b128 v[178:181], v186 offset:1024
	ds_read_b128 v[182:185], v186 offset:2048
	ds_read_b128 v[186:189], v186 offset:3072
	s_add_u32 s36, s36, 0xb0000
	s_addc_u32 s37, s37, 0
	s_mov_b32 m0, s43
	v_lshl_add_u64 v[226:227], s[36:37], 0, v[128:129]
	ds_read_b128 v[190:193], v151 offset:32768
	ds_read_b128 v[194:197], v151 offset:33792
	ds_read_b128 v[198:201], v151 offset:34816
	ds_read_b128 v[202:205], v151 offset:35840
	ds_read_b128 v[206:209], v151 offset:36864
	ds_read_b128 v[210:213], v151 offset:37888
	ds_read_b128 v[214:217], v151 offset:38912
	ds_read_b128 v[218:221], v151 offset:39936
	global_load_lds_dwordx4 v[226:227], off
	v_lshl_add_u64 v[226:227], s[36:37], 0, v[130:131]
	s_mov_b32 m0, s44
	s_nop 0
	global_load_lds_dwordx4 v[226:227], off
	s_waitcnt vmcnt(8)
	s_waitcnt lgkmcnt(0)
	s_barrier
	v_mfma_f32_16x16x32_bf16 v[124:127], v[152:155], v[190:193], v[124:127]
	v_mfma_f32_16x16x32_bf16 v[120:123], v[160:163], v[190:193], v[120:123]
	v_mfma_f32_16x16x32_bf16 v[112:115], v[152:155], v[198:201], v[112:115]
	v_mfma_f32_16x16x32_bf16 v[108:111], v[160:163], v[198:201], v[108:111]
	v_mfma_f32_16x16x32_bf16 v[96:99], v[152:155], v[206:209], v[96:99]
	v_mfma_f32_16x16x32_bf16 v[92:95], v[160:163], v[206:209], v[92:95]
	v_mfma_f32_16x16x32_bf16 v[80:83], v[152:155], v[214:217], v[80:83]
	v_mfma_f32_16x16x32_bf16 v[76:79], v[160:163], v[214:217], v[76:79]
	v_mfma_f32_16x16x32_bf16 v[124:127], v[156:159], v[194:197], v[124:127]
	v_mfma_f32_16x16x32_bf16 v[120:123], v[164:167], v[194:197], v[120:123]
	v_mfma_f32_16x16x32_bf16 v[112:115], v[156:159], v[202:205], v[112:115]
	v_mfma_f32_16x16x32_bf16 v[108:111], v[164:167], v[202:205], v[108:111]
	v_mfma_f32_16x16x32_bf16 v[96:99], v[156:159], v[210:213], v[96:99]
	v_mfma_f32_16x16x32_bf16 v[92:95], v[164:167], v[210:213], v[92:95]
	v_mfma_f32_16x16x32_bf16 v[80:83], v[156:159], v[218:221], v[80:83]
	v_mfma_f32_16x16x32_bf16 v[76:79], v[164:167], v[218:221], v[76:79]
	v_mfma_f32_16x16x32_bf16 v[116:119], v[174:177], v[190:193], v[116:119]
	v_mfma_f32_16x16x32_bf16 v[104:107], v[182:185], v[190:193], v[104:107]
	v_mfma_f32_16x16x32_bf16 v[100:103], v[174:177], v[198:201], v[100:103]
	v_mfma_f32_16x16x32_bf16 v[88:91], v[182:185], v[198:201], v[88:91]
	v_mfma_f32_16x16x32_bf16 v[84:87], v[174:177], v[206:209], v[84:87]
	v_mfma_f32_16x16x32_bf16 v[72:75], v[182:185], v[206:209], v[72:75]
	v_mfma_f32_16x16x32_bf16 v[68:71], v[174:177], v[214:217], v[68:71]
	v_mfma_f32_16x16x32_bf16 v[64:67], v[182:185], v[214:217], v[64:67]
	v_mfma_f32_16x16x32_bf16 v[116:119], v[178:181], v[194:197], v[116:119]
	v_mfma_f32_16x16x32_bf16 v[104:107], v[186:189], v[194:197], v[104:107]
	v_mfma_f32_16x16x32_bf16 v[100:103], v[178:181], v[202:205], v[100:103]
	v_mfma_f32_16x16x32_bf16 v[88:91], v[186:189], v[202:205], v[88:91]
	v_mfma_f32_16x16x32_bf16 v[84:87], v[178:181], v[210:213], v[84:87]
	v_mfma_f32_16x16x32_bf16 v[72:75], v[186:189], v[210:213], v[72:75]
	v_mfma_f32_16x16x32_bf16 v[68:71], v[178:181], v[218:221], v[68:71]
	v_mfma_f32_16x16x32_bf16 v[64:67], v[186:189], v[218:221], v[64:67]
	s_barrier
	s_add_i32 s36, s61, s40
	v_lshl_add_u64 v[140:141], v[140:141], 0, s[16:17]
	s_mov_b32 m0, s36
	ds_read_b128 v[190:193], v151 offset:49152
	ds_read_b128 v[194:197], v151 offset:50176
	ds_read_b128 v[198:201], v151 offset:51200
	ds_read_b128 v[202:205], v151 offset:52224
	ds_read_b128 v[206:209], v151 offset:53248
	ds_read_b128 v[210:213], v151 offset:54272
	ds_read_b128 v[214:217], v151 offset:55296
	ds_read_b128 v[218:221], v151 offset:56320
	global_load_lds_dwordx4 v[140:141], off
	s_add_i32 m0, s36, 0x2000
	s_add_u32 s34, s34, 0xb0080
	v_lshl_add_u64 v[140:141], v[168:169], 0, s[16:17]
	s_addc_u32 s35, s35, 0
	s_add_i32 s36, s62, s40
	global_load_lds_dwordx4 v[140:141], off
	v_lshl_add_u64 v[140:141], s[34:35], 0, v[128:129]
	s_mov_b32 m0, s36
	s_nop 0
	global_load_lds_dwordx4 v[140:141], off
	v_lshl_add_u64 v[140:141], s[34:35], 0, v[130:131]
	s_add_i32 m0, s36, 0x2000
	s_nop 0
	global_load_lds_dwordx4 v[140:141], off
	v_lshl_add_u64 v[140:141], v[222:223], 0, s[16:17]
	s_mov_b32 m0, s47
	s_nop 0
	global_load_lds_dwordx4 v[140:141], off
	v_lshl_add_u64 v[140:141], v[224:225], 0, s[16:17]
	s_mov_b32 m0, s48
	s_nop 0
	global_load_lds_dwordx4 v[140:141], off
	s_waitcnt vmcnt(8)
	s_waitcnt lgkmcnt(0)
	s_barrier
	v_mfma_f32_16x16x32_bf16 v[60:63], v[152:155], v[190:193], v[60:63]
	v_mfma_f32_16x16x32_bf16 v[56:59], v[160:163], v[190:193], v[56:59]
	v_mfma_f32_16x16x32_bf16 v[48:51], v[152:155], v[198:201], v[48:51]
	v_mfma_f32_16x16x32_bf16 v[44:47], v[160:163], v[198:201], v[44:47]
	v_mfma_f32_16x16x32_bf16 v[32:35], v[152:155], v[206:209], v[32:35]
	v_mfma_f32_16x16x32_bf16 v[28:31], v[160:163], v[206:209], v[28:31]
	v_mfma_f32_16x16x32_bf16 v[16:19], v[152:155], v[214:217], v[16:19]
	v_mfma_f32_16x16x32_bf16 v[8:11], v[160:163], v[214:217], v[8:11]
	v_mfma_f32_16x16x32_bf16 v[60:63], v[156:159], v[194:197], v[60:63]
	v_mfma_f32_16x16x32_bf16 v[56:59], v[164:167], v[194:197], v[56:59]
	v_mfma_f32_16x16x32_bf16 v[48:51], v[156:159], v[202:205], v[48:51]
	v_mfma_f32_16x16x32_bf16 v[44:47], v[164:167], v[202:205], v[44:47]
	v_mfma_f32_16x16x32_bf16 v[32:35], v[156:159], v[210:213], v[32:35]
	v_mfma_f32_16x16x32_bf16 v[28:31], v[164:167], v[210:213], v[28:31]
	v_mfma_f32_16x16x32_bf16 v[16:19], v[156:159], v[218:221], v[16:19]
	v_mfma_f32_16x16x32_bf16 v[8:11], v[164:167], v[218:221], v[8:11]
	v_mfma_f32_16x16x32_bf16 v[52:55], v[174:177], v[190:193], v[52:55]
	v_mfma_f32_16x16x32_bf16 v[40:43], v[182:185], v[190:193], v[40:43]
	v_mfma_f32_16x16x32_bf16 v[36:39], v[174:177], v[198:201], v[36:39]
	v_mfma_f32_16x16x32_bf16 v[24:27], v[182:185], v[198:201], v[24:27]
	v_mfma_f32_16x16x32_bf16 v[20:23], v[174:177], v[206:209], v[20:23]
	v_mfma_f32_16x16x32_bf16 v[12:15], v[182:185], v[206:209], v[12:15]
	v_mfma_f32_16x16x32_bf16 v[4:7], v[174:177], v[214:217], v[4:7]
	v_mfma_f32_16x16x32_bf16 v[0:3], v[182:185], v[214:217], v[0:3]
	v_mfma_f32_16x16x32_bf16 v[52:55], v[178:181], v[194:197], v[52:55]
	v_mfma_f32_16x16x32_bf16 v[40:43], v[186:189], v[194:197], v[40:43]
	v_mfma_f32_16x16x32_bf16 v[36:39], v[178:181], v[202:205], v[36:39]
	v_mfma_f32_16x16x32_bf16 v[24:27], v[186:189], v[202:205], v[24:27]
	v_mfma_f32_16x16x32_bf16 v[20:23], v[178:181], v[210:213], v[20:23]
	v_mfma_f32_16x16x32_bf16 v[12:15], v[186:189], v[210:213], v[12:15]
	v_mfma_f32_16x16x32_bf16 v[4:7], v[178:181], v[218:221], v[4:7]
	v_mfma_f32_16x16x32_bf16 v[0:3], v[186:189], v[218:221], v[0:3]
	s_barrier
	s_add_i32 s60, s60, 2
	s_add_u32 s30, s30, 0x100
	s_addc_u32 s31, s31, 0
	s_add_u32 s56, s56, 0x100
	s_addc_u32 s57, s57, 0
	s_cmp_gt_u32 s60, 41
	s_cbranch_scc0 .LBB0_1018
	s_and_b64 vcc, exec, s[18:19]
	s_cbranch_vccz .LBB0_1021
	s_barrier

.LBB0_1042:
	v_add_u32_e32 v147, s39, v146
	ds_read_b128 v[148:151], v147
	ds_read_b128 v[152:155], v147 offset:1024
	ds_read_b128 v[156:159], v147 offset:2048
	ds_read_b128 v[164:167], v147 offset:3072
	v_add_u32_e32 v147, s40, v146
	s_add_u32 s20, s12, s18
	ds_read_b128 v[174:177], v147
	ds_read_b128 v[178:181], v147 offset:1024
	ds_read_b128 v[182:185], v147 offset:2048
	ds_read_b128 v[186:189], v147 offset:3072
	s_addc_u32 s21, s13, s19
	s_add_u32 s20, s20, 0x100
	s_addc_u32 s21, s21, 0
	s_add_u32 s47, s44, s18
	s_addc_u32 s48, s45, s19
	s_cmpk_eq_i32 s18, 0x1500
	s_cselect_b32 s23, s17, s21
	s_cselect_b32 s22, s16, s20
	s_cselect_b32 s21, s5, s48
	s_cselect_b32 s20, s4, s47
	v_lshl_add_u64 v[160:161], v[140:141], 0, s[18:19]
	s_add_i32 m0, s29, 0xc000
	ds_read_b128 v[190:193], v144
	ds_read_b128 v[194:197], v144 offset:1024
	ds_read_b128 v[198:201], v144 offset:2048
	ds_read_b128 v[202:205], v144 offset:3072
	ds_read_b128 v[206:209], v144 offset:4096
	ds_read_b128 v[210:213], v144 offset:5120
	ds_read_b128 v[214:217], v144 offset:6144
	ds_read_b128 v[218:221], v144 offset:7168
	global_load_lds_dwordx4 v[160:161], off
	v_lshl_add_u64 v[160:161], v[142:143], 0, s[18:19]
	s_add_i32 m0, s29, 0xe000
	s_nop 0
	global_load_lds_dwordx4 v[160:161], off
	s_waitcnt vmcnt(8)
	s_waitcnt lgkmcnt(0)
	s_barrier
	v_mfma_f32_16x16x32_bf16 v[124:127], v[148:151], v[190:193], v[124:127]
	v_mfma_f32_16x16x32_bf16 v[120:123], v[156:159], v[190:193], v[120:123]
	v_mfma_f32_16x16x32_bf16 v[116:119], v[148:151], v[198:201], v[116:119]
	v_mfma_f32_16x16x32_bf16 v[100:103], v[156:159], v[198:201], v[100:103]
	v_mfma_f32_16x16x32_bf16 v[104:107], v[148:151], v[206:209], v[104:107]
	v_mfma_f32_16x16x32_bf16 v[92:95], v[156:159], v[206:209], v[92:95]
	v_mfma_f32_16x16x32_bf16 v[96:99], v[148:151], v[214:217], v[96:99]
	v_mfma_f32_16x16x32_bf16 v[76:79], v[156:159], v[214:217], v[76:79]
	v_mfma_f32_16x16x32_bf16 v[124:127], v[152:155], v[194:197], v[124:127]
	v_mfma_f32_16x16x32_bf16 v[120:123], v[164:167], v[194:197], v[120:123]
	v_mfma_f32_16x16x32_bf16 v[116:119], v[152:155], v[202:205], v[116:119]
	v_mfma_f32_16x16x32_bf16 v[100:103], v[164:167], v[202:205], v[100:103]
	v_mfma_f32_16x16x32_bf16 v[104:107], v[152:155], v[210:213], v[104:107]
	v_mfma_f32_16x16x32_bf16 v[92:95], v[164:167], v[210:213], v[92:95]
	v_mfma_f32_16x16x32_bf16 v[96:99], v[152:155], v[218:221], v[96:99]
	v_mfma_f32_16x16x32_bf16 v[76:79], v[164:167], v[218:221], v[76:79]
	v_mfma_f32_16x16x32_bf16 v[112:115], v[174:177], v[190:193], v[112:115]
	v_mfma_f32_16x16x32_bf16 v[108:111], v[182:185], v[190:193], v[108:111]
	v_mfma_f32_16x16x32_bf16 v[88:91], v[174:177], v[198:201], v[88:91]
	v_mfma_f32_16x16x32_bf16 v[80:83], v[182:185], v[198:201], v[80:83]
	v_mfma_f32_16x16x32_bf16 v[84:87], v[174:177], v[206:209], v[84:87]
	v_mfma_f32_16x16x32_bf16 v[72:75], v[182:185], v[206:209], v[72:75]
	v_mfma_f32_16x16x32_bf16 v[68:71], v[174:177], v[214:217], v[68:71]
	v_mfma_f32_16x16x32_bf16 v[64:67], v[182:185], v[214:217], v[64:67]
	v_mfma_f32_16x16x32_bf16 v[112:115], v[178:181], v[194:197], v[112:115]
	v_mfma_f32_16x16x32_bf16 v[108:111], v[186:189], v[194:197], v[108:111]
	v_mfma_f32_16x16x32_bf16 v[88:91], v[178:181], v[202:205], v[88:91]
	v_mfma_f32_16x16x32_bf16 v[80:83], v[186:189], v[202:205], v[80:83]
	v_mfma_f32_16x16x32_bf16 v[84:87], v[178:181], v[210:213], v[84:87]
	v_mfma_f32_16x16x32_bf16 v[72:75], v[186:189], v[210:213], v[72:75]
	v_mfma_f32_16x16x32_bf16 v[68:71], v[178:181], v[218:221], v[68:71]
	v_mfma_f32_16x16x32_bf16 v[64:67], v[186:189], v[218:221], v[64:67]
	s_barrier
	s_add_i32 s47, s39, s28
	v_lshl_add_u64 v[160:161], s[20:21], 0, v[128:129]
	s_mov_b32 m0, s47
	ds_read_b128 v[190:193], v144 offset:16384
	ds_read_b128 v[194:197], v144 offset:17408
	ds_read_b128 v[198:201], v144 offset:18432
	ds_read_b128 v[202:205], v144 offset:19456
	ds_read_b128 v[206:209], v144 offset:20480
	ds_read_b128 v[210:213], v144 offset:21504
	ds_read_b128 v[214:217], v144 offset:22528
	ds_read_b128 v[218:221], v144 offset:23552
	global_load_lds_dwordx4 v[160:161], off
	s_add_i32 m0, s47, 0x2000
	s_add_u32 s48, s20, 0xb0000
	v_lshl_add_u64 v[168:169], s[20:21], 0, v[130:131]
	s_addc_u32 s49, s21, 0
	s_add_i32 s47, s40, s28
	global_load_lds_dwordx4 v[168:169], off
	v_lshl_add_u64 v[222:223], s[48:49], 0, v[128:129]
	s_mov_b32 m0, s47
	v_lshl_add_u64 v[224:225], s[22:23], 0, v[130:131]
	global_load_lds_dwordx4 v[222:223], off
	v_lshl_add_u64 v[222:223], s[48:49], 0, v[130:131]
	s_add_i32 m0, s47, 0x2000
	s_nop 0
	global_load_lds_dwordx4 v[222:223], off
	v_lshl_add_u64 v[222:223], s[22:23], 0, v[128:129]
	s_mov_b32 m0, s29
	s_nop 0
	global_load_lds_dwordx4 v[222:223], off
	s_mov_b32 m0, s30
	s_nop 0
	global_load_lds_dwordx4 v[224:225], off
	s_waitcnt vmcnt(8)
	s_waitcnt lgkmcnt(0)
	s_barrier
	v_mfma_f32_16x16x32_bf16 v[60:63], v[148:151], v[190:193], v[60:63]
	v_mfma_f32_16x16x32_bf16 v[56:59], v[156:159], v[190:193], v[56:59]
	v_mfma_f32_16x16x32_bf16 v[44:47], v[148:151], v[198:201], v[44:47]
	v_mfma_f32_16x16x32_bf16 v[40:43], v[156:159], v[198:201], v[40:43]
	v_mfma_f32_16x16x32_bf16 v[28:31], v[148:151], v[206:209], v[28:31]
	v_mfma_f32_16x16x32_bf16 v[24:27], v[156:159], v[206:209], v[24:27]
	v_mfma_f32_16x16x32_bf16 v[12:15], v[148:151], v[214:217], v[12:15]
	v_mfma_f32_16x16x32_bf16 v[8:11], v[156:159], v[214:217], v[8:11]
	v_mfma_f32_16x16x32_bf16 v[60:63], v[152:155], v[194:197], v[60:63]
	v_mfma_f32_16x16x32_bf16 v[56:59], v[164:167], v[194:197], v[56:59]
	v_mfma_f32_16x16x32_bf16 v[44:47], v[152:155], v[202:205], v[44:47]
	v_mfma_f32_16x16x32_bf16 v[40:43], v[164:167], v[202:205], v[40:43]
	v_mfma_f32_16x16x32_bf16 v[28:31], v[152:155], v[210:213], v[28:31]
	v_mfma_f32_16x16x32_bf16 v[24:27], v[164:167], v[210:213], v[24:27]
	v_mfma_f32_16x16x32_bf16 v[12:15], v[152:155], v[218:221], v[12:15]
	v_mfma_f32_16x16x32_bf16 v[8:11], v[164:167], v[218:221], v[8:11]
	v_mfma_f32_16x16x32_bf16 v[52:55], v[174:177], v[190:193], v[52:55]
	v_mfma_f32_16x16x32_bf16 v[48:51], v[182:185], v[190:193], v[48:51]
	v_mfma_f32_16x16x32_bf16 v[36:39], v[174:177], v[198:201], v[36:39]
	v_mfma_f32_16x16x32_bf16 v[32:35], v[182:185], v[198:201], v[32:35]
	v_mfma_f32_16x16x32_bf16 v[20:23], v[174:177], v[206:209], v[20:23]
	v_mfma_f32_16x16x32_bf16 v[16:19], v[182:185], v[206:209], v[16:19]
	v_mfma_f32_16x16x32_bf16 v[4:7], v[174:177], v[214:217], v[4:7]
	v_mfma_f32_16x16x32_bf16 v[0:3], v[182:185], v[214:217], v[0:3]
	v_mfma_f32_16x16x32_bf16 v[52:55], v[178:181], v[194:197], v[52:55]
	v_mfma_f32_16x16x32_bf16 v[48:51], v[186:189], v[194:197], v[48:51]
	v_mfma_f32_16x16x32_bf16 v[36:39], v[178:181], v[202:205], v[36:39]
	v_mfma_f32_16x16x32_bf16 v[32:35], v[186:189], v[202:205], v[32:35]
	v_mfma_f32_16x16x32_bf16 v[20:23], v[178:181], v[210:213], v[20:23]
	v_mfma_f32_16x16x32_bf16 v[16:19], v[186:189], v[210:213], v[16:19]
	v_mfma_f32_16x16x32_bf16 v[4:7], v[178:181], v[218:221], v[4:7]
	v_mfma_f32_16x16x32_bf16 v[0:3], v[186:189], v[218:221], v[0:3]
	s_barrier
	s_add_i32 s47, 0, 0x18000
	v_add_u32_e32 v147, s47, v146
	s_add_i32 s48, 0, 0x1c000
	ds_read_b128 v[148:151], v147
	ds_read_b128 v[152:155], v147 offset:1024
	ds_read_b128 v[156:159], v147 offset:2048
	ds_read_b128 v[164:167], v147 offset:3072
	v_add_u32_e32 v147, s48, v146
	ds_read_b128 v[174:177], v147
	ds_read_b128 v[178:181], v147 offset:1024
	ds_read_b128 v[182:185], v147 offset:2048
	ds_read_b128 v[186:189], v147 offset:3072
	s_add_u32 s22, s22, 0xb0000
	s_addc_u32 s23, s23, 0
	s_mov_b32 m0, s31
	v_lshl_add_u64 v[226:227], s[22:23], 0, v[128:129]
	ds_read_b128 v[190:193], v144 offset:32768
	ds_read_b128 v[194:197], v144 offset:33792
	ds_read_b128 v[198:201], v144 offset:34816
	ds_read_b128 v[202:205], v144 offset:35840
	ds_read_b128 v[206:209], v144 offset:36864
	ds_read_b128 v[210:213], v144 offset:37888
	ds_read_b128 v[214:217], v144 offset:38912
	ds_read_b128 v[218:221], v144 offset:39936
	global_load_lds_dwordx4 v[226:227], off
	v_lshl_add_u64 v[226:227], s[22:23], 0, v[130:131]
	s_mov_b32 m0, s34
	s_nop 0
	global_load_lds_dwordx4 v[226:227], off
	s_waitcnt vmcnt(8)
	s_waitcnt lgkmcnt(0)
	s_barrier
	v_mfma_f32_16x16x32_bf16 v[124:127], v[148:151], v[190:193], v[124:127]
	v_mfma_f32_16x16x32_bf16 v[120:123], v[156:159], v[190:193], v[120:123]
	v_mfma_f32_16x16x32_bf16 v[116:119], v[148:151], v[198:201], v[116:119]
	v_mfma_f32_16x16x32_bf16 v[100:103], v[156:159], v[198:201], v[100:103]
	v_mfma_f32_16x16x32_bf16 v[104:107], v[148:151], v[206:209], v[104:107]
	v_mfma_f32_16x16x32_bf16 v[92:95], v[156:159], v[206:209], v[92:95]
	v_mfma_f32_16x16x32_bf16 v[96:99], v[148:151], v[214:217], v[96:99]
	v_mfma_f32_16x16x32_bf16 v[76:79], v[156:159], v[214:217], v[76:79]
	v_mfma_f32_16x16x32_bf16 v[124:127], v[152:155], v[194:197], v[124:127]
	v_mfma_f32_16x16x32_bf16 v[120:123], v[164:167], v[194:197], v[120:123]
	v_mfma_f32_16x16x32_bf16 v[116:119], v[152:155], v[202:205], v[116:119]
	v_mfma_f32_16x16x32_bf16 v[100:103], v[164:167], v[202:205], v[100:103]
	v_mfma_f32_16x16x32_bf16 v[104:107], v[152:155], v[210:213], v[104:107]
	v_mfma_f32_16x16x32_bf16 v[92:95], v[164:167], v[210:213], v[92:95]
	v_mfma_f32_16x16x32_bf16 v[96:99], v[152:155], v[218:221], v[96:99]
	v_mfma_f32_16x16x32_bf16 v[76:79], v[164:167], v[218:221], v[76:79]
	v_mfma_f32_16x16x32_bf16 v[112:115], v[174:177], v[190:193], v[112:115]
	v_mfma_f32_16x16x32_bf16 v[108:111], v[182:185], v[190:193], v[108:111]
	v_mfma_f32_16x16x32_bf16 v[88:91], v[174:177], v[198:201], v[88:91]
	v_mfma_f32_16x16x32_bf16 v[80:83], v[182:185], v[198:201], v[80:83]
	v_mfma_f32_16x16x32_bf16 v[84:87], v[174:177], v[206:209], v[84:87]
	v_mfma_f32_16x16x32_bf16 v[72:75], v[182:185], v[206:209], v[72:75]
	v_mfma_f32_16x16x32_bf16 v[68:71], v[174:177], v[214:217], v[68:71]
	v_mfma_f32_16x16x32_bf16 v[64:67], v[182:185], v[214:217], v[64:67]
	v_mfma_f32_16x16x32_bf16 v[112:115], v[178:181], v[194:197], v[112:115]
	v_mfma_f32_16x16x32_bf16 v[108:111], v[186:189], v[194:197], v[108:111]
	v_mfma_f32_16x16x32_bf16 v[88:91], v[178:181], v[202:205], v[88:91]
	v_mfma_f32_16x16x32_bf16 v[80:83], v[186:189], v[202:205], v[80:83]
	v_mfma_f32_16x16x32_bf16 v[84:87], v[178:181], v[210:213], v[84:87]
	v_mfma_f32_16x16x32_bf16 v[72:75], v[186:189], v[210:213], v[72:75]
	v_mfma_f32_16x16x32_bf16 v[68:71], v[178:181], v[218:221], v[68:71]
	v_mfma_f32_16x16x32_bf16 v[64:67], v[186:189], v[218:221], v[64:67]
	s_barrier
	s_add_i32 s22, s47, s28
	v_lshl_add_u64 v[160:161], v[160:161], 0, s[14:15]
	s_mov_b32 m0, s22
	ds_read_b128 v[190:193], v144 offset:49152
	ds_read_b128 v[194:197], v144 offset:50176
	ds_read_b128 v[198:201], v144 offset:51200
	ds_read_b128 v[202:205], v144 offset:52224
	ds_read_b128 v[206:209], v144 offset:53248
	ds_read_b128 v[210:213], v144 offset:54272
	ds_read_b128 v[214:217], v144 offset:55296
	ds_read_b128 v[218:221], v144 offset:56320
	global_load_lds_dwordx4 v[160:161], off
	s_add_i32 m0, s22, 0x2000
	s_add_u32 s20, s20, 0xb0080
	v_lshl_add_u64 v[160:161], v[168:169], 0, s[14:15]
	s_addc_u32 s21, s21, 0
	s_add_i32 s22, s48, s28
	global_load_lds_dwordx4 v[160:161], off
	v_lshl_add_u64 v[160:161], s[20:21], 0, v[128:129]
	s_mov_b32 m0, s22
	s_nop 0
	global_load_lds_dwordx4 v[160:161], off
	v_lshl_add_u64 v[160:161], s[20:21], 0, v[130:131]
	s_add_i32 m0, s22, 0x2000
	s_nop 0
	global_load_lds_dwordx4 v[160:161], off
	v_lshl_add_u64 v[160:161], v[222:223], 0, s[14:15]
	s_mov_b32 m0, s37
	s_nop 0
	global_load_lds_dwordx4 v[160:161], off
	v_lshl_add_u64 v[160:161], v[224:225], 0, s[14:15]
	s_mov_b32 m0, s38
	s_nop 0
	global_load_lds_dwordx4 v[160:161], off
	s_waitcnt vmcnt(8)
	s_waitcnt lgkmcnt(0)
	s_barrier
	v_mfma_f32_16x16x32_bf16 v[60:63], v[148:151], v[190:193], v[60:63]
	v_mfma_f32_16x16x32_bf16 v[56:59], v[156:159], v[190:193], v[56:59]
	v_mfma_f32_16x16x32_bf16 v[44:47], v[148:151], v[198:201], v[44:47]
	v_mfma_f32_16x16x32_bf16 v[40:43], v[156:159], v[198:201], v[40:43]
	v_mfma_f32_16x16x32_bf16 v[28:31], v[148:151], v[206:209], v[28:31]
	v_mfma_f32_16x16x32_bf16 v[24:27], v[156:159], v[206:209], v[24:27]
	v_mfma_f32_16x16x32_bf16 v[12:15], v[148:151], v[214:217], v[12:15]
	v_mfma_f32_16x16x32_bf16 v[8:11], v[156:159], v[214:217], v[8:11]
	v_mfma_f32_16x16x32_bf16 v[60:63], v[152:155], v[194:197], v[60:63]
	v_mfma_f32_16x16x32_bf16 v[56:59], v[164:167], v[194:197], v[56:59]
	v_mfma_f32_16x16x32_bf16 v[44:47], v[152:155], v[202:205], v[44:47]
	v_mfma_f32_16x16x32_bf16 v[40:43], v[164:167], v[202:205], v[40:43]
	v_mfma_f32_16x16x32_bf16 v[28:31], v[152:155], v[210:213], v[28:31]
	v_mfma_f32_16x16x32_bf16 v[24:27], v[164:167], v[210:213], v[24:27]
	v_mfma_f32_16x16x32_bf16 v[12:15], v[152:155], v[218:221], v[12:15]
	v_mfma_f32_16x16x32_bf16 v[8:11], v[164:167], v[218:221], v[8:11]
	v_mfma_f32_16x16x32_bf16 v[52:55], v[174:177], v[190:193], v[52:55]
	v_mfma_f32_16x16x32_bf16 v[48:51], v[182:185], v[190:193], v[48:51]
	v_mfma_f32_16x16x32_bf16 v[36:39], v[174:177], v[198:201], v[36:39]
	v_mfma_f32_16x16x32_bf16 v[32:35], v[182:185], v[198:201], v[32:35]
	v_mfma_f32_16x16x32_bf16 v[20:23], v[174:177], v[206:209], v[20:23]
	v_mfma_f32_16x16x32_bf16 v[16:19], v[182:185], v[206:209], v[16:19]
	v_mfma_f32_16x16x32_bf16 v[4:7], v[174:177], v[214:217], v[4:7]
	v_mfma_f32_16x16x32_bf16 v[0:3], v[182:185], v[214:217], v[0:3]
	v_mfma_f32_16x16x32_bf16 v[52:55], v[178:181], v[194:197], v[52:55]
	v_mfma_f32_16x16x32_bf16 v[48:51], v[186:189], v[194:197], v[48:51]
	v_mfma_f32_16x16x32_bf16 v[36:39], v[178:181], v[202:205], v[36:39]
	v_mfma_f32_16x16x32_bf16 v[32:35], v[186:189], v[202:205], v[32:35]
	v_mfma_f32_16x16x32_bf16 v[20:23], v[178:181], v[210:213], v[20:23]
	v_mfma_f32_16x16x32_bf16 v[16:19], v[186:189], v[210:213], v[16:19]
	v_mfma_f32_16x16x32_bf16 v[4:7], v[178:181], v[218:221], v[4:7]
	v_mfma_f32_16x16x32_bf16 v[0:3], v[186:189], v[218:221], v[0:3]
	s_barrier
	s_add_i32 s46, s46, 2
	s_add_u32 s18, s18, 0x100
	s_addc_u32 s19, s19, 0
	s_cmp_gt_u32 s46, 41
	s_cbranch_scc0 .LBB0_1042
	s_add_u32 s18, s44, 0xffffff00
	s_addc_u32 s19, s45, -1
	s_and_b64 vcc, exec, s[2:3]
	s_cbranch_vccnz .LBB0_1045
	v_mov_b64_e32 v[0:1], 0
	s_mov_b32 s10, s41
	s_mov_b32 s24, s42
	s_mov_b64 s[12:13], s[16:17]
	s_mov_b32 s36, s43
	v_mov_b64_e32 v[2:3], 0
	v_mov_b64_e32 v[4:5], 0
	v_mov_b64_e32 v[6:7], 0
	v_mov_b64_e32 v[16:17], 0
	v_mov_b64_e32 v[18:19], 0
	v_mov_b64_e32 v[20:21], 0
	v_mov_b64_e32 v[22:23], 0
	v_mov_b64_e32 v[32:33], 0
	v_mov_b64_e32 v[34:35], 0
	v_mov_b64_e32 v[36:37], 0
	v_mov_b64_e32 v[38:39], 0
	v_mov_b64_e32 v[48:49], 0
	v_mov_b64_e32 v[50:51], 0
	v_mov_b64_e32 v[52:53], 0
	v_mov_b64_e32 v[54:55], 0
	v_mov_b64_e32 v[8:9], 0
	v_mov_b64_e32 v[10:11], 0
	v_mov_b64_e32 v[12:13], 0
	v_mov_b64_e32 v[14:15], 0
	v_mov_b64_e32 v[24:25], 0
	v_mov_b64_e32 v[26:27], 0
	v_mov_b64_e32 v[28:29], 0
	v_mov_b64_e32 v[30:31], 0
	v_mov_b64_e32 v[40:41], 0
	v_mov_b64_e32 v[42:43], 0
	v_mov_b64_e32 v[44:45], 0
	v_mov_b64_e32 v[46:47], 0
	v_mov_b64_e32 v[56:57], 0
	v_mov_b64_e32 v[58:59], 0
	v_mov_b64_e32 v[60:61], 0
	v_mov_b64_e32 v[62:63], 0
	v_mov_b64_e32 v[64:65], 0
	v_mov_b64_e32 v[66:67], 0
	v_mov_b64_e32 v[68:69], 0
	v_mov_b64_e32 v[70:71], 0
	v_mov_b64_e32 v[72:73], 0
	v_mov_b64_e32 v[74:75], 0
	v_mov_b64_e32 v[84:85], 0
	v_mov_b64_e32 v[86:87], 0
	v_mov_b64_e32 v[80:81], 0
	v_mov_b64_e32 v[82:83], 0
	v_mov_b64_e32 v[88:89], 0
	v_mov_b64_e32 v[90:91], 0
	v_mov_b64_e32 v[108:109], 0
	v_mov_b64_e32 v[110:111], 0
	v_mov_b64_e32 v[112:113], 0
	v_mov_b64_e32 v[114:115], 0
	v_mov_b64_e32 v[76:77], 0
	v_mov_b64_e32 v[78:79], 0
	v_mov_b64_e32 v[96:97], 0
	v_mov_b64_e32 v[98:99], 0
	v_mov_b64_e32 v[92:93], 0
	v_mov_b64_e32 v[94:95], 0
	v_mov_b64_e32 v[104:105], 0
	v_mov_b64_e32 v[106:107], 0
	v_mov_b64_e32 v[100:101], 0
	v_mov_b64_e32 v[102:103], 0
	v_mov_b64_e32 v[116:117], 0
	v_mov_b64_e32 v[118:119], 0
	v_mov_b64_e32 v[120:121], 0
	v_mov_b64_e32 v[122:123], 0
	v_mov_b64_e32 v[124:125], 0
	v_mov_b64_e32 v[126:127], 0
	s_andn2_b64 vcc, exec, s[0:1]
	s_cbranch_vccnz .LBB0_1046
	s_branch .LBB0_1047
